# v_rcp_f32+mul instead of IEEE div expansion in silu/sigmoid (273 sites, hazard re-padded); XCD barrier at all seams; post preamble batched
# speedup vs baseline: 1.0697x; 1.0296x over previous
; __device__ __forceinline__ const float* pin(int i) { return kargs()->in[i]; }
; __device__ __forceinline__ void phase_post(const Params& p, int l) {
;     ...
;     const int c0 = lane * 16, mixer = lane >> 4, cm = c0 & 255;
;     const int gcol = mixer == 0 ? C_HG : mixer == 1 ? C_GZ : mixer == 2 ? C_RG : C_SZ;
;     float wn[16];
; #pragma unroll
;     for (int i = 0; i < 16; ++i) wn[i] = mixer == 0 ? pin(11)[l * 64 + ((cm + i) & 63)] : mixer == 1 ? pin(15)[l * 64 + ((cm + i) & 63)] : mixer == 2 ? 1.0f : pin(21)[l * 256 + cm + i];
.LBB0_70:
	s_mov_b32 s25, 0
	s_and_b64 vcc, exec, s[6:7]
	s_cbranch_vccz .LBB0_168
	s_cmp_gt_i32 s71, 1
	s_mov_b64 s[4:5], -1
	s_mov_b64 s[54:55], 0x200
	s_mov_b64 s[56:57], 0x2000
	v_writelane_b32 v252, s58, 56
	s_nop 1
	v_writelane_b32 v252, s59, 57
	s_cbranch_scc0 .LBB0_428
	s_cmp_gt_i32 s71, 2
	s_cbranch_scc0 .LBB0_170
	v_mov_b32_e32 v0, v202
	s_mov_b32 s22, s17
	v_mov_b32_e32 v7, v202
	s_mov_b64 s[2:3], s[0:1]
	s_load_dwordx2 s[6:7], s[2:3], 0xe0
	s_mov_b64 s[2:3], s[0:1]
	s_load_dwordx2 s[4:5], s[2:3], 0xe0
	v_and_b32_e32 v1, 63, v0
	s_and_b64 s[2:3], s[58:59], exec
	v_lshlrev_b32_e32 v6, 4, v1
	s_cselect_b32 s2, 64, 0
	v_and_b32_e32 v5, 0xf0, v6
	v_cmp_gt_u32_e32 vcc, 16, v1
	v_cmp_lt_u32_e64 s[42:43], 15, v1
	v_and_or_b32 v1, v6, 48, s2
	s_cselect_b32 s2, 0x100, 0
	v_bfe_u32 v4, v0, 4, 2
	v_or_b32_e32 v0, s2, v5
	s_load_dwordx2 s[44:45], s[0:1], 0x58
	s_load_dwordx2 s[46:47], s[0:1], 0x78
	s_load_dwordx2 s[10:11], s[0:1], 0xa8
	v_cmp_eq_u32_e64 s[2:3], 3, v4
	v_cmp_eq_u32_e64 s[8:9], 1, v4
	v_cmp_eq_u32_e64 s[12:13], 2, v4
	s_waitcnt lgkmcnt(0)
	v_mov_b32_e32 v2, s44
	v_mov_b32_e32 v3, s45
	v_mov_b32_e32 v82, s46
	v_mov_b32_e32 v83, s47
	v_cndmask_b32_e64 v16, v1, v0, s[2:3]
	v_cndmask_b32_e64 v2, v2, v82, s[8:9]
	v_cndmask_b32_e64 v3, v3, v83, s[8:9]
	v_mov_b32_e32 v82, s10
	v_mov_b32_e32 v83, s11
	v_cndmask_b32_e64 v2, v2, v82, s[2:3]
	v_cndmask_b32_e64 v3, v3, v83, s[2:3]
	v_lshl_add_u64 v[2:3], v[16:17], 2, v[2:3]
	global_load_dwordx4 v[66:69], v[2:3], off
	global_load_dwordx4 v[70:73], v[2:3], off offset:16
	global_load_dwordx4 v[74:77], v[2:3], off offset:32
	global_load_dwordx4 v[78:81], v[2:3], off offset:48
	s_waitcnt vmcnt(0)
	v_cndmask_b32_e64 v66, v66, 1.0, s[12:13]
	v_cndmask_b32_e64 v67, v67, 1.0, s[12:13]
	v_cndmask_b32_e64 v68, v68, 1.0, s[12:13]
	v_cndmask_b32_e64 v69, v69, 1.0, s[12:13]
	v_cndmask_b32_e64 v70, v70, 1.0, s[12:13]
	v_cndmask_b32_e64 v71, v71, 1.0, s[12:13]
	v_cndmask_b32_e64 v72, v72, 1.0, s[12:13]
	v_cndmask_b32_e64 v73, v73, 1.0, s[12:13]
	v_cndmask_b32_e64 v74, v74, 1.0, s[12:13]
	v_cndmask_b32_e64 v75, v75, 1.0, s[12:13]
	v_cndmask_b32_e64 v76, v76, 1.0, s[12:13]
	v_cndmask_b32_e64 v77, v77, 1.0, s[12:13]
	v_cndmask_b32_e64 v78, v78, 1.0, s[12:13]
	v_cndmask_b32_e64 v79, v79, 1.0, s[12:13]
	v_cndmask_b32_e64 v80, v80, 1.0, s[12:13]
	v_cndmask_b32_e64 v81, v81, 1.0, s[12:13]
.LBB0_137:
	v_ashrrev_i32_e32 v0, 6, v7
	v_lshl_add_u32 v88, s22, 3, v0
	v_cmp_gt_i32_e64 s[42:43], s87, v88
	s_and_saveexec_b64 s[50:51], s[42:43]
	s_cbranch_execz .LBB0_169
	v_cmp_eq_u32_e64 s[42:43], 2, v4
	s_mov_b64 s[2:3], 0x3500000
	s_mov_b64 s[52:53], 0
	v_cndmask_b32_e64 v0, v212, v213, s[42:43]
	v_cmp_ne_u32_e64 s[42:43], 1, v4
	s_nop 1
	v_cndmask_b32_e64 v0, v214, v0, s[42:43]
	v_cndmask_b32_e32 v0, v0, v215, vcc
	v_lshlrev_b32_e32 v16, 1, v0
	s_waitcnt lgkmcnt(0)
	v_lshl_add_u64 v[0:1], s[6:7], 0, v[16:17]
	v_lshlrev_b32_e32 v16, 1, v6
	v_lshl_add_u64 v[2:3], s[4:5], 0, v[16:17]
	v_lshlrev_b32_e32 v16, 1, v5
	v_lshl_add_u64 v[82:83], v[2:3], 0, s[2:3]
	v_lshl_add_u64 v[0:1], v[0:1], 0, v[16:17]
	s_mov_b64 s[2:3], 0x5600000
	v_lshl_add_u64 v[84:85], v[0:1], 0, s[2:3]
	v_cmp_ne_u32_e64 s[42:43], 3, v4
	s_branch .LBB0_141

; __device__ __forceinline__ float siluf_(float x) { return x / (1.0f + __expf(-x)); }
; __device__ __forceinline__ float red4(float x) { x += dppf<0xB1>(x); x += dppf<0x4E>(x); return x; }
; __device__ __forceinline__ float red8(float x) { x = red4(x); x += dppf<0x141>(x); return x; }
; __device__ __forceinline__ void u4f(const u32x4& u, float (&f)[8]) { h2f(u.x, f[0], f[1]); h2f(u.y, f[2], f[3]); h2f(u.z, f[4], f[5]); h2f(u.w, f[6], f[7]); }
; __device__ __forceinline__ void phase_post(const Params& p, int l) {
;     ...
;                 { float t0[8], t1[8]; u4f(rg[bb][0], t0); u4f(rg[bb][1], t1);
; #pragma unroll
;                   for (int i = 0; i < 8; ++i) { g[i] = siluf_(t0[i]); g[i + 8] = siluf_(t1[i]); } }
;                 float ss = 0.f;
;                 if (mixer == 3) {
; #pragma unroll
;                     for (int i = 0; i < 16; ++i) { x[i] *= g[i]; ss += x[i] * x[i]; }
;                     ss = red8(ss);
;                     const float sc = rsqrtf(ss * (1.0f / 128.0f) + EPS);
; #pragma unroll
;                     for (int i = 0; i < 16; ++i) x[i] = x[i] * sc * wn[i];
;                 } else {
; #pragma unroll
;                     for (int i = 0; i < 16; ++i) ss += x[i] * x[i];
;                     ss = red4(ss);
;                     const float sc = rsqrtf(ss * (1.0f / 64.0f) + EPS);
; #pragma unroll
;                     for (int i = 0; i < 16; ++i) x[i] = x[i] * sc * wn[i] * g[i];
;                 }
.LBB0_147:
	s_or_b64 exec, exec, s[4:5]
	s_waitcnt vmcnt(2)
	v_cvt_f32_f16_sdwa v95, v12 dst_sel:DWORD dst_unused:UNUSED_PAD src0_sel:WORD_1
	v_cvt_f32_f16_e32 v94, v12
	s_waitcnt vmcnt(0)
	v_cvt_f32_f16_sdwa v12, v8 dst_sel:DWORD dst_unused:UNUSED_PAD src0_sel:WORD_1
	v_cvt_f32_f16_e32 v8, v8
	v_cvt_f32_f16_sdwa v107, v5 dst_sel:DWORD dst_unused:UNUSED_PAD src0_sel:WORD_1
	v_cvt_f32_f16_e32 v106, v5
	v_cvt_f32_f16_e32 v5, v1
	v_mul_f32_e32 v16, 0xbfb8aa3b, v8
	v_exp_f32_e32 v96, v16
	v_mul_f32_e32 v16, 0xbfb8aa3b, v12
	v_exp_f32_e32 v97, v16
	v_cvt_f32_f16_sdwa v115, v6 dst_sel:DWORD dst_unused:UNUSED_PAD src0_sel:WORD_1
	v_cvt_f32_f16_e32 v114, v6
	v_cvt_f32_f16_sdwa v123, v7 dst_sel:DWORD dst_unused:UNUSED_PAD src0_sel:WORD_1
	v_pk_add_f32 v[96:97], v[96:97], 1.0 op_sel_hi:[1,0]
	v_cvt_f32_f16_e32 v122, v7
	v_cvt_f32_f16_sdwa v111, v14 dst_sel:DWORD dst_unused:UNUSED_PAD src0_sel:WORD_1
	v_cvt_f32_f16_e32 v110, v14
	v_cvt_f32_f16_sdwa v119, v15 dst_sel:DWORD dst_unused:UNUSED_PAD src0_sel:WORD_1
	v_rcp_f32_e32 v16, v97
	s_nop 0
	v_mul_f32_e32 v97, v12, v16
	v_cvt_f32_f16_e32 v118, v15
	v_cvt_f32_f16_sdwa v99, v4 dst_sel:DWORD dst_unused:UNUSED_PAD src0_sel:WORD_1
	v_cvt_f32_f16_e32 v98, v4
	v_cvt_f32_f16_sdwa v4, v0 dst_sel:DWORD dst_unused:UNUSED_PAD src0_sel:WORD_1
	v_cvt_f32_f16_e32 v0, v0
	v_rcp_f32_e32 v12, v96
	s_nop 0
	v_mul_f32_e32 v96, v8, v12
	v_mul_f32_e32 v8, 0xbfb8aa3b, v0
	v_exp_f32_e32 v100, v8
	v_mul_f32_e32 v8, 0xbfb8aa3b, v4
	v_exp_f32_e32 v101, v8
	s_nop 0
	v_pk_add_f32 v[100:101], v[100:101], 1.0 op_sel_hi:[1,0]
	s_nop 0
	s_nop 0
	v_rcp_f32_e32 v8, v101
	s_nop 0
	v_mul_f32_e32 v101, v4, v8
	v_cvt_f32_f16_sdwa v103, v13 dst_sel:DWORD dst_unused:UNUSED_PAD src0_sel:WORD_1
	v_rcp_f32_e32 v4, v100
	s_nop 0
	v_mul_f32_e32 v100, v0, v4
	v_cvt_f32_f16_sdwa v0, v9 dst_sel:DWORD dst_unused:UNUSED_PAD src0_sel:WORD_1
	v_cvt_f32_f16_e32 v4, v9
	v_cvt_f32_f16_e32 v102, v13
	v_mul_f32_e32 v9, 0xbfb8aa3b, v0
	v_mul_f32_e32 v8, 0xbfb8aa3b, v4
	v_exp_f32_e32 v8, v8
	v_exp_f32_e32 v9, v9
	s_nop 0
	v_pk_add_f32 v[8:9], v[8:9], 1.0 op_sel_hi:[1,0]
	s_nop 0
	s_nop 0
	v_rcp_f32_e32 v12, v9
	s_nop 0
	v_mul_f32_e32 v105, v0, v12
	s_nop 0
	v_rcp_f32_e32 v0, v8
	s_nop 0
	v_mul_f32_e32 v104, v4, v0
	v_cvt_f32_f16_sdwa v4, v1 dst_sel:DWORD dst_unused:UNUSED_PAD src0_sel:WORD_1
	v_mul_f32_e32 v0, 0xbfb8aa3b, v5
	v_exp_f32_e32 v0, v0
	v_mul_f32_e32 v1, 0xbfb8aa3b, v4
	v_exp_f32_e32 v1, v1
	s_nop 0
	v_pk_add_f32 v[0:1], v[0:1], 1.0 op_sel_hi:[1,0]
	s_nop 0
	s_nop 0
	v_rcp_f32_e32 v8, v1
	s_nop 0
	v_mul_f32_e32 v109, v4, v8
	s_nop 0
	v_rcp_f32_e32 v1, v0
	s_nop 0
	v_mul_f32_e32 v108, v5, v1
	v_cvt_f32_f16_sdwa v4, v10 dst_sel:DWORD dst_unused:UNUSED_PAD src0_sel:WORD_1
	v_cvt_f32_f16_e32 v5, v10
	v_mul_f32_e32 v1, 0xbfb8aa3b, v4
	v_mul_f32_e32 v0, 0xbfb8aa3b, v5
	v_exp_f32_e32 v0, v0
	v_exp_f32_e32 v1, v1
	s_nop 0
	v_pk_add_f32 v[0:1], v[0:1], 1.0 op_sel_hi:[1,0]
	s_nop 0
	s_nop 0
	v_rcp_f32_e32 v8, v1
	s_nop 0
	v_mul_f32_e32 v113, v4, v8
	s_nop 0
	v_cvt_f32_f16_sdwa v4, v2 dst_sel:DWORD dst_unused:UNUSED_PAD src0_sel:WORD_1
	v_cvt_f32_f16_e32 v2, v2
	v_rcp_f32_e32 v1, v0
	s_nop 0
	v_mul_f32_e32 v112, v5, v1
	v_mul_f32_e32 v1, 0xbfb8aa3b, v4
	v_mul_f32_e32 v0, 0xbfb8aa3b, v2
	v_exp_f32_e32 v0, v0
	v_exp_f32_e32 v1, v1
	s_nop 0
	v_pk_add_f32 v[0:1], v[0:1], 1.0 op_sel_hi:[1,0]
	s_nop 0
	s_nop 0
	v_rcp_f32_e32 v5, v1
	s_nop 0
	v_mul_f32_e32 v117, v4, v5
	s_nop 0
	v_rcp_f32_e32 v1, v0
	s_nop 0
	v_mul_f32_e32 v116, v2, v1
	v_cvt_f32_f16_sdwa v2, v11 dst_sel:DWORD dst_unused:UNUSED_PAD src0_sel:WORD_1
	v_cvt_f32_f16_e32 v4, v11
	v_mul_f32_e32 v1, 0xbfb8aa3b, v2
	v_mul_f32_e32 v0, 0xbfb8aa3b, v4
	v_exp_f32_e32 v0, v0
	v_exp_f32_e32 v1, v1
	s_nop 0
	v_pk_add_f32 v[0:1], v[0:1], 1.0 op_sel_hi:[1,0]
	s_nop 0
	s_nop 0
	v_rcp_f32_e32 v5, v1
	s_nop 0
	v_mul_f32_e32 v121, v2, v5
	s_nop 0
	v_cvt_f32_f16_sdwa v2, v3 dst_sel:DWORD dst_unused:UNUSED_PAD src0_sel:WORD_1
	v_cvt_f32_f16_e32 v3, v3
	v_rcp_f32_e32 v1, v0
	s_nop 0
	v_mul_f32_e32 v120, v4, v1
	v_mul_f32_e32 v1, 0xbfb8aa3b, v2
	v_mul_f32_e32 v0, 0xbfb8aa3b, v3
	v_exp_f32_e32 v0, v0
	v_exp_f32_e32 v1, v1
	s_nop 0
	v_pk_add_f32 v[0:1], v[0:1], 1.0 op_sel_hi:[1,0]
	s_nop 0
	s_nop 0
	v_rcp_f32_e32 v4, v1
	s_nop 0
	v_mul_f32_e32 v125, v2, v4
	s_nop 0
	v_rcp_f32_e32 v1, v0
	s_nop 0
	v_mul_f32_e32 v124, v3, v1
	s_and_saveexec_b64 s[2:3], s[42:43]
	s_xor_b64 s[4:5], exec, s[2:3]
	s_cbranch_execz .LBB0_149
	v_pk_mul_f32 v[0:1], v[94:95], v[94:95]
	v_pk_mul_f32 v[2:3], v[102:103], v[102:103]
	v_add_f32_e32 v0, v0, v1
	v_add_f32_e32 v0, v2, v0
	v_pk_mul_f32 v[4:5], v[110:111], v[110:111]
	v_add_f32_e32 v0, v3, v0
	v_add_f32_e32 v0, v4, v0
	v_pk_mul_f32 v[6:7], v[118:119], v[118:119]
	v_add_f32_e32 v0, v5, v0
	v_add_f32_e32 v0, v6, v0
	v_pk_mul_f32 v[8:9], v[98:99], v[98:99]
	v_add_f32_e32 v0, v7, v0
	v_add_f32_e32 v0, v8, v0
	v_pk_mul_f32 v[10:11], v[106:107], v[106:107]
	v_add_f32_e32 v0, v9, v0
	v_add_f32_e32 v0, v10, v0
	v_pk_mul_f32 v[12:13], v[114:115], v[114:115]
	v_add_f32_e32 v0, v11, v0
	v_add_f32_e32 v0, v12, v0
	v_pk_mul_f32 v[14:15], v[122:123], v[122:123]
	v_add_f32_e32 v0, v13, v0
	v_add_f32_e32 v0, v14, v0
	v_add_f32_e32 v0, v15, v0
	s_nop 1
	v_add_f32_dpp v0, v0, v0 quad_perm:[1,0,3,2] row_mask:0xf bank_mask:0xf bound_ctrl:1
	s_nop 1
	v_add_f32_dpp v0, v0, v0 quad_perm:[2,3,0,1] row_mask:0xf bank_mask:0xf bound_ctrl:1
	v_fmamk_f32 v0, v0, 0x3c800000, v203
	v_mul_f32_e32 v1, 0x4b800000, v0
	v_cmp_gt_f32_e32 vcc, s16, v0
	s_nop 1
	v_cndmask_b32_e32 v0, v0, v1, vcc
	v_rsq_f32_e32 v0, v0
	s_nop 0
	v_mul_f32_e32 v1, 0x45800000, v0
	v_cndmask_b32_e32 v0, v0, v1, vcc
	v_pk_mul_f32 v[2:3], v[0:1], v[122:123] op_sel_hi:[0,1]
	v_pk_mul_f32 v[4:5], v[0:1], v[114:115] op_sel_hi:[0,1]
	v_pk_mul_f32 v[6:7], v[0:1], v[106:107] op_sel_hi:[0,1]
	v_pk_mul_f32 v[8:9], v[0:1], v[98:99] op_sel_hi:[0,1]
	v_pk_mul_f32 v[10:11], v[0:1], v[118:119] op_sel_hi:[0,1]
	v_pk_mul_f32 v[12:13], v[0:1], v[110:111] op_sel_hi:[0,1]
	v_pk_mul_f32 v[14:15], v[0:1], v[102:103] op_sel_hi:[0,1]
	v_pk_mul_f32 v[0:1], v[0:1], v[94:95] op_sel_hi:[0,1]
	v_pk_mul_f32 v[0:1], v[66:67], v[0:1]
	v_pk_mul_f32 v[94:95], v[68:69], v[14:15]
	v_pk_mul_f32 v[98:99], v[70:71], v[12:13]
	v_pk_mul_f32 v[102:103], v[72:73], v[10:11]
	v_pk_mul_f32 v[8:9], v[74:75], v[8:9]
	v_pk_mul_f32 v[6:7], v[76:77], v[6:7]
	v_pk_mul_f32 v[4:5], v[78:79], v[4:5]
	v_pk_mul_f32 v[2:3], v[80:81], v[2:3]
	v_pk_mul_f32 v[12:13], v[116:117], v[4:5]
	v_pk_mul_f32 v[14:15], v[124:125], v[2:3]
	v_pk_mul_f32 v[10:11], v[108:109], v[6:7]
	v_pk_mul_f32 v[8:9], v[100:101], v[8:9]
	v_pk_mul_f32 v[6:7], v[120:121], v[102:103]
	v_pk_mul_f32 v[4:5], v[112:113], v[98:99]
	v_pk_mul_f32 v[2:3], v[104:105], v[94:95]
	v_pk_mul_f32 v[0:1], v[96:97], v[0:1]

; __device__ __forceinline__ float siluf_(float x) { return x / (1.0f + __expf(-x)); }
; __device__ __forceinline__ float red4(float x) { x += dppf<0xB1>(x); x += dppf<0x4E>(x); return x; }
; __device__ __forceinline__ float red8(float x) { x = red4(x); x += dppf<0x141>(x); return x; }
; __device__ __forceinline__ void u4f(const u32x4& u, float (&f)[8]) { h2f(u.x, f[0], f[1]); h2f(u.y, f[2], f[3]); h2f(u.z, f[4], f[5]); h2f(u.w, f[6], f[7]); }
; __device__ __forceinline__ void phase_post(const Params& p, int l) {
;     ...
;                 { float t0[8], t1[8]; u4f(rg[bb][0], t0); u4f(rg[bb][1], t1);
; #pragma unroll
;                   for (int i = 0; i < 8; ++i) { g[i] = siluf_(t0[i]); g[i + 8] = siluf_(t1[i]); } }
;                 float ss = 0.f;
;                 if (mixer == 3) {
; #pragma unroll
;                     for (int i = 0; i < 16; ++i) { x[i] *= g[i]; ss += x[i] * x[i]; }
;                     ss = red8(ss);
;                     const float sc = rsqrtf(ss * (1.0f / 128.0f) + EPS);
; #pragma unroll
;                     for (int i = 0; i < 16; ++i) x[i] = x[i] * sc * wn[i];
;                 } else {
; #pragma unroll
;                     for (int i = 0; i < 16; ++i) ss += x[i] * x[i];
;                     ss = red4(ss);
;                     const float sc = rsqrtf(ss * (1.0f / 64.0f) + EPS);
; #pragma unroll
;                     for (int i = 0; i < 16; ++i) x[i] = x[i] * sc * wn[i] * g[i];
;                 }
.LBB0_154:
	v_cvt_f32_f16_sdwa v2, v62 dst_sel:DWORD dst_unused:UNUSED_PAD src0_sel:WORD_1
	v_cvt_f32_f16_e32 v3, v62
	v_cvt_f32_f16_sdwa v93, v38 dst_sel:DWORD dst_unused:UNUSED_PAD src0_sel:WORD_1
	v_cvt_f32_f16_e32 v92, v38
	v_mul_f32_e32 v1, 0xbfb8aa3b, v2
	v_mul_f32_e32 v0, 0xbfb8aa3b, v3
	v_exp_f32_e32 v0, v0
	v_exp_f32_e32 v1, v1
	v_cvt_f32_f16_sdwa v97, v30 dst_sel:DWORD dst_unused:UNUSED_PAD src0_sel:WORD_1
	v_cvt_f32_f16_e32 v96, v30
	v_cvt_f32_f16_sdwa v101, v39 dst_sel:DWORD dst_unused:UNUSED_PAD src0_sel:WORD_1
	v_pk_add_f32 v[0:1], v[0:1], 1.0 op_sel_hi:[1,0]
	v_cvt_f32_f16_e32 v100, v39
	v_cvt_f32_f16_sdwa v105, v31 dst_sel:DWORD dst_unused:UNUSED_PAD src0_sel:WORD_1
	v_cvt_f32_f16_e32 v104, v31
	v_cvt_f32_f16_sdwa v109, v40 dst_sel:DWORD dst_unused:UNUSED_PAD src0_sel:WORD_1
	v_rcp_f32_e32 v4, v1
	s_nop 0
	v_mul_f32_e32 v95, v2, v4
	v_cvt_f32_f16_e32 v108, v40
	v_cvt_f32_f16_sdwa v113, v32 dst_sel:DWORD dst_unused:UNUSED_PAD src0_sel:WORD_1
	v_cvt_f32_f16_e32 v112, v32
	v_rcp_f32_e32 v1, v0
	s_nop 0
	v_mul_f32_e32 v94, v3, v1
	v_cvt_f32_f16_sdwa v2, v54 dst_sel:DWORD dst_unused:UNUSED_PAD src0_sel:WORD_1
	v_cvt_f32_f16_e32 v3, v54
	v_cvt_f32_f16_sdwa v117, v41 dst_sel:DWORD dst_unused:UNUSED_PAD src0_sel:WORD_1
	v_cvt_f32_f16_e32 v116, v41
	v_mul_f32_e32 v1, 0xbfb8aa3b, v2
	v_mul_f32_e32 v0, 0xbfb8aa3b, v3
	v_exp_f32_e32 v0, v0
	v_exp_f32_e32 v1, v1
	v_cvt_f32_f16_sdwa v121, v33 dst_sel:DWORD dst_unused:UNUSED_PAD src0_sel:WORD_1
	v_cvt_f32_f16_e32 v120, v33
	v_pk_add_f32 v[0:1], v[0:1], 1.0 op_sel_hi:[1,0]
	s_nop 0
	s_nop 0
	v_rcp_f32_e32 v4, v1
	s_nop 0
	v_mul_f32_e32 v99, v2, v4
	s_nop 0
	v_rcp_f32_e32 v1, v0
	s_nop 0
	v_mul_f32_e32 v98, v3, v1
	v_cvt_f32_f16_sdwa v2, v63 dst_sel:DWORD dst_unused:UNUSED_PAD src0_sel:WORD_1
	v_cvt_f32_f16_e32 v3, v63
	v_mul_f32_e32 v1, 0xbfb8aa3b, v2
	v_mul_f32_e32 v0, 0xbfb8aa3b, v3
	v_exp_f32_e32 v0, v0
	v_exp_f32_e32 v1, v1
	s_nop 0
	v_pk_add_f32 v[0:1], v[0:1], 1.0 op_sel_hi:[1,0]
	s_nop 0
	s_nop 0
	v_rcp_f32_e32 v4, v1
	s_nop 0
	v_mul_f32_e32 v103, v2, v4
	s_nop 0
	v_rcp_f32_e32 v1, v0
	s_nop 0
	v_mul_f32_e32 v102, v3, v1
	v_cvt_f32_f16_sdwa v2, v55 dst_sel:DWORD dst_unused:UNUSED_PAD src0_sel:WORD_1
	v_cvt_f32_f16_e32 v3, v55
	v_mul_f32_e32 v1, 0xbfb8aa3b, v2
	v_mul_f32_e32 v0, 0xbfb8aa3b, v3
	v_exp_f32_e32 v0, v0
	v_exp_f32_e32 v1, v1
	s_nop 0
	v_pk_add_f32 v[0:1], v[0:1], 1.0 op_sel_hi:[1,0]
	s_nop 0
	s_nop 0
	v_rcp_f32_e32 v4, v1
	s_nop 0
	v_mul_f32_e32 v107, v2, v4
	s_nop 0
	v_rcp_f32_e32 v1, v0
	s_nop 0
	v_mul_f32_e32 v106, v3, v1
	v_cvt_f32_f16_sdwa v2, v64 dst_sel:DWORD dst_unused:UNUSED_PAD src0_sel:WORD_1
	v_cvt_f32_f16_e32 v3, v64
	v_mul_f32_e32 v1, 0xbfb8aa3b, v2
	v_mul_f32_e32 v0, 0xbfb8aa3b, v3
	v_exp_f32_e32 v0, v0
	v_exp_f32_e32 v1, v1
	s_nop 0
	v_pk_add_f32 v[0:1], v[0:1], 1.0 op_sel_hi:[1,0]
	s_nop 0
	s_nop 0
	v_rcp_f32_e32 v4, v1
	s_nop 0
	v_mul_f32_e32 v111, v2, v4
	s_nop 0
	v_rcp_f32_e32 v1, v0
	s_nop 0
	v_mul_f32_e32 v110, v3, v1
	v_cvt_f32_f16_sdwa v2, v56 dst_sel:DWORD dst_unused:UNUSED_PAD src0_sel:WORD_1
	v_cvt_f32_f16_e32 v3, v56
	v_mul_f32_e32 v1, 0xbfb8aa3b, v2
	v_mul_f32_e32 v0, 0xbfb8aa3b, v3
	v_exp_f32_e32 v0, v0
	v_exp_f32_e32 v1, v1
	s_nop 0
	v_pk_add_f32 v[0:1], v[0:1], 1.0 op_sel_hi:[1,0]
	s_nop 0
	s_nop 0
	v_rcp_f32_e32 v4, v1
	s_nop 0
	v_mul_f32_e32 v115, v2, v4
	s_nop 0
	v_rcp_f32_e32 v1, v0
	s_nop 0
	v_mul_f32_e32 v114, v3, v1
	v_cvt_f32_f16_sdwa v2, v65 dst_sel:DWORD dst_unused:UNUSED_PAD src0_sel:WORD_1
	v_cvt_f32_f16_e32 v3, v65
	v_mul_f32_e32 v1, 0xbfb8aa3b, v2
	v_mul_f32_e32 v0, 0xbfb8aa3b, v3
	v_exp_f32_e32 v0, v0
	v_exp_f32_e32 v1, v1
	s_nop 0
	v_pk_add_f32 v[0:1], v[0:1], 1.0 op_sel_hi:[1,0]
	s_nop 0
	s_nop 0
	v_rcp_f32_e32 v4, v1
	s_nop 0
	v_mul_f32_e32 v119, v2, v4
	s_nop 0
	v_rcp_f32_e32 v1, v0
	s_nop 0
	v_mul_f32_e32 v118, v3, v1
	v_cvt_f32_f16_sdwa v2, v57 dst_sel:DWORD dst_unused:UNUSED_PAD src0_sel:WORD_1
	v_cvt_f32_f16_e32 v3, v57
	v_mul_f32_e32 v1, 0xbfb8aa3b, v2
	v_mul_f32_e32 v0, 0xbfb8aa3b, v3
	v_exp_f32_e32 v0, v0
	v_exp_f32_e32 v1, v1
	s_nop 0
	v_pk_add_f32 v[0:1], v[0:1], 1.0 op_sel_hi:[1,0]
	s_nop 0
	s_nop 0
	v_rcp_f32_e32 v4, v1
	s_nop 0
	v_mul_f32_e32 v123, v2, v4
	s_nop 0
	v_rcp_f32_e32 v1, v0
	s_nop 0
	v_mul_f32_e32 v122, v3, v1
	s_and_saveexec_b64 s[2:3], s[42:43]
	s_xor_b64 s[6:7], exec, s[2:3]
	s_cbranch_execz .LBB0_156
	v_pk_mul_f32 v[0:1], v[92:93], v[92:93]
	v_pk_mul_f32 v[2:3], v[100:101], v[100:101]
	v_add_f32_e32 v0, v0, v1
	v_add_f32_e32 v0, v2, v0
	v_pk_mul_f32 v[4:5], v[108:109], v[108:109]
	v_add_f32_e32 v0, v3, v0
	v_add_f32_e32 v0, v4, v0
	v_pk_mul_f32 v[6:7], v[116:117], v[116:117]
	v_add_f32_e32 v0, v5, v0
	v_add_f32_e32 v0, v6, v0
	v_pk_mul_f32 v[8:9], v[96:97], v[96:97]
	v_add_f32_e32 v0, v7, v0
	v_add_f32_e32 v0, v8, v0
	v_pk_mul_f32 v[10:11], v[104:105], v[104:105]
	v_add_f32_e32 v0, v9, v0
	v_add_f32_e32 v0, v10, v0
	v_pk_mul_f32 v[12:13], v[112:113], v[112:113]
	v_add_f32_e32 v0, v11, v0
	v_add_f32_e32 v0, v12, v0
	v_pk_mul_f32 v[14:15], v[120:121], v[120:121]
	v_add_f32_e32 v0, v13, v0
	v_add_f32_e32 v0, v14, v0
	v_add_f32_e32 v0, v15, v0
	s_nop 1
	v_add_f32_dpp v0, v0, v0 quad_perm:[1,0,3,2] row_mask:0xf bank_mask:0xf bound_ctrl:1
	s_nop 1
	v_add_f32_dpp v0, v0, v0 quad_perm:[2,3,0,1] row_mask:0xf bank_mask:0xf bound_ctrl:1
	v_fmamk_f32 v0, v0, 0x3c800000, v203
	v_mul_f32_e32 v1, 0x4b800000, v0
	v_cmp_gt_f32_e32 vcc, s16, v0
	s_nop 1
	v_cndmask_b32_e32 v0, v0, v1, vcc
	v_rsq_f32_e32 v0, v0
	s_nop 0
	v_mul_f32_e32 v1, 0x45800000, v0
	v_cndmask_b32_e32 v0, v0, v1, vcc
	v_pk_mul_f32 v[2:3], v[0:1], v[120:121] op_sel_hi:[0,1]
	v_pk_mul_f32 v[4:5], v[0:1], v[112:113] op_sel_hi:[0,1]
	v_pk_mul_f32 v[6:7], v[0:1], v[104:105] op_sel_hi:[0,1]
	v_pk_mul_f32 v[8:9], v[0:1], v[96:97] op_sel_hi:[0,1]
	v_pk_mul_f32 v[10:11], v[0:1], v[116:117] op_sel_hi:[0,1]
	v_pk_mul_f32 v[12:13], v[0:1], v[108:109] op_sel_hi:[0,1]
	v_pk_mul_f32 v[14:15], v[0:1], v[100:101] op_sel_hi:[0,1]
	v_pk_mul_f32 v[0:1], v[0:1], v[92:93] op_sel_hi:[0,1]
	v_pk_mul_f32 v[0:1], v[66:67], v[0:1]
	v_pk_mul_f32 v[92:93], v[68:69], v[14:15]
	v_pk_mul_f32 v[96:97], v[70:71], v[12:13]
	v_pk_mul_f32 v[100:101], v[72:73], v[10:11]
	v_pk_mul_f32 v[8:9], v[74:75], v[8:9]
	v_pk_mul_f32 v[6:7], v[76:77], v[6:7]
	v_pk_mul_f32 v[4:5], v[78:79], v[4:5]
	v_pk_mul_f32 v[2:3], v[80:81], v[2:3]
	v_pk_mul_f32 v[12:13], v[114:115], v[4:5]
	v_pk_mul_f32 v[14:15], v[122:123], v[2:3]
	v_pk_mul_f32 v[10:11], v[106:107], v[6:7]
	v_pk_mul_f32 v[8:9], v[98:99], v[8:9]
	v_pk_mul_f32 v[6:7], v[118:119], v[100:101]
	v_pk_mul_f32 v[4:5], v[110:111], v[96:97]
	v_pk_mul_f32 v[2:3], v[102:103], v[92:93]
	v_pk_mul_f32 v[0:1], v[94:95], v[0:1]

; __device__ __forceinline__ float siluf_(float x) { return x / (1.0f + __expf(-x)); }
; __device__ __forceinline__ float red4(float x) { x += dppf<0xB1>(x); x += dppf<0x4E>(x); return x; }
; __device__ __forceinline__ float red8(float x) { x = red4(x); x += dppf<0x141>(x); return x; }
; __device__ __forceinline__ void u4f(const u32x4& u, float (&f)[8]) { h2f(u.x, f[0], f[1]); h2f(u.y, f[2], f[3]); h2f(u.z, f[4], f[5]); h2f(u.w, f[6], f[7]); }
; __device__ __forceinline__ void phase_post(const Params& p, int l) {
;     ...
;                 { float t0[8], t1[8]; u4f(rg[bb][0], t0); u4f(rg[bb][1], t1);
; #pragma unroll
;                   for (int i = 0; i < 8; ++i) { g[i] = siluf_(t0[i]); g[i + 8] = siluf_(t1[i]); } }
;                 float ss = 0.f;
;                 if (mixer == 3) {
; #pragma unroll
;                     for (int i = 0; i < 16; ++i) { x[i] *= g[i]; ss += x[i] * x[i]; }
;                     ss = red8(ss);
;                     const float sc = rsqrtf(ss * (1.0f / 128.0f) + EPS);
; #pragma unroll
;                     for (int i = 0; i < 16; ++i) x[i] = x[i] * sc * wn[i];
;                 } else {
; #pragma unroll
;                     for (int i = 0; i < 16; ++i) ss += x[i] * x[i];
;                     ss = red4(ss);
;                     const float sc = rsqrtf(ss * (1.0f / 64.0f) + EPS);
; #pragma unroll
;                     for (int i = 0; i < 16; ++i) x[i] = x[i] * sc * wn[i] * g[i];
;                 }
.LBB0_159:
	v_cvt_f32_f16_sdwa v2, v58 dst_sel:DWORD dst_unused:UNUSED_PAD src0_sel:WORD_1
	v_cvt_f32_f16_e32 v3, v58
	v_cvt_f32_f16_sdwa v93, v34 dst_sel:DWORD dst_unused:UNUSED_PAD src0_sel:WORD_1
	v_cvt_f32_f16_e32 v92, v34
	v_mul_f32_e32 v1, 0xbfb8aa3b, v2
	v_mul_f32_e32 v0, 0xbfb8aa3b, v3
	v_exp_f32_e32 v0, v0
	v_exp_f32_e32 v1, v1
	v_cvt_f32_f16_sdwa v97, v22 dst_sel:DWORD dst_unused:UNUSED_PAD src0_sel:WORD_1
	v_cvt_f32_f16_e32 v96, v22
	v_cvt_f32_f16_sdwa v101, v35 dst_sel:DWORD dst_unused:UNUSED_PAD src0_sel:WORD_1
	v_pk_add_f32 v[0:1], v[0:1], 1.0 op_sel_hi:[1,0]
	v_cvt_f32_f16_e32 v100, v35
	v_cvt_f32_f16_sdwa v105, v23 dst_sel:DWORD dst_unused:UNUSED_PAD src0_sel:WORD_1
	v_cvt_f32_f16_e32 v104, v23
	v_cvt_f32_f16_sdwa v109, v36 dst_sel:DWORD dst_unused:UNUSED_PAD src0_sel:WORD_1
	v_rcp_f32_e32 v4, v1
	s_nop 0
	v_mul_f32_e32 v95, v2, v4
	v_cvt_f32_f16_e32 v108, v36
	v_cvt_f32_f16_sdwa v113, v24 dst_sel:DWORD dst_unused:UNUSED_PAD src0_sel:WORD_1
	v_cvt_f32_f16_e32 v112, v24
	v_rcp_f32_e32 v1, v0
	s_nop 0
	v_mul_f32_e32 v94, v3, v1
	v_cvt_f32_f16_sdwa v2, v46 dst_sel:DWORD dst_unused:UNUSED_PAD src0_sel:WORD_1
	v_cvt_f32_f16_e32 v3, v46
	v_cvt_f32_f16_sdwa v117, v37 dst_sel:DWORD dst_unused:UNUSED_PAD src0_sel:WORD_1
	v_cvt_f32_f16_e32 v116, v37
	v_mul_f32_e32 v1, 0xbfb8aa3b, v2
	v_mul_f32_e32 v0, 0xbfb8aa3b, v3
	v_exp_f32_e32 v0, v0
	v_exp_f32_e32 v1, v1
	v_cvt_f32_f16_sdwa v121, v25 dst_sel:DWORD dst_unused:UNUSED_PAD src0_sel:WORD_1
	v_cvt_f32_f16_e32 v120, v25
	v_pk_add_f32 v[0:1], v[0:1], 1.0 op_sel_hi:[1,0]
	s_nop 0
	s_nop 0
	v_rcp_f32_e32 v4, v1
	s_nop 0
	v_mul_f32_e32 v99, v2, v4
	s_nop 0
	v_rcp_f32_e32 v1, v0
	s_nop 0
	v_mul_f32_e32 v98, v3, v1
	v_cvt_f32_f16_sdwa v2, v59 dst_sel:DWORD dst_unused:UNUSED_PAD src0_sel:WORD_1
	v_cvt_f32_f16_e32 v3, v59
	v_mul_f32_e32 v1, 0xbfb8aa3b, v2
	v_mul_f32_e32 v0, 0xbfb8aa3b, v3
	v_exp_f32_e32 v0, v0
	v_exp_f32_e32 v1, v1
	s_nop 0
	v_pk_add_f32 v[0:1], v[0:1], 1.0 op_sel_hi:[1,0]
	s_nop 0
	s_nop 0
	v_rcp_f32_e32 v4, v1
	s_nop 0
	v_mul_f32_e32 v103, v2, v4
	s_nop 0
	v_rcp_f32_e32 v1, v0
	s_nop 0
	v_mul_f32_e32 v102, v3, v1
	v_cvt_f32_f16_sdwa v2, v47 dst_sel:DWORD dst_unused:UNUSED_PAD src0_sel:WORD_1
	v_cvt_f32_f16_e32 v3, v47
	v_mul_f32_e32 v1, 0xbfb8aa3b, v2
	v_mul_f32_e32 v0, 0xbfb8aa3b, v3
	v_exp_f32_e32 v0, v0
	v_exp_f32_e32 v1, v1
	s_nop 0
	v_pk_add_f32 v[0:1], v[0:1], 1.0 op_sel_hi:[1,0]
	s_nop 0
	s_nop 0
	v_rcp_f32_e32 v4, v1
	s_nop 0
	v_mul_f32_e32 v107, v2, v4
	s_nop 0
	v_rcp_f32_e32 v1, v0
	s_nop 0
	v_mul_f32_e32 v106, v3, v1
	v_cvt_f32_f16_sdwa v2, v60 dst_sel:DWORD dst_unused:UNUSED_PAD src0_sel:WORD_1
	v_cvt_f32_f16_e32 v3, v60
	v_mul_f32_e32 v1, 0xbfb8aa3b, v2
	v_mul_f32_e32 v0, 0xbfb8aa3b, v3
	v_exp_f32_e32 v0, v0
	v_exp_f32_e32 v1, v1
	s_nop 0
	v_pk_add_f32 v[0:1], v[0:1], 1.0 op_sel_hi:[1,0]
	s_nop 0
	s_nop 0
	v_rcp_f32_e32 v4, v1
	s_nop 0
	v_mul_f32_e32 v111, v2, v4
	s_nop 0
	v_rcp_f32_e32 v1, v0
	s_nop 0
	v_mul_f32_e32 v110, v3, v1
	v_cvt_f32_f16_sdwa v2, v48 dst_sel:DWORD dst_unused:UNUSED_PAD src0_sel:WORD_1
	v_cvt_f32_f16_e32 v3, v48
	v_mul_f32_e32 v1, 0xbfb8aa3b, v2
	v_mul_f32_e32 v0, 0xbfb8aa3b, v3
	v_exp_f32_e32 v0, v0
	v_exp_f32_e32 v1, v1
	s_nop 0
	v_pk_add_f32 v[0:1], v[0:1], 1.0 op_sel_hi:[1,0]
	s_nop 0
	s_nop 0
	v_rcp_f32_e32 v4, v1
	s_nop 0
	v_mul_f32_e32 v115, v2, v4
	s_nop 0
	v_rcp_f32_e32 v1, v0
	s_nop 0
	v_mul_f32_e32 v114, v3, v1
	v_cvt_f32_f16_sdwa v2, v61 dst_sel:DWORD dst_unused:UNUSED_PAD src0_sel:WORD_1
	v_cvt_f32_f16_e32 v3, v61
	v_mul_f32_e32 v1, 0xbfb8aa3b, v2
	v_mul_f32_e32 v0, 0xbfb8aa3b, v3
	v_exp_f32_e32 v0, v0
	v_exp_f32_e32 v1, v1
	s_nop 0
	v_pk_add_f32 v[0:1], v[0:1], 1.0 op_sel_hi:[1,0]
	s_nop 0
	s_nop 0
	v_rcp_f32_e32 v4, v1
	s_nop 0
	v_mul_f32_e32 v119, v2, v4
	s_nop 0
	v_rcp_f32_e32 v1, v0
	s_nop 0
	v_mul_f32_e32 v118, v3, v1
	v_cvt_f32_f16_sdwa v2, v49 dst_sel:DWORD dst_unused:UNUSED_PAD src0_sel:WORD_1
	v_cvt_f32_f16_e32 v3, v49
	v_mul_f32_e32 v1, 0xbfb8aa3b, v2
	v_mul_f32_e32 v0, 0xbfb8aa3b, v3
	v_exp_f32_e32 v0, v0
	v_exp_f32_e32 v1, v1
	s_nop 0
	v_pk_add_f32 v[0:1], v[0:1], 1.0 op_sel_hi:[1,0]
	s_nop 0
	s_nop 0
	v_rcp_f32_e32 v4, v1
	s_nop 0
	v_mul_f32_e32 v123, v2, v4
	s_nop 0
	v_rcp_f32_e32 v1, v0
	s_nop 0
	v_mul_f32_e32 v122, v3, v1
	s_and_saveexec_b64 s[2:3], s[42:43]
	s_xor_b64 s[6:7], exec, s[2:3]
	s_cbranch_execz .LBB0_161
	v_pk_mul_f32 v[0:1], v[92:93], v[92:93]
	v_pk_mul_f32 v[2:3], v[100:101], v[100:101]
	v_add_f32_e32 v0, v0, v1
	v_add_f32_e32 v0, v2, v0
	v_pk_mul_f32 v[4:5], v[108:109], v[108:109]
	v_add_f32_e32 v0, v3, v0
	v_add_f32_e32 v0, v4, v0
	v_pk_mul_f32 v[6:7], v[116:117], v[116:117]
	v_add_f32_e32 v0, v5, v0
	v_add_f32_e32 v0, v6, v0
	v_pk_mul_f32 v[8:9], v[96:97], v[96:97]
	v_add_f32_e32 v0, v7, v0
	v_add_f32_e32 v0, v8, v0
	v_pk_mul_f32 v[10:11], v[104:105], v[104:105]
	v_add_f32_e32 v0, v9, v0
	v_add_f32_e32 v0, v10, v0
	v_pk_mul_f32 v[12:13], v[112:113], v[112:113]
	v_add_f32_e32 v0, v11, v0
	v_add_f32_e32 v0, v12, v0
	v_pk_mul_f32 v[14:15], v[120:121], v[120:121]
	v_add_f32_e32 v0, v13, v0
	v_add_f32_e32 v0, v14, v0
	v_add_f32_e32 v0, v15, v0
	s_nop 1
	v_add_f32_dpp v0, v0, v0 quad_perm:[1,0,3,2] row_mask:0xf bank_mask:0xf bound_ctrl:1
	s_nop 1
	v_add_f32_dpp v0, v0, v0 quad_perm:[2,3,0,1] row_mask:0xf bank_mask:0xf bound_ctrl:1
	v_fmamk_f32 v0, v0, 0x3c800000, v203
	v_mul_f32_e32 v1, 0x4b800000, v0
	v_cmp_gt_f32_e32 vcc, s16, v0
	s_nop 1
	v_cndmask_b32_e32 v0, v0, v1, vcc
	v_rsq_f32_e32 v0, v0
	s_nop 0
	v_mul_f32_e32 v1, 0x45800000, v0
	v_cndmask_b32_e32 v0, v0, v1, vcc
	v_pk_mul_f32 v[2:3], v[0:1], v[120:121] op_sel_hi:[0,1]
	v_pk_mul_f32 v[4:5], v[0:1], v[112:113] op_sel_hi:[0,1]
	v_pk_mul_f32 v[6:7], v[0:1], v[104:105] op_sel_hi:[0,1]
	v_pk_mul_f32 v[8:9], v[0:1], v[96:97] op_sel_hi:[0,1]
	v_pk_mul_f32 v[10:11], v[0:1], v[116:117] op_sel_hi:[0,1]
	v_pk_mul_f32 v[12:13], v[0:1], v[108:109] op_sel_hi:[0,1]
	v_pk_mul_f32 v[14:15], v[0:1], v[100:101] op_sel_hi:[0,1]
	v_pk_mul_f32 v[0:1], v[0:1], v[92:93] op_sel_hi:[0,1]
	v_pk_mul_f32 v[0:1], v[66:67], v[0:1]
	v_pk_mul_f32 v[92:93], v[68:69], v[14:15]
	v_pk_mul_f32 v[96:97], v[70:71], v[12:13]
	v_pk_mul_f32 v[100:101], v[72:73], v[10:11]
	v_pk_mul_f32 v[8:9], v[74:75], v[8:9]
	v_pk_mul_f32 v[6:7], v[76:77], v[6:7]
	v_pk_mul_f32 v[4:5], v[78:79], v[4:5]
	v_pk_mul_f32 v[2:3], v[80:81], v[2:3]
	v_pk_mul_f32 v[12:13], v[114:115], v[4:5]
	v_pk_mul_f32 v[14:15], v[122:123], v[2:3]
	v_pk_mul_f32 v[10:11], v[106:107], v[6:7]
	v_pk_mul_f32 v[8:9], v[98:99], v[8:9]
	v_pk_mul_f32 v[6:7], v[118:119], v[100:101]
	v_pk_mul_f32 v[4:5], v[110:111], v[96:97]
	v_pk_mul_f32 v[2:3], v[102:103], v[92:93]
	v_pk_mul_f32 v[0:1], v[94:95], v[0:1]

; __device__ __forceinline__ float siluf_(float x) { return x / (1.0f + __expf(-x)); }
; __device__ __forceinline__ float red4(float x) { x += dppf<0xB1>(x); x += dppf<0x4E>(x); return x; }
; __device__ __forceinline__ float red8(float x) { x = red4(x); x += dppf<0x141>(x); return x; }
; __device__ __forceinline__ void u4f(const u32x4& u, float (&f)[8]) { h2f(u.x, f[0], f[1]); h2f(u.y, f[2], f[3]); h2f(u.z, f[4], f[5]); h2f(u.w, f[6], f[7]); }
; __device__ __forceinline__ void phase_post(const Params& p, int l) {
;     ...
;                 { float t0[8], t1[8]; u4f(rg[bb][0], t0); u4f(rg[bb][1], t1);
; #pragma unroll
;                   for (int i = 0; i < 8; ++i) { g[i] = siluf_(t0[i]); g[i + 8] = siluf_(t1[i]); } }
;                 float ss = 0.f;
;                 if (mixer == 3) {
; #pragma unroll
;                     for (int i = 0; i < 16; ++i) { x[i] *= g[i]; ss += x[i] * x[i]; }
;                     ss = red8(ss);
;                     const float sc = rsqrtf(ss * (1.0f / 128.0f) + EPS);
; #pragma unroll
;                     for (int i = 0; i < 16; ++i) x[i] = x[i] * sc * wn[i];
;                 } else {
; #pragma unroll
;                     for (int i = 0; i < 16; ++i) ss += x[i] * x[i];
;                     ss = red4(ss);
;                     const float sc = rsqrtf(ss * (1.0f / 64.0f) + EPS);
; #pragma unroll
;                     for (int i = 0; i < 16; ++i) x[i] = x[i] * sc * wn[i] * g[i];
;                 }
.LBB0_164:
	v_cvt_f32_f16_sdwa v2, v50 dst_sel:DWORD dst_unused:UNUSED_PAD src0_sel:WORD_1
	v_cvt_f32_f16_e32 v3, v50
	v_cvt_f32_f16_sdwa v91, v26 dst_sel:DWORD dst_unused:UNUSED_PAD src0_sel:WORD_1
	v_cvt_f32_f16_e32 v90, v26
	v_mul_f32_e32 v1, 0xbfb8aa3b, v2
	v_mul_f32_e32 v0, 0xbfb8aa3b, v3
	v_exp_f32_e32 v0, v0
	v_exp_f32_e32 v1, v1
	v_cvt_f32_f16_sdwa v95, v18 dst_sel:DWORD dst_unused:UNUSED_PAD src0_sel:WORD_1
	v_cvt_f32_f16_e32 v94, v18
	v_cvt_f32_f16_sdwa v99, v27 dst_sel:DWORD dst_unused:UNUSED_PAD src0_sel:WORD_1
	v_pk_add_f32 v[0:1], v[0:1], 1.0 op_sel_hi:[1,0]
	v_cvt_f32_f16_e32 v98, v27
	v_cvt_f32_f16_sdwa v103, v19 dst_sel:DWORD dst_unused:UNUSED_PAD src0_sel:WORD_1
	v_cvt_f32_f16_e32 v102, v19
	v_cvt_f32_f16_sdwa v107, v28 dst_sel:DWORD dst_unused:UNUSED_PAD src0_sel:WORD_1
	v_rcp_f32_e32 v4, v1
	s_nop 0
	v_mul_f32_e32 v93, v2, v4
	v_cvt_f32_f16_e32 v106, v28
	v_cvt_f32_f16_sdwa v111, v20 dst_sel:DWORD dst_unused:UNUSED_PAD src0_sel:WORD_1
	v_cvt_f32_f16_e32 v110, v20
	v_rcp_f32_e32 v1, v0
	s_nop 0
	v_mul_f32_e32 v92, v3, v1
	v_cvt_f32_f16_sdwa v2, v42 dst_sel:DWORD dst_unused:UNUSED_PAD src0_sel:WORD_1
	v_cvt_f32_f16_e32 v3, v42
	v_cvt_f32_f16_sdwa v115, v29 dst_sel:DWORD dst_unused:UNUSED_PAD src0_sel:WORD_1
	v_cvt_f32_f16_e32 v114, v29
	v_mul_f32_e32 v1, 0xbfb8aa3b, v2
	v_mul_f32_e32 v0, 0xbfb8aa3b, v3
	v_exp_f32_e32 v0, v0
	v_exp_f32_e32 v1, v1
	v_cvt_f32_f16_sdwa v119, v21 dst_sel:DWORD dst_unused:UNUSED_PAD src0_sel:WORD_1
	v_cvt_f32_f16_e32 v118, v21
	v_pk_add_f32 v[0:1], v[0:1], 1.0 op_sel_hi:[1,0]
	s_nop 0
	s_nop 0
	v_rcp_f32_e32 v4, v1
	s_nop 0
	v_mul_f32_e32 v97, v2, v4
	s_nop 0
	v_rcp_f32_e32 v1, v0
	s_nop 0
	v_mul_f32_e32 v96, v3, v1
	v_cvt_f32_f16_sdwa v2, v51 dst_sel:DWORD dst_unused:UNUSED_PAD src0_sel:WORD_1
	v_cvt_f32_f16_e32 v3, v51
	v_mul_f32_e32 v1, 0xbfb8aa3b, v2
	v_mul_f32_e32 v0, 0xbfb8aa3b, v3
	v_exp_f32_e32 v0, v0
	v_exp_f32_e32 v1, v1
	s_nop 0
	v_pk_add_f32 v[0:1], v[0:1], 1.0 op_sel_hi:[1,0]
	s_nop 0
	s_nop 0
	v_rcp_f32_e32 v4, v1
	s_nop 0
	v_mul_f32_e32 v101, v2, v4
	s_nop 0
	v_rcp_f32_e32 v1, v0
	s_nop 0
	v_mul_f32_e32 v100, v3, v1
	v_cvt_f32_f16_sdwa v2, v43 dst_sel:DWORD dst_unused:UNUSED_PAD src0_sel:WORD_1
	v_cvt_f32_f16_e32 v3, v43
	v_mul_f32_e32 v1, 0xbfb8aa3b, v2
	v_mul_f32_e32 v0, 0xbfb8aa3b, v3
	v_exp_f32_e32 v0, v0
	v_exp_f32_e32 v1, v1
	s_nop 0
	v_pk_add_f32 v[0:1], v[0:1], 1.0 op_sel_hi:[1,0]
	s_nop 0
	s_nop 0
	v_rcp_f32_e32 v4, v1
	s_nop 0
	v_mul_f32_e32 v105, v2, v4
	s_nop 0
	v_rcp_f32_e32 v1, v0
	s_nop 0
	v_mul_f32_e32 v104, v3, v1
	v_cvt_f32_f16_sdwa v2, v52 dst_sel:DWORD dst_unused:UNUSED_PAD src0_sel:WORD_1
	v_cvt_f32_f16_e32 v3, v52
	v_mul_f32_e32 v1, 0xbfb8aa3b, v2
	v_mul_f32_e32 v0, 0xbfb8aa3b, v3
	v_exp_f32_e32 v0, v0
	v_exp_f32_e32 v1, v1
	s_nop 0
	v_pk_add_f32 v[0:1], v[0:1], 1.0 op_sel_hi:[1,0]
	s_nop 0
	s_nop 0
	v_rcp_f32_e32 v4, v1
	s_nop 0
	v_mul_f32_e32 v109, v2, v4
	s_nop 0
	v_rcp_f32_e32 v1, v0
	s_nop 0
	v_mul_f32_e32 v108, v3, v1
	v_cvt_f32_f16_sdwa v2, v44 dst_sel:DWORD dst_unused:UNUSED_PAD src0_sel:WORD_1
	v_cvt_f32_f16_e32 v3, v44
	v_mul_f32_e32 v1, 0xbfb8aa3b, v2
	v_mul_f32_e32 v0, 0xbfb8aa3b, v3
	v_exp_f32_e32 v0, v0
	v_exp_f32_e32 v1, v1
	s_nop 0
	v_pk_add_f32 v[0:1], v[0:1], 1.0 op_sel_hi:[1,0]
	s_nop 0
	s_nop 0
	v_rcp_f32_e32 v4, v1
	s_nop 0
	v_mul_f32_e32 v113, v2, v4
	s_nop 0
	v_rcp_f32_e32 v1, v0
	s_nop 0
	v_mul_f32_e32 v112, v3, v1
	v_cvt_f32_f16_sdwa v2, v53 dst_sel:DWORD dst_unused:UNUSED_PAD src0_sel:WORD_1
	v_cvt_f32_f16_e32 v3, v53
	v_mul_f32_e32 v1, 0xbfb8aa3b, v2
	v_mul_f32_e32 v0, 0xbfb8aa3b, v3
	v_exp_f32_e32 v0, v0
	v_exp_f32_e32 v1, v1
	s_nop 0
	v_pk_add_f32 v[0:1], v[0:1], 1.0 op_sel_hi:[1,0]
	s_nop 0
	s_nop 0
	v_rcp_f32_e32 v4, v1
	s_nop 0
	v_mul_f32_e32 v117, v2, v4
	s_nop 0
	v_rcp_f32_e32 v1, v0
	s_nop 0
	v_mul_f32_e32 v116, v3, v1
	v_cvt_f32_f16_sdwa v2, v45 dst_sel:DWORD dst_unused:UNUSED_PAD src0_sel:WORD_1
	v_cvt_f32_f16_e32 v3, v45
	v_mul_f32_e32 v1, 0xbfb8aa3b, v2
	v_mul_f32_e32 v0, 0xbfb8aa3b, v3
	v_exp_f32_e32 v0, v0
	v_exp_f32_e32 v1, v1
	s_nop 0
	v_pk_add_f32 v[0:1], v[0:1], 1.0 op_sel_hi:[1,0]
	s_nop 0
	s_nop 0
	v_rcp_f32_e32 v4, v1
	s_nop 0
	v_mul_f32_e32 v121, v2, v4
	s_nop 0
	v_rcp_f32_e32 v1, v0
	s_nop 0
	v_mul_f32_e32 v120, v3, v1
	s_and_saveexec_b64 s[2:3], s[42:43]
	s_xor_b64 s[6:7], exec, s[2:3]
	s_cbranch_execz .LBB0_166
	v_pk_mul_f32 v[0:1], v[90:91], v[90:91]
	v_pk_mul_f32 v[2:3], v[98:99], v[98:99]
	v_add_f32_e32 v0, v0, v1
	v_add_f32_e32 v0, v2, v0
	v_pk_mul_f32 v[4:5], v[106:107], v[106:107]
	v_add_f32_e32 v0, v3, v0
	v_add_f32_e32 v0, v4, v0
	v_pk_mul_f32 v[6:7], v[114:115], v[114:115]
	v_add_f32_e32 v0, v5, v0
	v_add_f32_e32 v0, v6, v0
	v_pk_mul_f32 v[8:9], v[94:95], v[94:95]
	v_add_f32_e32 v0, v7, v0
	v_add_f32_e32 v0, v8, v0
	v_pk_mul_f32 v[10:11], v[102:103], v[102:103]
	v_add_f32_e32 v0, v9, v0
	v_add_f32_e32 v0, v10, v0
	v_pk_mul_f32 v[12:13], v[110:111], v[110:111]
	v_add_f32_e32 v0, v11, v0
	v_add_f32_e32 v0, v12, v0
	v_pk_mul_f32 v[14:15], v[118:119], v[118:119]
	v_add_f32_e32 v0, v13, v0
	v_add_f32_e32 v0, v14, v0
	v_add_f32_e32 v0, v15, v0
	s_nop 1
	v_add_f32_dpp v0, v0, v0 quad_perm:[1,0,3,2] row_mask:0xf bank_mask:0xf bound_ctrl:1
	s_nop 1
	v_add_f32_dpp v0, v0, v0 quad_perm:[2,3,0,1] row_mask:0xf bank_mask:0xf bound_ctrl:1
	v_fmamk_f32 v0, v0, 0x3c800000, v203
	v_mul_f32_e32 v1, 0x4b800000, v0
	v_cmp_gt_f32_e32 vcc, s16, v0
	s_nop 1
	v_cndmask_b32_e32 v0, v0, v1, vcc
	v_rsq_f32_e32 v0, v0
	s_nop 0
	v_mul_f32_e32 v1, 0x45800000, v0
	v_cndmask_b32_e32 v0, v0, v1, vcc
	v_pk_mul_f32 v[2:3], v[0:1], v[118:119] op_sel_hi:[0,1]
	v_pk_mul_f32 v[4:5], v[0:1], v[110:111] op_sel_hi:[0,1]
	v_pk_mul_f32 v[6:7], v[0:1], v[102:103] op_sel_hi:[0,1]
	v_pk_mul_f32 v[8:9], v[0:1], v[94:95] op_sel_hi:[0,1]
	v_pk_mul_f32 v[10:11], v[0:1], v[114:115] op_sel_hi:[0,1]
	v_pk_mul_f32 v[12:13], v[0:1], v[106:107] op_sel_hi:[0,1]
	v_pk_mul_f32 v[14:15], v[0:1], v[98:99] op_sel_hi:[0,1]
	v_pk_mul_f32 v[0:1], v[0:1], v[90:91] op_sel_hi:[0,1]
	v_pk_mul_f32 v[0:1], v[66:67], v[0:1]
	v_pk_mul_f32 v[90:91], v[68:69], v[14:15]
	v_pk_mul_f32 v[94:95], v[70:71], v[12:13]
	v_pk_mul_f32 v[98:99], v[72:73], v[10:11]
	v_pk_mul_f32 v[8:9], v[74:75], v[8:9]
	v_pk_mul_f32 v[6:7], v[76:77], v[6:7]
	v_pk_mul_f32 v[4:5], v[78:79], v[4:5]
	v_pk_mul_f32 v[2:3], v[80:81], v[2:3]
	v_pk_mul_f32 v[12:13], v[112:113], v[4:5]
	v_pk_mul_f32 v[14:15], v[120:121], v[2:3]
	v_pk_mul_f32 v[10:11], v[104:105], v[6:7]
	v_pk_mul_f32 v[8:9], v[96:97], v[8:9]
	v_pk_mul_f32 v[6:7], v[116:117], v[98:99]
	v_pk_mul_f32 v[4:5], v[108:109], v[94:95]
	v_pk_mul_f32 v[2:3], v[100:101], v[90:91]
	v_pk_mul_f32 v[0:1], v[92:93], v[0:1]

; #define LAS __attribute__((address_space(3)))
; __device__ __forceinline__ float sigmoidf_(float x) { return 1.0f / (1.0f + __expf(-x)); }
; __device__ __forceinline__ float softplusf_(float x) { return x > 20.f ? x : log1pf(expf(x)); }
; template <int MIX, bool SAMPLE>
; __device__ __forceinline__ void rec_process(const Raw<MIX>& R, const MixPar& par, int l, LAS float* L, int chunk, int sg, int head) {
;     ...
;         if (cgi == 0) { const float a = expf(-par.f[0] * softplusf_(R.ga + par.f[1]));
;             *(LAS f32x4*)(L + C::OFF_SC + s * 4) = (f32x4){a, sigmoidf_(R.gb), kq, 0.f}; }
.LBB0_194:
	s_or_b64 exec, exec, s[6:7]
	v_mul_f32_e32 v8, 0x3fb8aa3b, v2
	v_rndne_f32_e32 v9, v8
	v_sub_f32_e32 v10, v8, v9
	v_fma_f32 v8, v2, s19, -v8
	v_fmac_f32_e32 v8, 0x32a5705f, v2
	v_add_f32_e32 v8, v10, v8
	v_cvt_i32_f32_e32 v9, v9
	v_exp_f32_e32 v8, v8
	s_waitcnt vmcnt(0)
	v_cvt_f32_f16_e32 v3, v3
	v_cmp_ngt_f32_e32 vcc, s96, v2
	v_add_f32_e32 v16, v6, v7
	v_ldexp_f32 v8, v8, v9
	v_cndmask_b32_e32 v8, 0, v8, vcc
	v_cmp_nlt_f32_e32 vcc, s97, v2
	v_mul_f32_e32 v3, 0xbfb8aa3b, v3
	v_exp_f32_e32 v3, v3
	v_cndmask_b32_e32 v2, v216, v8, vcc
	v_mul_f32_e64 v2, v5, -v2
	v_mul_f32_e32 v5, 0x3fb8aa3b, v2
	v_fma_f32 v8, v2, s19, -v5
	v_rndne_f32_e32 v9, v5
	v_fmac_f32_e32 v8, 0x32a5705f, v2
	v_sub_f32_e32 v5, v5, v9
	v_add_f32_e32 v5, v5, v8
	v_add_f32_e32 v3, 1.0, v3
	v_exp_f32_e32 v5, v5
	v_cvt_i32_f32_e32 v8, v9
	v_ldexp_f32 v5, v5, v8
	v_cmp_ngt_f32_e32 vcc, s96, v2
	s_movk_i32 s2, 0xff90
	s_nop 0
	v_cndmask_b32_e32 v5, 0, v5, vcc
	v_cmp_nlt_f32_e32 vcc, s97, v2
	s_nop 1
	v_cndmask_b32_e32 v14, v216, v5, vcc
	v_rcp_f32_e32 v2, v3
	s_nop 0
	v_mov_b32_e32 v15, v2
	v_mad_u64_u32 v[2:3], s[2:3], v4, s2, v[0:1]
	ds_write_b128 v2, v[14:17] offset:49152

; #define LAS __attribute__((address_space(3)))
; __device__ __forceinline__ float sigmoidf_(float x) { return 1.0f / (1.0f + __expf(-x)); }
; __device__ __forceinline__ int tidx() { int t = threadIdx.x; asm volatile("" : "+v"(t)); return t; }
; __device__ __forceinline__ const float* pin(int i) { return kargs()->in[i]; }
; template <int MIX> __device__ __forceinline__ MixPar mix_par(int l, int head) {
;     MixPar m; const int cgi = tidx() & 7;
; #pragma unroll
;     for (int i = 0; i < 8; ++i) m.f[i] = 0.f;
;     if constexpr (MIX == 0) {
; #pragma unroll
;         for (int i = 0; i < 8; ++i) { const int c = head * 64 + cgi * 8 + i; m.f[i] = l == 0 ? 0.f : sigmoidf_(pin(10)[256 + c] - pin(10)[c]); }
;     typedef RecCfg<MIX> C;
;     const int tid = tidx(), s = tid >> 3, c4 = (tid & 7) * 4;
;     const Slot sl = slot_of<SAMPLE>(chunk, s, sg);
;     f32x4 o = *(const LAS f32x4*)(L + C::OFF_O + s * 32 + c4);
;     if constexpr (MIX == 3) o = o + *(const LAS f32x4*)(L + C::OFF_XSD + s * 32 + c4);
;     u32x2 w; w.x = pkh(o[0], o[1]); w.y = pkh(o[2], o[3]);
;     if (c4 < nv) *(u32x2*)(raw + (size_t)sl.row * DM + mixer * 256 + head * 64 + vcol0 + c4) = w;
.LBB0_202:
	s_or_b64 exec, exec, s[10:11]
	v_mov_b32_e32 v0, v202
	s_waitcnt lgkmcnt(0)
	s_barrier
	s_mov_b32 s89, s79
	v_ashrrev_i32_e32 v1, 3, v0
	v_lshlrev_b32_e32 v0, 2, v0
	v_and_b32_e32 v6, 28, v0
	v_and_b32_e32 v0, -4, v1
	v_add_u32_e32 v0, s26, v0
	v_and_or_b32 v4, v1, 3, v0
	v_lshlrev_b32_e32 v0, 7, v1
	v_lshlrev_b32_e32 v1, 2, v6
	v_add3_u32 v0, 0, v0, v1
	s_waitcnt vmcnt(0)
	ds_read_b128 v[0:3], v0 offset:50176
	v_ashrrev_i32_e32 v5, 31, v4
	v_lshlrev_b32_e32 v16, 1, v6
	s_mov_b32 s2, 0x3500000
	v_mov_b32_e32 v28, v202
	s_waitcnt lgkmcnt(0)
	v_cvt_pk_f16_f32 v0, v0, v1
	v_cvt_pk_f16_f32 v1, v2, v3
	v_lshlrev_b64 v[2:3], 11, v[4:5]
	v_lshl_add_u64 v[2:3], s[8:9], 0, v[2:3]
	v_lshl_add_u64 v[2:3], v[2:3], 0, s[78:79]
	v_lshl_add_u64 v[2:3], v[2:3], 0, s[88:89]
	v_lshl_add_u64 v[2:3], v[2:3], 0, v[16:17]
	v_add_co_u32_e32 v2, vcc, s2, v2
	s_mov_b64 s[2:3], s[0:1]
	s_nop 0
	v_addc_co_u32_e32 v3, vcc, 0, v3, vcc
	global_store_dwordx2 v[2:3], v[0:1], off offset:512
	s_barrier
	s_load_dwordx2 s[10:11], s[2:3], 0xe0
	s_mov_b64 s[2:3], s[0:1]
	s_load_dwordx2 s[8:9], s[2:3], 0xe0
	v_mov_b32_e32 v0, v202
	v_readlane_b32 s2, v252, 56
	v_lshlrev_b32_e32 v0, 3, v0
	v_readlane_b32 s3, v252, 57
	v_and_or_b32 v0, v0, 56, s83
	v_mov_b32_e32 v1, 0
	v_cndmask_b32_e64 v2, 0, 1, s[2:3]
	v_cmp_ne_u32_e64 s[42:43], 1, v2
	s_andn2_b64 vcc, exec, s[2:3]
	v_lshlrev_b32_e32 v0, 2, v0
	v_mov_b32_e32 v4, 0
	s_cbranch_vccnz .LBB0_204
	s_mov_b64 s[2:3], s[0:1]
	s_load_dwordx2 s[2:3], s[2:3], 0x50
	s_mov_b64 s[12:13], s[0:1]
	s_waitcnt lgkmcnt(0)
	global_load_dword v2, v0, s[2:3] offset:1024
	s_load_dwordx2 s[2:3], s[12:13], 0x50
	s_waitcnt lgkmcnt(0)
	global_load_dword v3, v0, s[2:3]
	s_waitcnt vmcnt(0)
	v_sub_f32_e32 v2, v2, v3
	v_mul_f32_e32 v2, 0xbfb8aa3b, v2
	v_exp_f32_e32 v2, v2
	s_nop 0
	v_add_f32_e32 v2, 1.0, v2
	v_rcp_f32_e32 v3, v2
	s_nop 0
	v_mov_b32_e32 v4, v3
.LBB0_204:
	s_and_b64 vcc, exec, s[42:43]
	s_cbranch_vccnz .LBB0_206
	s_mov_b64 s[2:3], s[0:1]
	s_load_dwordx2 s[2:3], s[2:3], 0x50
	s_mov_b64 s[12:13], s[0:1]
	s_waitcnt lgkmcnt(0)
	global_load_dword v1, v0, s[2:3] offset:1028
	s_load_dwordx2 s[2:3], s[12:13], 0x50
	s_waitcnt lgkmcnt(0)
	global_load_dword v2, v0, s[2:3] offset:4
	s_waitcnt vmcnt(0)
	v_sub_f32_e32 v1, v1, v2
	v_mul_f32_e32 v1, 0xbfb8aa3b, v1
	v_exp_f32_e32 v1, v1
	s_nop 0
	v_add_f32_e32 v1, 1.0, v1
	v_rcp_f32_e32 v2, v1
	s_nop 0
	v_mov_b32_e32 v1, v2

; #define LAS __attribute__((address_space(3)))
; __device__ __forceinline__ float sigmoidf_(float x) { return 1.0f / (1.0f + __expf(-x)); }
; __device__ __forceinline__ void u4f(const u32x4& u, float (&f)[8]) { h2f(u.x, f[0], f[1]); h2f(u.y, f[2], f[3]); h2f(u.z, f[4], f[5]); h2f(u.w, f[6], f[7]); }
; __device__ __forceinline__ void u2f(const u32x2& u, float (&f)[4]) { h2f(u.x, f[0], f[1]); h2f(u.y, f[2], f[3]); }
; __device__ __forceinline__ int tidx() { int t = threadIdx.x; asm volatile("" : "+v"(t)); return t; }
; template <int MIX, bool SAMPLE>
; __device__ __forceinline__ void rec_load(Raw<MIX>& R, const f16_t* proj, int chunk, int sg, int head, int vcol0) {
;     const int tid = tidx(), s = tid >> 3, cgi = tid & 7;
;     const Slot sl = slot_of<SAMPLE>(chunk, s, sg);
;     const f16_t* rowp = proj + (size_t)sl.row * PN;
;     if constexpr (MIX == 0) {
;         R.hq = *(const u32x4*)(rowp + C_HQ + head * 64 + cgi * 8);
;         R.hf = *(const u32x4*)(rowp + C_HF + head * 64 + cgi * 8);
;         R.hi = *(const u32x2*)(rowp + C_HI + head * 64 + vcol0 + cgi * 4);
; template <int MIX, bool SAMPLE>
; __device__ __forceinline__ void rec_process(const Raw<MIX>& R, const MixPar& par, int l, LAS float* L, int chunk, int sg, int head) {
;     ...
;     if constexpr (MIX == 0) {
;         float hq[8], hf[8], hi[4]; u4f(R.hq, hq); u4f(R.hf, hf); u2f(R.hi, hi);
;         float q[8], k[8], f[8];
; #pragma unroll
;         for (int i = 0; i < 8; ++i) { const int c = head * 64 + cgi * 8 + i;
;             const float lb = par.f[i];
;             const float sg_ = sigmoidf_(hf[i]);
;             q[i] = sigmoidf_(hq[i]); f[i] = lb + (1.f - lb) * sg_; k[i] = (1.f - lb) * (1.f - sg_); }
;         *(LAS f32x4*)(L + C::OFF_Q + s * 64 + cgi * 8) = (f32x4){q[0], q[1], q[2], q[3]}; *(LAS f32x4*)(L + C::OFF_Q + s * 64 + cgi * 8 + 4) = (f32x4){q[4], q[5], q[6], q[7]};
;         *(LAS f32x4*)(L + C::OFF_K + s * 64 + cgi * 8) = (f32x4){k[0], k[1], k[2], k[3]}; *(LAS f32x4*)(L + C::OFF_K + s * 64 + cgi * 8 + 4) = (f32x4){k[4], k[5], k[6], k[7]};
;         *(LAS f32x4*)(L + C::OFF_F + s * 64 + cgi * 8) = (f32x4){f[0], f[1], f[2], f[3]}; *(LAS f32x4*)(L + C::OFF_F + s * 64 + cgi * 8 + 4) = (f32x4){f[4], f[5], f[6], f[7]};
;         *(LAS f32x4*)(L + C::OFF_V + s * 32 + cgi * 4) = (f32x4){hi[0], hi[1], hi[2], hi[3]};
.LBB0_212:
	s_mov_b64 s[2:3], s[0:1]
	s_load_dwordx2 s[2:3], s[2:3], 0x50
	s_mov_b64 s[12:13], s[0:1]
	s_waitcnt lgkmcnt(0)
	global_load_dword v2, v0, s[2:3] offset:1052
	s_load_dwordx2 s[2:3], s[12:13], 0x50
	s_waitcnt lgkmcnt(0)
	global_load_dword v0, v0, s[2:3] offset:28
	s_waitcnt vmcnt(0)
	v_sub_f32_e32 v0, v2, v0
	v_mul_f32_e32 v0, 0xbfb8aa3b, v0
	v_exp_f32_e32 v0, v0
	s_nop 0
	v_add_f32_e32 v0, 1.0, v0
	v_rcp_f32_e32 v2, v0
	s_nop 0
	v_mov_b32_e32 v15, v2
.LBB0_213:
	v_mov_b32_e32 v0, v202
	s_waitcnt lgkmcnt(0)
	v_mov_b64_e32 v[6:7], s[10:11]
	v_lshrrev_b32_e32 v2, 3, v0
	v_and_b32_e32 v5, 7, v0
	v_ashrrev_i32_e32 v0, 3, v0
	v_and_b32_e32 v0, -4, v0
	v_add_u32_e32 v0, s26, v0
	v_and_or_b32 v0, v2, 3, v0
	v_mad_i64_i32 v[6:7], s[2:3], v0, s18, v[6:7]
	v_lshl_add_u64 v[6:7], v[6:7], 0, s[78:79]
	s_mov_b64 s[2:3], 0x5600000
	v_lshl_add_u64 v[6:7], v[6:7], 0, s[2:3]
	v_lshlrev_b32_e32 v10, 4, v5
	v_mov_b32_e32 v11, v17
	v_lshl_add_u64 v[10:11], v[6:7], 0, v[10:11]
	global_load_dwordx4 v[24:27], v[10:11], off
	global_load_dwordx4 v[34:37], v[10:11], off offset:512
	s_mov_b32 s89, s79
	v_lshlrev_b32_e32 v16, 3, v5
	v_lshl_add_u64 v[6:7], v[6:7], 0, s[88:89]
	v_lshl_add_u64 v[6:7], v[6:7], 0, v[16:17]
	global_load_dwordx2 v[20:21], v[6:7], off offset:1024
	v_mov_b32_e32 v16, v202
	v_ashrrev_i32_e32 v30, 4, v28
	v_and_b32_e32 v29, -4, v30
	v_cmp_gt_i32_e64 s[42:43], 32, v29
	s_mov_b64 s[12:13], s[0:1]
	s_waitcnt vmcnt(2)
	v_cvt_f32_f16_e32 v0, v24
	s_waitcnt vmcnt(1)
	v_cvt_f32_f16_e32 v5, v34
	v_cvt_f32_f16_sdwa v7, v34 dst_sel:DWORD dst_unused:UNUSED_PAD src0_sel:WORD_1
	v_cvt_f32_f16_e32 v34, v36
	v_mul_f32_e32 v0, 0xbfb8aa3b, v0
	v_cvt_f32_f16_sdwa v23, v36 dst_sel:DWORD dst_unused:UNUSED_PAD src0_sel:WORD_1
	v_mul_f32_e32 v5, 0xbfb8aa3b, v5
	v_exp_f32_e32 v36, v0
	v_mul_f32_e32 v0, 0xbfb8aa3b, v7
	v_cvt_f32_f16_sdwa v2, v24 dst_sel:DWORD dst_unused:UNUSED_PAD src0_sel:WORD_1
	v_exp_f32_e32 v6, v5
	v_exp_f32_e32 v7, v0
	v_cvt_f32_f16_e32 v32, v37
	v_mul_f32_e32 v0, 0xbfb8aa3b, v2
	v_cvt_f32_f16_sdwa v31, v37 dst_sel:DWORD dst_unused:UNUSED_PAD src0_sel:WORD_1
	v_pk_add_f32 v[6:7], v[6:7], 1.0 op_sel_hi:[1,0]
	v_exp_f32_e32 v37, v0
	v_cvt_f32_f16_e32 v39, v35
	v_cvt_f32_f16_e32 v9, v25
	v_cvt_f32_f16_sdwa v35, v35 dst_sel:DWORD dst_unused:UNUSED_PAD src0_sel:WORD_1
	v_rcp_f32_e32 v0, v7
	s_nop 0
	v_mov_b32_e32 v7, v0
	v_cvt_f32_f16_sdwa v38, v25 dst_sel:DWORD dst_unused:UNUSED_PAD src0_sel:WORD_1
	v_cvt_f32_f16_e32 v33, v26
	v_cvt_f32_f16_sdwa v12, v26 dst_sel:DWORD dst_unused:UNUSED_PAD src0_sel:WORD_1
	v_rcp_f32_e32 v0, v6
	s_nop 0
	v_mov_b32_e32 v6, v0
	v_mov_b32_e32 v5, v7
	v_mov_b32_e32 v0, v6
	v_pk_add_f32 v[10:11], v[4:5], 1.0 op_sel_hi:[1,0] neg_lo:[1,0] neg_hi:[1,0]
	v_pk_add_f32 v[24:25], v[0:1], 1.0 op_sel_hi:[1,0] neg_lo:[1,0] neg_hi:[1,0]
	v_cvt_f32_f16_e32 v19, v27
	v_cvt_f32_f16_sdwa v14, v27 dst_sel:DWORD dst_unused:UNUSED_PAD src0_sel:WORD_1
	v_mov_b32_e32 v26, v10
	v_mov_b32_e32 v27, v25
	v_mov_b32_e32 v5, v1
	v_mul_f32_e32 v2, 0xbfb8aa3b, v39
	v_pk_fma_f32 v[0:1], v[26:27], v[6:7], v[4:5]
	v_exp_f32_e32 v26, v2
	v_mul_f32_e32 v2, 0xbfb8aa3b, v9
	v_exp_f32_e32 v6, v2
	v_mul_f32_e32 v2, 0xbfb8aa3b, v35
	v_exp_f32_e32 v27, v2
	v_mul_f32_e32 v2, 0xbfb8aa3b, v38
	v_exp_f32_e32 v7, v2
	v_pk_add_f32 v[4:5], v[36:37], 1.0 op_sel_hi:[1,0]
	v_pk_add_f32 v[26:27], v[26:27], 1.0 op_sel_hi:[1,0]
	v_mul_f32_e32 v23, 0xbfb8aa3b, v23
	v_pk_add_f32 v[6:7], v[6:7], 1.0 op_sel_hi:[1,0]
	v_mul_f32_e32 v12, 0xbfb8aa3b, v12
	v_mul_f32_e32 v19, 0xbfb8aa3b, v19
	v_mul_f32_e32 v14, 0xbfb8aa3b, v14
	v_rcp_f32_e32 v2, v7
	s_nop 0
	v_mov_b32_e32 v7, v2
	s_nop 0
	v_rcp_f32_e32 v2, v6
	s_nop 0
	v_mov_b32_e32 v6, v2
	s_nop 0
	v_rcp_f32_e32 v2, v5
	s_nop 0
	v_mov_b32_e32 v5, v2
	s_nop 0
	v_rcp_f32_e32 v2, v4
	s_nop 0
	v_mov_b32_e32 v4, v2
	s_nop 0
	v_rcp_f32_e32 v2, v27
	s_nop 0
	v_mov_b32_e32 v27, v2
	s_nop 0
	v_rcp_f32_e32 v2, v26
	s_nop 0
	v_mov_b32_e32 v26, v2
	v_mov_b32_e32 v9, v27
	v_mov_b32_e32 v2, v26
	v_pk_add_f32 v[36:37], v[8:9], 1.0 op_sel_hi:[1,0] neg_lo:[1,0] neg_hi:[1,0]
	v_pk_add_f32 v[38:39], v[2:3], 1.0 op_sel_hi:[1,0] neg_lo:[1,0] neg_hi:[1,0]
	v_mov_b32_e32 v40, v36
	v_mov_b32_e32 v41, v39
	v_mov_b32_e32 v9, v3
	v_pk_fma_f32 v[2:3], v[40:41], v[26:27], v[8:9]
	v_pk_mul_f32 v[8:9], v[24:25], v[10:11]
	v_mul_f32_e32 v24, 0xbfb8aa3b, v34
	v_mul_f32_e32 v25, 0xbfb8aa3b, v33
	v_exp_f32_e32 v24, v24
	v_exp_f32_e32 v34, v25
	v_exp_f32_e32 v25, v23
	v_exp_f32_e32 v35, v12
	v_pk_mul_f32 v[10:11], v[38:39], v[36:37]
	v_pk_add_f32 v[24:25], v[24:25], 1.0 op_sel_hi:[1,0]
	s_nop 0
	s_nop 0
	v_rcp_f32_e32 v12, v25
	s_nop 0
	v_mov_b32_e32 v37, v12
	v_exp_f32_e32 v33, v14
	v_rcp_f32_e32 v12, v24
	s_nop 0
	v_mov_b32_e32 v36, v12
	v_mov_b32_e32 v23, v37
	v_mov_b32_e32 v12, v36
	v_pk_add_f32 v[24:25], v[22:23], 1.0 op_sel_hi:[1,0] neg_lo:[1,0] neg_hi:[1,0]
	v_pk_add_f32 v[26:27], v[12:13], 1.0 op_sel_hi:[1,0] neg_lo:[1,0] neg_hi:[1,0]
	v_mov_b32_e32 v38, v24
	v_mov_b32_e32 v39, v27
	v_mov_b32_e32 v23, v13
	v_pk_fma_f32 v[12:13], v[38:39], v[36:37], v[22:23]
	v_mul_f32_e32 v22, 0xbfb8aa3b, v32
	v_exp_f32_e32 v32, v19
	v_mul_f32_e32 v19, 0xbfb8aa3b, v31
	v_exp_f32_e32 v23, v19
	v_pk_add_f32 v[36:37], v[34:35], 1.0 op_sel_hi:[1,0]
	v_pk_add_f32 v[32:33], v[32:33], 1.0 op_sel_hi:[1,0]
	v_exp_f32_e32 v22, v22
	s_nop 0
	v_pk_add_f32 v[22:23], v[22:23], 1.0 op_sel_hi:[1,0]
	v_rcp_f32_e32 v14, v33
	s_nop 0
	v_mov_b32_e32 v35, v14
	s_nop 0
	v_rcp_f32_e32 v14, v32
	s_nop 0
	v_mov_b32_e32 v34, v14
	s_nop 0
	v_rcp_f32_e32 v14, v37
	s_nop 0
	v_mov_b32_e32 v33, v14
	s_nop 0
	v_rcp_f32_e32 v14, v36
	s_nop 0
	v_mov_b32_e32 v32, v14
	s_nop 0
	v_rcp_f32_e32 v14, v23
	s_nop 0
	v_mov_b32_e32 v23, v14
	s_nop 0
	v_rcp_f32_e32 v14, v22
	s_nop 0
	v_mov_b32_e32 v22, v14
	v_mov_b32_e32 v19, v23
	v_mov_b32_e32 v14, v22
	v_pk_add_f32 v[36:37], v[18:19], 1.0 op_sel_hi:[1,0] neg_lo:[1,0] neg_hi:[1,0]
	v_pk_add_f32 v[38:39], v[14:15], 1.0 op_sel_hi:[1,0] neg_lo:[1,0] neg_hi:[1,0]
	v_mov_b32_e32 v40, v36
	v_mov_b32_e32 v41, v39
	v_mov_b32_e32 v19, v15
	v_pk_fma_f32 v[14:15], v[40:41], v[22:23], v[18:19]
	v_ashrrev_i32_e32 v18, 3, v16
	v_and_b32_e32 v16, 7, v16
	v_lshl_add_u32 v19, v18, 8, 0
	v_pk_mul_f32 v[22:23], v[26:27], v[24:25]
	v_pk_mul_f32 v[24:25], v[38:39], v[36:37]
	s_waitcnt vmcnt(0)
	v_cvt_f32_f16_e32 v38, v21
	v_cvt_f32_f16_sdwa v39, v21 dst_sel:DWORD dst_unused:UNUSED_PAD src0_sel:WORD_1
	v_cvt_f32_f16_e32 v36, v20
	v_cvt_f32_f16_sdwa v37, v20 dst_sel:DWORD dst_unused:UNUSED_PAD src0_sel:WORD_1
	v_lshl_add_u32 v20, v16, 5, v19
	ds_write_b128 v20, v[4:7]
	ds_write_b128 v20, v[32:35] offset:16
	ds_write_b128 v20, v[8:11] offset:16384
	ds_write_b128 v20, v[22:25] offset:16400
	ds_write_b128 v20, v[0:3] offset:32768
	ds_write_b128 v20, v[12:15] offset:32784
	v_lshlrev_b32_e32 v0, 7, v18
	v_sub_u32_e32 v0, v19, v0
	v_lshl_add_u32 v0, v16, 4, v0
	ds_write_b128 v0, v[36:39] offset:49152
	s_waitcnt lgkmcnt(0)
	s_barrier
; __device__ __forceinline__ float* pout() { return kargs()->out; }
;     ...
;     const float* sbase = p.in[sidx] + ((size_t)(l * NSB + sg * 16) * 4 + head) * K * 64;
;     float* obase = pout() + o_s + ((size_t)(l * NSB + sg * 16) * 4 + head) * K * 64;
;     float Sn[KPL], Sm[KPL];
; #pragma unroll
;     for (int i = 0; i < KPL; ++i) { Sn[i] = 0.f; Sm[i] = 0.f; if (act) { Sn[i] = sbase[(kg * KPL + i) * 64 + vcol]; Sm[i] = sbase[(size_t)4 * K * 64 + (kg * KPL + i) * 64 + vcol]; } }
; #pragma unroll 1
;     for (int g = 0; g < (act ? 4 : 0); ++g) { float oacc = 0.f;
; #pragma unroll
;         for (int qq = 0; qq < 4; ++qq) { const int q = g * 4 + qq;
; #pragma unroll
;             for (int i = 0; i < KPL; ++i) { S[i] = Sn[i]; Sn[i] = Sm[i]; }
;             if (q + 2 < 16) {
; #pragma unroll
;                 for (int i = 0; i < KPL; ++i) Sm[i] = sbase[(size_t)(q + 2) * 4 * K * 64 + (kg * KPL + i) * 64 + vcol]; }
; #pragma unroll
;             for (int t = 0; t < 4; ++t) { const float o = rec_step<MIX>(S, L, q * 4 + t, kg, vl); oacc = (kg == qq * 4 + t) ? o : oacc; }
	s_and_saveexec_b64 s[10:11], s[42:43]
	s_mov_b32 s17, 0x30000
	s_cbranch_execz .LBB0_220
	s_load_dwordx4 s[20:23], s[0:1], 0x10
	v_bfe_u32 v5, v28, 4, 2
	s_lshl_b64 s[2:3], s[6:7], 2
	v_and_b32_e32 v4, 15, v28
	v_or_b32_e32 v0, v29, v5
	s_waitcnt lgkmcnt(0)
	s_add_u32 s2, s20, s2
	v_add_u32_e32 v0, s82, v0
	s_addc_u32 s3, s21, s3
	v_lshlrev_b32_e32 v16, 10, v4
	v_lshl_add_u64 v[2:3], s[2:3], 0, v[16:17]
	v_ashrrev_i32_e32 v1, 31, v0
	v_lshl_add_u64 v[0:1], v[0:1], 2, v[2:3]
	s_mov_b32 s2, 0x10000
	v_add_co_u32_e32 v2, vcc, s2, v0
	s_lshl_b64 s[4:5], s[4:5], 16
	s_nop 0
	v_addc_co_u32_e32 v3, vcc, 0, v1, vcc
	global_load_dword v12, v[0:1], off
	global_load_dword v8, v[2:3], off
	global_load_dword v13, v[0:1], off offset:256
	global_load_dword v9, v[2:3], off offset:256
	global_load_dword v14, v[0:1], off offset:512
	global_load_dword v10, v[2:3], off offset:512
	global_load_dword v11, v[2:3], off offset:768
	global_load_dword v15, v[0:1], off offset:768
	s_load_dwordx2 s[6:7], s[12:13], 0xd8
	v_lshlrev_b32_e32 v2, 2, v30
	v_lshlrev_b32_e32 v3, 2, v5
	v_and_or_b32 v2, v2, -16, v3
	v_lshlrev_b32_e32 v0, 4, v4
	v_mul_u32_u24_e32 v1, 0x70, v4
	v_add_u32_e32 v27, 0, v2
	s_mov_b32 s3, 0x10400
	s_or_b64 s[4:5], s[4:5], s[94:95]
	v_add3_u32 v2, v67, v29, v5
	v_add_u32_e32 v26, 0, v0
	v_add3_u32 v28, v1, v0, s3
	v_lshl_add_u64 v[0:1], s[4:5], 0, v[16:17]
	v_ashrrev_i32_e32 v3, 31, v2
	v_lshl_add_u64 v[2:3], v[2:3], 2, v[0:1]
	v_cmp_eq_u32_e64 s[42:43], 0, v4
	v_cmp_eq_u32_e64 s[44:45], 1, v4
	v_cmp_eq_u32_e64 s[46:47], 2, v4
	s_mov_b32 s2, 3
	v_cmp_eq_u32_e64 s[48:49], 3, v4
	v_cmp_eq_u32_e64 s[50:51], 4, v4
	v_cmp_eq_u32_e64 s[52:53], 5, v4
	v_cmp_eq_u32_e64 s[54:55], 6, v4
	v_cmp_eq_u32_e64 s[56:57], 7, v4
	v_cmp_eq_u32_e64 s[58:59], 8, v4
	v_cmp_eq_u32_e64 s[60:61], 9, v4
	v_cmp_eq_u32_e64 s[62:63], 10, v4
	v_cmp_eq_u32_e64 s[64:65], 11, v4
	v_cmp_eq_u32_e64 s[66:67], 12, v4
	v_cmp_eq_u32_e64 s[68:69], 13, v4
	v_cmp_eq_u32_e64 s[70:71], 14, v4
	v_cmp_eq_u32_e64 s[72:73], 15, v4
	s_waitcnt lgkmcnt(0)
	v_lshl_add_u64 v[0:1], s[6:7], 0, v[2:3]
	v_lshl_add_u64 v[2:3], s[20:21], 0, v[2:3]
	s_mov_b32 s21, 0x7f800000
	s_movk_i32 s20, 0x1000
	s_mov_b64 s[4:5], 0
	s_branch .LBB0_216

; __device__ __forceinline__ float sigmoidf_(float x) { return 1.0f / (1.0f + __expf(-x)); }
; __device__ __forceinline__ const float* pin(int i) { return kargs()->in[i]; }
; template <int MIX> __device__ __forceinline__ MixPar mix_par(int l, int head) {
;     ...
;         for (int i = 0; i < 8; ++i) { const int c = head * 64 + cgi * 8 + i; m.f[i] = l == 0 ? 0.f : sigmoidf_(pin(10)[256 + c] - pin(10)[c]); }
.LBB0_324:
	s_mov_b64 s[2:3], s[0:1]
	s_load_dwordx2 s[2:3], s[2:3], 0x50
	s_mov_b64 s[12:13], s[0:1]
	s_waitcnt lgkmcnt(0)
	global_load_dword v2, v0, s[2:3] offset:1032
	s_load_dwordx2 s[2:3], s[12:13], 0x50
	s_waitcnt lgkmcnt(0)
	global_load_dword v5, v0, s[2:3] offset:8
	s_waitcnt vmcnt(0)
	v_sub_f32_e32 v2, v2, v5
	v_mul_f32_e32 v2, 0xbfb8aa3b, v2
	v_exp_f32_e32 v2, v2
	s_nop 0
	v_add_f32_e32 v2, 1.0, v2
	v_rcp_f32_e32 v5, v2
	s_nop 0
	v_mov_b32_e32 v8, v5
	s_and_b64 vcc, exec, s[42:43]
	s_cbranch_vccnz .LBB0_208
.LBB0_325:
	s_mov_b64 s[2:3], s[0:1]
	s_load_dwordx2 s[2:3], s[2:3], 0x50
	s_mov_b64 s[12:13], s[0:1]
	s_waitcnt lgkmcnt(0)
	global_load_dword v2, v0, s[2:3] offset:1036
	s_load_dwordx2 s[2:3], s[12:13], 0x50
	s_waitcnt lgkmcnt(0)
	global_load_dword v3, v0, s[2:3] offset:12
	s_waitcnt vmcnt(0)
	v_sub_f32_e32 v2, v2, v3
	v_mul_f32_e32 v2, 0xbfb8aa3b, v2
	v_exp_f32_e32 v2, v2
	s_nop 0
	v_add_f32_e32 v2, 1.0, v2
	v_rcp_f32_e32 v3, v2
	v_mov_b32_e32 v13, 0
	s_and_b64 vcc, exec, s[42:43]
	v_mov_b32_e32 v22, 0
	s_cbranch_vccnz .LBB0_209
.LBB0_326:
	s_mov_b64 s[2:3], s[0:1]
	s_load_dwordx2 s[2:3], s[2:3], 0x50
	s_mov_b64 s[12:13], s[0:1]
	s_waitcnt lgkmcnt(0)
	global_load_dword v2, v0, s[2:3] offset:1040
	s_load_dwordx2 s[2:3], s[12:13], 0x50
	s_waitcnt lgkmcnt(0)
	global_load_dword v5, v0, s[2:3] offset:16
	s_waitcnt vmcnt(0)
	v_sub_f32_e32 v2, v2, v5
	v_mul_f32_e32 v2, 0xbfb8aa3b, v2
	v_exp_f32_e32 v2, v2
	s_nop 0
	v_add_f32_e32 v2, 1.0, v2
	v_rcp_f32_e32 v5, v2
	s_nop 0
	v_mov_b32_e32 v22, v5
	s_and_b64 vcc, exec, s[42:43]
	s_cbranch_vccnz .LBB0_210
.LBB0_327:
	s_mov_b64 s[2:3], s[0:1]
	s_load_dwordx2 s[2:3], s[2:3], 0x50
	s_mov_b64 s[12:13], s[0:1]
	s_waitcnt lgkmcnt(0)
	global_load_dword v2, v0, s[2:3] offset:1044
	s_load_dwordx2 s[2:3], s[12:13], 0x50
	s_waitcnt lgkmcnt(0)
	global_load_dword v5, v0, s[2:3] offset:20
	s_waitcnt vmcnt(0)
	v_sub_f32_e32 v2, v2, v5
	v_mul_f32_e32 v2, 0xbfb8aa3b, v2
	v_exp_f32_e32 v2, v2
	s_nop 0
	v_add_f32_e32 v2, 1.0, v2
	v_rcp_f32_e32 v5, v2
	s_nop 0
	v_mov_b32_e32 v13, v5
	v_mov_b32_e32 v15, 0
	s_and_b64 vcc, exec, s[42:43]
	v_mov_b32_e32 v18, 0
	s_cbranch_vccnz .LBB0_211
.LBB0_328:
	s_mov_b64 s[2:3], s[0:1]
	s_load_dwordx2 s[2:3], s[2:3], 0x50
	s_mov_b64 s[12:13], s[0:1]
	s_waitcnt lgkmcnt(0)
	global_load_dword v2, v0, s[2:3] offset:1048
	s_load_dwordx2 s[2:3], s[12:13], 0x50
	s_waitcnt lgkmcnt(0)
	global_load_dword v5, v0, s[2:3] offset:24
	s_waitcnt vmcnt(0)
	v_sub_f32_e32 v2, v2, v5
	v_mul_f32_e32 v2, 0xbfb8aa3b, v2
	v_exp_f32_e32 v2, v2
	s_nop 0
	v_add_f32_e32 v2, 1.0, v2
	v_rcp_f32_e32 v5, v2
	s_nop 0
	v_mov_b32_e32 v18, v5
	s_and_b64 vcc, exec, s[42:43]
	s_cbranch_vccz .LBB0_212
	s_branch .LBB0_213

; __device__ __forceinline__ float sigmoidf_(float x) { return 1.0f / (1.0f + __expf(-x)); }
; __device__ __forceinline__ const float* pin(int i) { return kargs()->in[i]; }
; template <int MIX> __device__ __forceinline__ MixPar mix_par(int l, int head) {
;     ...
;         for (int i = 0; i < 8; ++i) { const int c = head * 64 + cgi * 8 + i; m.f[i] = l == 0 ? 0.f : sigmoidf_(pin(10)[256 + c] - pin(10)[c]); }
.LBB0_344:
	s_mov_b64 s[8:9], s[0:1]
	s_load_dwordx2 s[8:9], s[8:9], 0x50
	s_mov_b64 s[10:11], s[0:1]
	s_waitcnt lgkmcnt(0)
	global_load_dword v1, v0, s[8:9] offset:1052
	s_load_dwordx2 s[8:9], s[10:11], 0x50
	s_waitcnt lgkmcnt(0)
	global_load_dword v0, v0, s[8:9] offset:28
	s_waitcnt vmcnt(0)
	v_sub_f32_e32 v0, v1, v0
	v_mul_f32_e32 v0, 0xbfb8aa3b, v0
	v_exp_f32_e32 v0, v0
	s_nop 0
	v_add_f32_e32 v0, 1.0, v0
	v_rcp_f32_e32 v1, v0
	s_nop 0
	v_mov_b32_e32 v25, v1

; #define LAS __attribute__((address_space(3)))
; __device__ __forceinline__ float sigmoidf_(float x) { return 1.0f / (1.0f + __expf(-x)); }
; __device__ __forceinline__ void u4f(const u32x4& u, float (&f)[8]) { h2f(u.x, f[0], f[1]); h2f(u.y, f[2], f[3]); h2f(u.z, f[4], f[5]); h2f(u.w, f[6], f[7]); }
; __device__ __forceinline__ void u2f(const u32x2& u, float (&f)[4]) { h2f(u.x, f[0], f[1]); h2f(u.y, f[2], f[3]); }
; template <int MIX, bool SAMPLE>
; __device__ __forceinline__ void rec_process(const Raw<MIX>& R, const MixPar& par, int l, LAS float* L, int chunk, int sg, int head) {
;     ...
;     if constexpr (MIX == 0) {
;         float hq[8], hf[8], hi[4]; u4f(R.hq, hq); u4f(R.hf, hf); u2f(R.hi, hi);
;         float q[8], k[8], f[8];
; #pragma unroll
;         for (int i = 0; i < 8; ++i) { const int c = head * 64 + cgi * 8 + i;
;             const float lb = par.f[i];
;             const float sg_ = sigmoidf_(hf[i]);
;             q[i] = sigmoidf_(hq[i]); f[i] = lb + (1.f - lb) * sg_; k[i] = (1.f - lb) * (1.f - sg_); }
;         *(LAS f32x4*)(L + C::OFF_Q + s * 64 + cgi * 8) = (f32x4){q[0], q[1], q[2], q[3]}; *(LAS f32x4*)(L + C::OFF_Q + s * 64 + cgi * 8 + 4) = (f32x4){q[4], q[5], q[6], q[7]};
;         *(LAS f32x4*)(L + C::OFF_K + s * 64 + cgi * 8) = (f32x4){k[0], k[1], k[2], k[3]}; *(LAS f32x4*)(L + C::OFF_K + s * 64 + cgi * 8 + 4) = (f32x4){k[4], k[5], k[6], k[7]};
;         *(LAS f32x4*)(L + C::OFF_F + s * 64 + cgi * 8) = (f32x4){f[0], f[1], f[2], f[3]}; *(LAS f32x4*)(L + C::OFF_F + s * 64 + cgi * 8 + 4) = (f32x4){f[4], f[5], f[6], f[7]};
;         *(LAS f32x4*)(L + C::OFF_V + s * 32 + cgi * 4) = (f32x4){hi[0], hi[1], hi[2], hi[3]};
;     ...
;     rec_load<MIX, false>(R, proj, 0, sg, head, vcol0);
; #pragma unroll 1
;     for (int c = 0; c < SEQ / 64; ++c) {
;         rec_process<MIX, false>(R, par, l, L, c, sg, head);
;         __syncthreads();
;         if (c + 1 < SEQ / 64) rec_load<MIX, false>(R, proj, c + 1, sg, head, vcol0);
;         else if (DO_SAMPLE) rec_load<MIX, true>(R, proj, 0, sg, head, vcol0);
.LBB0_346:
	s_waitcnt vmcnt(2)
	v_cvt_f32_f16_e32 v9, v0
	s_waitcnt vmcnt(1)
	v_cvt_f32_f16_e32 v8, v4
	v_cvt_f32_f16_sdwa v12, v4 dst_sel:DWORD dst_unused:UNUSED_PAD src0_sel:WORD_1
	v_cvt_f32_f16_e32 v15, v5
	v_mul_f32_e32 v9, 0xbfb8aa3b, v9
	v_mul_f32_e32 v8, 0xbfb8aa3b, v8
	v_exp_f32_e32 v10, v9
	v_mul_f32_e32 v9, 0xbfb8aa3b, v12
	v_exp_f32_e32 v8, v8
	v_exp_f32_e32 v9, v9
	v_cvt_f32_f16_sdwa v42, v5 dst_sel:DWORD dst_unused:UNUSED_PAD src0_sel:WORD_1
	v_cvt_f32_f16_e32 v13, v1
	v_cvt_f32_f16_sdwa v14, v1 dst_sel:DWORD dst_unused:UNUSED_PAD src0_sel:WORD_1
	v_pk_add_f32 v[8:9], v[8:9], 1.0 op_sel_hi:[1,0]
	v_cvt_f32_f16_sdwa v11, v0 dst_sel:DWORD dst_unused:UNUSED_PAD src0_sel:WORD_1
	v_mul_f32_e32 v11, 0xbfb8aa3b, v11
	v_exp_f32_e32 v11, v11
	v_cvt_f32_f16_e32 v45, v2
	v_rcp_f32_e32 v12, v9
	s_nop 0
	v_mov_b32_e32 v41, v12
	v_cvt_f32_f16_e32 v44, v6
	v_cvt_f32_f16_sdwa v58, v6 dst_sel:DWORD dst_unused:UNUSED_PAD src0_sel:WORD_1
	v_mul_f32_e32 v45, 0xbfb8aa3b, v45
	v_rcp_f32_e32 v9, v8
	s_nop 0
	v_mov_b32_e32 v40, v9
	v_mul_f32_e32 v8, 0xbfb8aa3b, v15
	v_mul_f32_e32 v9, 0xbfb8aa3b, v42
	v_exp_f32_e32 v12, v8
	v_mul_f32_e32 v8, 0xbfb8aa3b, v13
	v_exp_f32_e32 v13, v9
	v_mul_f32_e32 v9, 0xbfb8aa3b, v14
	v_exp_f32_e32 v8, v8
	v_exp_f32_e32 v9, v9
	v_pk_add_f32 v[14:15], v[10:11], 1.0 op_sel_hi:[1,0]
	v_pk_add_f32 v[12:13], v[12:13], 1.0 op_sel_hi:[1,0]
	v_mul_f32_e32 v44, 0xbfb8aa3b, v44
	v_pk_add_f32 v[8:9], v[8:9], 1.0 op_sel_hi:[1,0]
	v_exp_f32_e32 v44, v44
	v_cvt_f32_f16_e32 v53, v3
	v_cvt_f32_f16_sdwa v52, v3 dst_sel:DWORD dst_unused:UNUSED_PAD src0_sel:WORD_1
	v_cvt_f32_f16_sdwa v57, v2 dst_sel:DWORD dst_unused:UNUSED_PAD src0_sel:WORD_1
	v_rcp_f32_e32 v10, v9
	s_nop 0
	v_mov_b32_e32 v11, v10
	v_cvt_f32_f16_e32 v55, v7
	v_mul_f32_e32 v53, 0xbfb8aa3b, v53
	v_mul_f32_e32 v52, 0xbfb8aa3b, v52
	v_rcp_f32_e32 v9, v8
	s_nop 0
	v_mov_b32_e32 v10, v9
	v_cvt_f32_f16_sdwa v54, v7 dst_sel:DWORD dst_unused:UNUSED_PAD src0_sel:WORD_1
	v_mul_f32_e32 v57, 0xbfb8aa3b, v57
	v_exp_f32_e32 v57, v57
	v_rcp_f32_e32 v8, v15
	s_nop 0
	v_mov_b32_e32 v9, v8
	v_mul_f32_e32 v55, 0xbfb8aa3b, v55
	v_mov_b32_e32 v16, v202
	v_rcp_f32_e32 v8, v14
	v_ashrrev_i32_e32 v66, 3, v16
	v_and_b32_e32 v16, 7, v16
	v_lshl_add_u32 v67, v66, 8, 0
	v_rcp_f32_e32 v14, v13
	s_nop 0
	v_mov_b32_e32 v43, v14
	v_lshl_add_u32 v68, v16, 5, v67
	s_waitcnt vmcnt(0)
	v_cvt_f32_f16_sdwa v63, v33 dst_sel:DWORD dst_unused:UNUSED_PAD src0_sel:WORD_1
	v_exp_f32_e32 v56, v45
	v_mul_f32_e32 v45, 0xbfb8aa3b, v58
	v_exp_f32_e32 v45, v45
	v_rcp_f32_e32 v13, v12
	s_nop 0
	v_mov_b32_e32 v42, v13
	v_pk_add_f32 v[44:45], v[44:45], 1.0 op_sel_hi:[1,0]
	v_sub_f32_e32 v13, 1.0, v41
	v_sub_f32_e32 v12, 1.0, v40
	v_sub_f32_e32 v15, 1.0, v43
	v_sub_f32_e32 v14, 1.0, v42
	v_rcp_f32_e32 v58, v45
	s_nop 0
	v_mov_b32_e32 v45, v58
	v_pk_mul_f32 v[14:15], v[28:29], v[14:15]
	v_pk_mul_f32 v[12:13], v[26:27], v[12:13]
	v_exp_f32_e32 v60, v53
	v_exp_f32_e32 v61, v52
	v_rcp_f32_e32 v58, v44
	s_nop 0
	v_mov_b32_e32 v44, v58
	v_exp_f32_e32 v58, v55
	v_mul_f32_e32 v53, 0xbfb8aa3b, v54
	v_pk_add_f32 v[54:55], v[60:61], 1.0 op_sel_hi:[1,0]
	v_exp_f32_e32 v59, v53
	v_pk_add_f32 v[52:53], v[56:57], 1.0 op_sel_hi:[1,0]
	s_nop 0
	v_rcp_f32_e32 v56, v55
	s_nop 0
	v_mov_b32_e32 v55, v56
	s_nop 0
	v_rcp_f32_e32 v56, v54
	s_nop 0
	v_mov_b32_e32 v54, v56
	s_nop 0
	v_rcp_f32_e32 v56, v53
	s_nop 0
	v_mov_b32_e32 v53, v56
	s_nop 0
	v_rcp_f32_e32 v56, v52
	s_nop 0
	v_mov_b32_e32 v52, v56
	v_pk_add_f32 v[56:57], v[58:59], 1.0 op_sel_hi:[1,0]
	s_nop 0
	s_nop 0
	v_rcp_f32_e32 v58, v57
	s_nop 0
	v_mov_b32_e32 v65, v58
	v_cvt_f32_f16_e32 v62, v33
	s_add_i32 s2, s12, 1
	s_cmp_eq_u32 s12, 31
	v_rcp_f32_e32 v57, v56
	s_nop 0
	v_mov_b32_e32 v64, v57
	v_sub_f32_e32 v57, 1.0, v45
	v_sub_f32_e32 v56, 1.0, v44
	v_sub_f32_e32 v59, 1.0, v65
	v_sub_f32_e32 v58, 1.0, v64
	v_pk_mul_f32 v[58:59], v[34:35], v[58:59]
	v_pk_mul_f32 v[56:57], v[30:31], v[56:57]
	ds_write_b128 v68, v[8:11]
	ds_write_b128 v68, v[52:55] offset:16
	ds_write_b128 v68, v[12:15] offset:16384
	ds_write_b128 v68, v[56:59] offset:16400
	v_pk_fma_f32 v[8:9], v[26:27], v[40:41], v[18:19]
	v_pk_fma_f32 v[10:11], v[28:29], v[42:43], v[20:21]
	v_cvt_f32_f16_sdwa v61, v32 dst_sel:DWORD dst_unused:UNUSED_PAD src0_sel:WORD_1
	v_cvt_f32_f16_e32 v60, v32
	ds_write_b128 v68, v[8:11] offset:32768
	v_pk_fma_f32 v[8:9], v[30:31], v[44:45], v[22:23]
	v_pk_fma_f32 v[10:11], v[34:35], v[64:65], v[24:25]
	ds_write_b128 v68, v[8:11] offset:32784
	v_lshlrev_b32_e32 v8, 7, v66
	v_sub_u32_e32 v8, v67, v8
	v_lshl_add_u32 v8, v16, 4, v8
	ds_write_b128 v8, v[60:63] offset:49152
	s_waitcnt lgkmcnt(0)
	s_barrier
	s_cbranch_scc1 .LBB0_348
	v_mov_b32_e32 v0, v202
	s_lshl_b32 s3, s2, 6
	s_add_i32 s3, s3, s11
	v_ashrrev_i32_e32 v1, 3, v0
	v_and_b32_e32 v2, 7, v0
	v_add_u32_e32 v3, s3, v1
	v_mov_b64_e32 v[0:1], s[6:7]
	v_mad_i64_i32 v[8:9], s[8:9], v3, s18, v[0:1]
	v_lshlrev_b32_e32 v0, 4, v2
	v_mov_b32_e32 v1, v17
	v_lshlrev_b32_e32 v16, 3, v2
	v_lshl_add_u64 v[4:5], v[8:9], 0, v[0:1]
	v_lshl_add_u64 v[8:9], v[8:9], 0, s[78:79]
	v_lshl_add_u64 v[8:9], v[8:9], 0, v[16:17]
	global_load_dwordx4 v[0:3], v[4:5], off
	s_nop 0
	global_load_dwordx4 v[4:7], v[4:5], off offset:512
	s_nop 0
	global_load_dwordx2 v[32:33], v[8:9], off offset:1024

; __device__ __forceinline__ float sigmoidf_(float x) { return 1.0f / (1.0f + __expf(-x)); }
; __device__ __forceinline__ const float* pin(int i) { return kargs()->in[i]; }
; template <int MIX> __device__ __forceinline__ MixPar mix_par(int l, int head) {
;     ...
;         for (int i = 0; i < 8; ++i) { const int c = head * 64 + cgi * 8 + i; m.f[i] = l == 0 ? 0.f : sigmoidf_(pin(10)[256 + c] - pin(10)[c]); }
.LBB0_391:
	s_mov_b64 s[8:9], s[0:1]
	s_load_dwordx2 s[8:9], s[8:9], 0x50
	s_mov_b64 s[10:11], s[0:1]
	s_waitcnt lgkmcnt(0)
	global_load_dword v1, v0, s[8:9] offset:1024
	s_load_dwordx2 s[8:9], s[10:11], 0x50
	s_waitcnt lgkmcnt(0)
	global_load_dword v2, v0, s[8:9]
	s_waitcnt vmcnt(0)
	v_sub_f32_e32 v1, v1, v2
	v_mul_f32_e32 v1, 0xbfb8aa3b, v1
	v_exp_f32_e32 v1, v1
	s_nop 0
	v_add_f32_e32 v1, 1.0, v1
	v_rcp_f32_e32 v2, v1
	s_nop 0
	v_mov_b32_e32 v18, v2
	s_and_b64 vcc, exec, s[42:43]
	s_cbranch_vccnz .LBB0_338
.LBB0_392:
	s_mov_b64 s[8:9], s[0:1]
	s_load_dwordx2 s[8:9], s[8:9], 0x50
	s_mov_b64 s[10:11], s[0:1]
	s_waitcnt lgkmcnt(0)
	global_load_dword v1, v0, s[8:9] offset:1028
	s_load_dwordx2 s[8:9], s[10:11], 0x50
	s_waitcnt lgkmcnt(0)
	global_load_dword v2, v0, s[8:9] offset:4
	s_waitcnt vmcnt(0)
	v_sub_f32_e32 v1, v1, v2
	v_mul_f32_e32 v1, 0xbfb8aa3b, v1
	v_exp_f32_e32 v1, v1
	s_nop 0
	v_add_f32_e32 v1, 1.0, v1
	v_rcp_f32_e32 v2, v1
	s_nop 0
	v_mov_b32_e32 v19, v2
	v_mov_b32_e32 v21, 0
	s_and_b64 vcc, exec, s[42:43]
	v_mov_b32_e32 v20, 0
	s_cbranch_vccnz .LBB0_339
.LBB0_393:
	s_mov_b64 s[8:9], s[0:1]
	s_load_dwordx2 s[8:9], s[8:9], 0x50
	s_mov_b64 s[10:11], s[0:1]
	s_waitcnt lgkmcnt(0)
	global_load_dword v1, v0, s[8:9] offset:1032
	s_load_dwordx2 s[8:9], s[10:11], 0x50
	s_waitcnt lgkmcnt(0)
	global_load_dword v2, v0, s[8:9] offset:8
	s_waitcnt vmcnt(0)
	v_sub_f32_e32 v1, v1, v2
	v_mul_f32_e32 v1, 0xbfb8aa3b, v1
	v_exp_f32_e32 v1, v1
	s_nop 0
	v_add_f32_e32 v1, 1.0, v1
	v_rcp_f32_e32 v2, v1
	s_nop 0
	v_mov_b32_e32 v20, v2
	s_and_b64 vcc, exec, s[42:43]
	s_cbranch_vccnz .LBB0_340
.LBB0_394:
	s_mov_b64 s[8:9], s[0:1]
	s_load_dwordx2 s[8:9], s[8:9], 0x50
	s_mov_b64 s[10:11], s[0:1]
	s_waitcnt lgkmcnt(0)
	global_load_dword v1, v0, s[8:9] offset:1036
	s_load_dwordx2 s[8:9], s[10:11], 0x50
	s_waitcnt lgkmcnt(0)
	global_load_dword v2, v0, s[8:9] offset:12
	s_waitcnt vmcnt(0)
	v_sub_f32_e32 v1, v1, v2
	v_mul_f32_e32 v1, 0xbfb8aa3b, v1
	v_exp_f32_e32 v1, v1
	s_nop 0
	v_add_f32_e32 v1, 1.0, v1
	v_rcp_f32_e32 v2, v1
	s_nop 0
	v_mov_b32_e32 v21, v2
	v_mov_b32_e32 v23, 0
	s_and_b64 vcc, exec, s[42:43]
	v_mov_b32_e32 v22, 0
	s_cbranch_vccnz .LBB0_341
.LBB0_395:
	s_mov_b64 s[8:9], s[0:1]
	s_load_dwordx2 s[8:9], s[8:9], 0x50
	s_mov_b64 s[10:11], s[0:1]
	s_waitcnt lgkmcnt(0)
	global_load_dword v1, v0, s[8:9] offset:1040
	s_load_dwordx2 s[8:9], s[10:11], 0x50
	s_waitcnt lgkmcnt(0)
	global_load_dword v2, v0, s[8:9] offset:16
	s_waitcnt vmcnt(0)
	v_sub_f32_e32 v1, v1, v2
	v_mul_f32_e32 v1, 0xbfb8aa3b, v1
	v_exp_f32_e32 v1, v1
	s_nop 0
	v_add_f32_e32 v1, 1.0, v1
	v_rcp_f32_e32 v2, v1
	s_nop 0
	v_mov_b32_e32 v22, v2
	s_and_b64 vcc, exec, s[42:43]
	s_cbranch_vccnz .LBB0_342
.LBB0_396:
	s_mov_b64 s[8:9], s[0:1]
	s_load_dwordx2 s[8:9], s[8:9], 0x50
	s_mov_b64 s[10:11], s[0:1]
	s_waitcnt lgkmcnt(0)
	global_load_dword v1, v0, s[8:9] offset:1044
	s_load_dwordx2 s[8:9], s[10:11], 0x50
	s_waitcnt lgkmcnt(0)
	global_load_dword v2, v0, s[8:9] offset:20
	s_waitcnt vmcnt(0)
	v_sub_f32_e32 v1, v1, v2
	v_mul_f32_e32 v1, 0xbfb8aa3b, v1
	v_exp_f32_e32 v1, v1
	s_nop 0
	v_add_f32_e32 v1, 1.0, v1
	v_rcp_f32_e32 v2, v1
	s_nop 0
	v_mov_b32_e32 v23, v2
	v_mov_b32_e32 v25, 0
	s_and_b64 vcc, exec, s[42:43]
	v_mov_b32_e32 v24, 0
	s_cbranch_vccnz .LBB0_343
.LBB0_397:
	s_mov_b64 s[8:9], s[0:1]
	s_load_dwordx2 s[8:9], s[8:9], 0x50
	s_mov_b64 s[10:11], s[0:1]
	s_waitcnt lgkmcnt(0)
	global_load_dword v1, v0, s[8:9] offset:1048
	s_load_dwordx2 s[8:9], s[10:11], 0x50
	s_waitcnt lgkmcnt(0)
	global_load_dword v2, v0, s[8:9] offset:24
	s_waitcnt vmcnt(0)
	v_sub_f32_e32 v1, v1, v2
	v_mul_f32_e32 v1, 0xbfb8aa3b, v1
	v_exp_f32_e32 v1, v1
	s_nop 0
	v_add_f32_e32 v1, 1.0, v1
	v_rcp_f32_e32 v2, v1
	s_nop 0
	v_mov_b32_e32 v24, v2
	s_and_b64 vcc, exec, s[42:43]
	s_cbranch_vccz .LBB0_344
	s_branch .LBB0_345

; #define LAS __attribute__((address_space(3)))
; __device__ __forceinline__ float sigmoidf_(float x) { return 1.0f / (1.0f + __expf(-x)); }
; __device__ __forceinline__ float softplusf_(float x) { return x > 20.f ? x : log1pf(expf(x)); }
; template <int MIX, bool SAMPLE>
; __device__ __forceinline__ void rec_process(const Raw<MIX>& R, const MixPar& par, int l, LAS float* L, int chunk, int sg, int head) {
;     ...
;         if (cgi == 0) { const float a = expf(-par.f[0] * softplusf_(R.ga + par.f[1]));
;             *(LAS f32x4*)(L + C::OFF_SC + s * 4) = (f32x4){a, sigmoidf_(R.gb), kq, 0.f}; }
.LBB0_417:
	s_or_b64 exec, exec, s[8:9]
	v_mul_f32_e32 v29, v19, v16
	v_mul_f32_e32 v16, 0x3fb8aa3b, v29
	v_fma_f32 v30, v29, s19, -v16
	v_rndne_f32_e32 v31, v16
	v_fmac_f32_e32 v30, 0x32a5705f, v29
	v_sub_f32_e32 v16, v16, v31
	v_add_f32_e32 v16, v16, v30
	v_exp_f32_e32 v30, v16
	v_mul_f32_e32 v16, 0xbfb8aa3b, v24
	v_exp_f32_e32 v32, v16
	v_cvt_i32_f32_e32 v31, v31
	v_add_f32_e32 v16, v14, v15
	v_cmp_ngt_f32_e32 vcc, s96, v29
	v_add_f32_e32 v15, 1.0, v32
	v_ldexp_f32 v14, v30, v31
	v_cndmask_b32_e32 v14, 0, v14, vcc
	v_cmp_nlt_f32_e32 vcc, s97, v29
	v_lshl_add_u32 v28, v28, 4, s3
	s_nop 0
	v_cndmask_b32_e32 v14, v216, v14, vcc
	v_rcp_f32_e32 v29, v15
	s_nop 0
	v_mov_b32_e32 v15, v29
	ds_write_b128 v28, v[14:17] offset:49152

; __device__ __forceinline__ int tidx() { int t = threadIdx.x; asm volatile("" : "+v"(t)); return t; }
; __device__ __forceinline__ int bidx() { int t = blockIdx.x; asm volatile("" : "+s"(t)); return t; }
; __device__ __forceinline__ const float* pin(int i) { return kargs()->in[i]; }
; __device__ __forceinline__ unsigned char* pws() { return kargs()->ws; }
; __device__ __forceinline__ void phase_post(const Params& p, int l) {
;     const int lane = tidx() & 63, gw = bidx() * 8 + (tidx() >> 6), nw = gridDim.x * 8;
;     const f16_t* proj = (const f16_t*)(pws() + WS_PROJ);
;     f16_t* mix = (f16_t*)(pws() + WS_XN);
;     const int c0 = lane * 16, mixer = lane >> 4, cm = c0 & 255;
;     const int gcol = mixer == 0 ? C_HG : mixer == 1 ? C_GZ : mixer == 2 ? C_RG : C_SZ;
;     float wn[16];
; #pragma unroll
;     for (int i = 0; i < 16; ++i) wn[i] = mixer == 0 ? pin(11)[l * 64 + ((cm + i) & 63)] : mixer == 1 ? pin(15)[l * 64 + ((cm + i) & 63)] : mixer == 2 ? 1.0f : pin(21)[l * 256 + cm + i];
.LBB0_472:
	s_cmp_lt_u32 s3, 0x40001
	s_mov_b64 s[8:9], 0
	s_cselect_b64 s[12:13], -1, 0
	s_and_b64 vcc, exec, s[12:13]
	s_cbranch_vccz .LBB0_465
	s_branch .LBB0_471
.LBB0_633:
	v_readlane_b32 s20, v252, 8
	v_readlane_b32 s62, v252, 10
	v_readlane_b32 s64, v252, 12
	v_readlane_b32 s66, v252, 14
	v_readlane_b32 s68, v252, 16
	v_readlane_b32 s72, v252, 18
	v_readlane_b32 s80, v252, 20
	v_readlane_b32 s84, v252, 22
	v_readlane_b32 s34, v252, 31
	v_readlane_b32 s58, v252, 56
	v_readlane_b32 s17, v252, 7
	v_readlane_b32 s21, v252, 9
	v_readlane_b32 s63, v252, 11
	v_readlane_b32 s65, v252, 13
	v_readlane_b32 s67, v252, 15
	v_readlane_b32 s69, v252, 17
	v_readlane_b32 s73, v252, 19
	v_readlane_b32 s81, v252, 21
	v_readlane_b32 s85, v252, 23
	v_readlane_b32 s77, v252, 30
	v_readlane_b32 s35, v252, 32
	v_readlane_b32 s71, v252, 58
	v_readlane_b32 s59, v252, 57
	s_cbranch_execz .LBB0_429
	s_branch .LBB0_693

; __device__ __forceinline__ void u4f(const u32x4& u, float (&f)[8]) { h2f(u.x, f[0], f[1]); h2f(u.y, f[2], f[3]); h2f(u.z, f[4], f[5]); h2f(u.w, f[6], f[7]); }
; __device__ __forceinline__ float siluf_(float x) { return x / (1.0f + __expf(-x)); }
; __device__ __forceinline__ void phase_conv(const Params& p, int l, const XcdBarrier& xbar) {
;     ...
;             for (int i = 0; i < 16; ++i) { float w3[8], o[8]; u4f(cur[i], w3);
; #pragma unroll
;                 for (int e = 0; e < 8; ++e) { const float a = bias[e] + w[0][e] * w0[e] + w[1][e] * w1[e] + w[2][e] * w2[e] + w[3][e] * w3[e]; o[e] = siluf_(a); w0[e] = w1[e]; w1[e] = w2[e]; w2[e] = w3[e]; }
;                 *(u32x4*)(proj + (size_t)(r + i) * PN + col) = (u32x4){pkh(o[0], o[1]), pkh(o[2], o[3]), pkh(o[4], o[5]), pkh(o[6], o[7])}; }
.LBB0_677:
	s_or_b64 exec, exec, s[4:5]
	s_mov_b64 s[2:3], 0x6600
	v_lshl_add_u64 v[182:183], v[152:153], 0, s[2:3]
	s_mov_b64 s[2:3], 0x8800
	v_cvt_f32_f16_sdwa v185, v122 dst_sel:DWORD dst_unused:UNUSED_PAD src0_sel:WORD_1
	v_cvt_f32_f16_e32 v184, v122
	v_lshl_add_u64 v[180:181], v[152:153], 0, s[2:3]
	s_mov_b64 s[2:3], 0xaa00
	v_cvt_f32_f16_sdwa v195, v126 dst_sel:DWORD dst_unused:UNUSED_PAD src0_sel:WORD_1
	v_cvt_f32_f16_e32 v194, v126
	v_lshl_add_u64 v[176:177], v[152:153], 0, s[2:3]
	s_mov_b64 s[2:3], 0xcc00
	v_cvt_f32_f16_sdwa v187, v130 dst_sel:DWORD dst_unused:UNUSED_PAD src0_sel:WORD_1
	v_cvt_f32_f16_e32 v186, v130
	v_lshl_add_u64 v[174:175], v[152:153], 0, s[2:3]
	s_mov_b64 s[2:3], 0xee00
	v_cvt_f32_f16_sdwa v179, v118 dst_sel:DWORD dst_unused:UNUSED_PAD src0_sel:WORD_1
	v_cvt_f32_f16_e32 v178, v118
	v_lshl_add_u64 v[172:173], v[152:153], 0, s[2:3]
	s_mov_b64 s[2:3], 0x11000
	v_pk_fma_f32 v[184:185], v[22:23], v[184:185], v[146:147]
	v_lshl_add_u64 v[170:171], v[152:153], 0, s[2:3]
	s_mov_b64 s[2:3], 0x13200
	v_pk_fma_f32 v[184:185], v[26:27], v[194:195], v[184:185]
	v_lshl_add_u64 v[168:169], v[152:153], 0, s[2:3]
	s_mov_b64 s[2:3], 0x15400
	v_pk_fma_f32 v[184:185], v[30:31], v[186:187], v[184:185]
	v_lshl_add_u64 v[166:167], v[152:153], 0, s[2:3]
	s_mov_b64 s[2:3], 0x17600
	v_pk_fma_f32 v[184:185], v[34:35], v[178:179], v[184:185]
	v_lshl_add_u64 v[164:165], v[152:153], 0, s[2:3]
	s_mov_b64 s[2:3], 0x19800
	v_mul_f32_e32 v118, 0xbfb8aa3b, v184
	v_lshl_add_u64 v[162:163], v[152:153], 0, s[2:3]
	s_mov_b64 s[2:3], 0x1ba00
	v_exp_f32_e32 v188, v118
	v_mul_f32_e32 v118, 0xbfb8aa3b, v185
	v_lshl_add_u64 v[160:161], v[152:153], 0, s[2:3]
	s_mov_b64 s[2:3], 0x1dc00
	v_exp_f32_e32 v189, v118
	v_lshl_add_u64 v[158:159], v[152:153], 0, s[2:3]
	s_mov_b64 s[2:3], 0x1fe00
	v_lshl_add_u64 v[156:157], v[152:153], 0, s[2:3]
	s_mov_b64 s[2:3], 0x22000
	v_lshl_add_u64 v[154:155], v[152:153], 0, s[2:3]
	s_mov_b64 s[2:3], 0x24200
	v_lshl_add_u64 v[136:137], v[152:153], 0, s[2:3]
	s_mov_b64 s[2:3], 0x26400
	v_pk_add_f32 v[188:189], v[188:189], 1.0 op_sel_hi:[1,0]
	v_lshl_add_u64 v[134:135], v[152:153], 0, s[2:3]
	v_cvt_f32_f16_sdwa v197, v127 dst_sel:DWORD dst_unused:UNUSED_PAD src0_sel:WORD_1
	v_cvt_f32_f16_e32 v196, v127
	v_cvt_f32_f16_sdwa v199, v128 dst_sel:DWORD dst_unused:UNUSED_PAD src0_sel:WORD_1
	v_rcp_f32_e32 v118, v189
	s_nop 0
	v_mul_f32_e32 v118, v185, v118
	v_cvt_f32_f16_sdwa v189, v131 dst_sel:DWORD dst_unused:UNUSED_PAD src0_sel:WORD_1
	v_cvt_f32_f16_e32 v198, v128
	v_rcp_f32_e32 v122, v188
	s_nop 0
	v_mul_f32_e32 v122, v184, v122
	v_cvt_f32_f16_sdwa v185, v123 dst_sel:DWORD dst_unused:UNUSED_PAD src0_sel:WORD_1
	v_cvt_f32_f16_e32 v184, v123
	v_cvt_f32_f16_e32 v188, v131
	v_cvt_pk_f16_f32 v118, v122, v118
	v_cvt_f32_f16_sdwa v123, v119 dst_sel:DWORD dst_unused:UNUSED_PAD src0_sel:WORD_1
	v_cvt_f32_f16_e32 v122, v119
	v_pk_fma_f32 v[126:127], v[24:25], v[184:185], v[144:145]
	v_cvt_f32_f16_sdwa v191, v132 dst_sel:DWORD dst_unused:UNUSED_PAD src0_sel:WORD_1
	v_pk_fma_f32 v[126:127], v[28:29], v[196:197], v[126:127]
	v_cvt_f32_f16_sdwa v201, v129 dst_sel:DWORD dst_unused:UNUSED_PAD src0_sel:WORD_1
	v_pk_fma_f32 v[126:127], v[32:33], v[188:189], v[126:127]
	v_cvt_f32_f16_e32 v200, v129
	v_pk_fma_f32 v[126:127], v[36:37], v[122:123], v[126:127]
	v_cvt_f32_f16_sdwa v193, v133 dst_sel:DWORD dst_unused:UNUSED_PAD src0_sel:WORD_1
	v_mul_f32_e32 v119, 0xbfb8aa3b, v126
	v_exp_f32_e32 v130, v119
	v_mul_f32_e32 v119, 0xbfb8aa3b, v127
	v_exp_f32_e32 v131, v119
	v_cvt_f32_f16_e32 v192, v133
	s_add_i32 s6, s6, 1
	s_cmp_eq_u32 s6, 1
	v_pk_add_f32 v[130:131], v[130:131], 1.0 op_sel_hi:[1,0]
	s_nop 0
	s_nop 0
	v_rcp_f32_e32 v119, v131
	s_nop 0
	v_mul_f32_e32 v119, v127, v119
	v_cvt_f32_f16_e32 v190, v132
	v_rcp_f32_e32 v127, v130
	s_nop 0
	v_mul_f32_e32 v126, v126, v127
	v_cvt_f32_f16_sdwa v131, v124 dst_sel:DWORD dst_unused:UNUSED_PAD src0_sel:WORD_1
	v_cvt_f32_f16_e32 v130, v124
	v_cvt_pk_f16_f32 v119, v126, v119
	v_cvt_f32_f16_sdwa v127, v120 dst_sel:DWORD dst_unused:UNUSED_PAD src0_sel:WORD_1
	v_cvt_f32_f16_e32 v126, v120
	v_pk_fma_f32 v[130:131], v[0:1], v[130:131], v[142:143]
	s_nop 0
	v_pk_fma_f32 v[130:131], v[4:5], v[198:199], v[130:131]
	s_nop 0
	v_pk_fma_f32 v[130:131], v[8:9], v[190:191], v[130:131]
	s_nop 0
	v_pk_fma_f32 v[130:131], v[18:19], v[126:127], v[130:131]
	s_nop 0
	v_mul_f32_e32 v120, 0xbfb8aa3b, v130
	v_exp_f32_e32 v184, v120
	v_mul_f32_e32 v120, 0xbfb8aa3b, v131
	v_exp_f32_e32 v185, v120
	s_nop 0
	v_pk_add_f32 v[184:185], v[184:185], 1.0 op_sel_hi:[1,0]
	s_nop 0
	s_nop 0
	v_rcp_f32_e32 v120, v185
	s_nop 0
	v_mul_f32_e32 v120, v131, v120
	v_cvt_f32_f16_sdwa v185, v121 dst_sel:DWORD dst_unused:UNUSED_PAD src0_sel:WORD_1
	v_rcp_f32_e32 v124, v184
	s_nop 0
	v_mul_f32_e32 v124, v130, v124
	v_cvt_f32_f16_sdwa v131, v125 dst_sel:DWORD dst_unused:UNUSED_PAD src0_sel:WORD_1
	v_cvt_f32_f16_e32 v130, v125
	v_cvt_f32_f16_e32 v184, v121
	v_cvt_pk_f16_f32 v120, v124, v120
	v_pk_fma_f32 v[124:125], v[2:3], v[130:131], v[140:141]
	s_nop 0
	v_pk_fma_f32 v[124:125], v[6:7], v[200:201], v[124:125]
	s_nop 0
	v_pk_fma_f32 v[124:125], v[10:11], v[192:193], v[124:125]
	s_nop 0
	v_pk_fma_f32 v[124:125], v[20:21], v[184:185], v[124:125]
	s_nop 0
	v_mul_f32_e32 v121, 0xbfb8aa3b, v124
	v_exp_f32_e32 v128, v121
	v_mul_f32_e32 v121, 0xbfb8aa3b, v125
	v_exp_f32_e32 v129, v121
	s_nop 0
	v_pk_add_f32 v[128:129], v[128:129], 1.0 op_sel_hi:[1,0]
	s_nop 0
	s_nop 0
	v_rcp_f32_e32 v121, v129
	s_nop 0
	v_mul_f32_e32 v121, v125, v121
	s_nop 0
	v_rcp_f32_e32 v125, v128
	s_nop 0
	v_mul_f32_e32 v124, v124, v125
	v_cvt_pk_f16_f32 v121, v124, v121
; __device__ __forceinline__ void u4f(const u32x4& u, float (&f)[8]) { h2f(u.x, f[0], f[1]); h2f(u.y, f[2], f[3]); h2f(u.z, f[4], f[5]); h2f(u.w, f[6], f[7]); }
; __device__ __forceinline__ float siluf_(float x) { return x / (1.0f + __expf(-x)); }
; __device__ __forceinline__ void phase_conv(const Params& p, int l, const XcdBarrier& xbar) {
;     ...
;             for (int i = 0; i < 16; ++i) { float w3[8], o[8]; u4f(cur[i], w3);
; #pragma unroll
;                 for (int e = 0; e < 8; ++e) { const float a = bias[e] + w[0][e] * w0[e] + w[1][e] * w1[e] + w[2][e] * w2[e] + w[3][e] * w3[e]; o[e] = siluf_(a); w0[e] = w1[e]; w1[e] = w2[e]; w2[e] = w3[e]; }
;                 *(u32x4*)(proj + (size_t)(r + i) * PN + col) = (u32x4){pkh(o[0], o[1]), pkh(o[2], o[3]), pkh(o[4], o[5]), pkh(o[6], o[7])}; }
	v_cvt_f32_f16_sdwa v131, v114 dst_sel:DWORD dst_unused:UNUSED_PAD src0_sel:WORD_1
	v_cvt_f32_f16_e32 v130, v114
	global_store_dwordx4 v[182:183], v[118:121], off
	v_cvt_f32_f16_sdwa v183, v116 dst_sel:DWORD dst_unused:UNUSED_PAD src0_sel:WORD_1
	v_cvt_f32_f16_e32 v182, v116
	v_pk_fma_f32 v[118:119], v[22:23], v[194:195], v[146:147]
	s_nop 0
	v_pk_fma_f32 v[118:119], v[26:27], v[186:187], v[118:119]
	s_nop 0
	v_pk_fma_f32 v[118:119], v[30:31], v[178:179], v[118:119]
	s_nop 0
	v_pk_fma_f32 v[118:119], v[34:35], v[130:131], v[118:119]
	s_nop 0
	v_mul_f32_e32 v114, 0xbfb8aa3b, v118
	v_exp_f32_e32 v120, v114
	v_mul_f32_e32 v114, 0xbfb8aa3b, v119
	v_exp_f32_e32 v121, v114
	s_nop 0
	v_pk_add_f32 v[120:121], v[120:121], 1.0 op_sel_hi:[1,0]
	s_nop 0
	s_nop 0
	v_rcp_f32_e32 v114, v121
	s_nop 0
	v_mul_f32_e32 v114, v119, v114
	v_cvt_f32_f16_sdwa v129, v115 dst_sel:DWORD dst_unused:UNUSED_PAD src0_sel:WORD_1
	v_rcp_f32_e32 v119, v120
	s_nop 0
	v_mul_f32_e32 v118, v118, v119
	v_cvt_f32_f16_e32 v128, v115
	v_cvt_pk_f16_f32 v114, v118, v114
	v_pk_fma_f32 v[118:119], v[24:25], v[196:197], v[144:145]
	s_nop 0
	v_pk_fma_f32 v[118:119], v[28:29], v[188:189], v[118:119]
	s_nop 0
	v_pk_fma_f32 v[118:119], v[32:33], v[122:123], v[118:119]
	s_nop 0
	v_pk_fma_f32 v[118:119], v[36:37], v[128:129], v[118:119]
	s_nop 0
	v_mul_f32_e32 v115, 0xbfb8aa3b, v118
	v_exp_f32_e32 v120, v115
	v_mul_f32_e32 v115, 0xbfb8aa3b, v119
	v_exp_f32_e32 v121, v115
	s_nop 0
	v_pk_add_f32 v[120:121], v[120:121], 1.0 op_sel_hi:[1,0]
	s_nop 0
	s_nop 0
	v_rcp_f32_e32 v115, v121
	s_nop 0
	v_mul_f32_e32 v115, v119, v115
	s_nop 0
	v_rcp_f32_e32 v119, v120
	s_nop 0
	v_mul_f32_e32 v118, v118, v119
	v_cvt_pk_f16_f32 v115, v118, v115
	v_pk_fma_f32 v[118:119], v[0:1], v[198:199], v[142:143]
	s_nop 0
	v_pk_fma_f32 v[118:119], v[4:5], v[190:191], v[118:119]
	s_nop 0
	v_pk_fma_f32 v[118:119], v[8:9], v[126:127], v[118:119]
	s_nop 0
	v_pk_fma_f32 v[118:119], v[18:19], v[182:183], v[118:119]
	s_nop 0
	v_mul_f32_e32 v116, 0xbfb8aa3b, v118
	v_exp_f32_e32 v120, v116
	v_mul_f32_e32 v116, 0xbfb8aa3b, v119
	v_exp_f32_e32 v121, v116
	s_nop 0
	v_pk_add_f32 v[120:121], v[120:121], 1.0 op_sel_hi:[1,0]
	s_nop 0
	s_nop 0
	v_rcp_f32_e32 v116, v121
	s_nop 0
	v_mul_f32_e32 v116, v119, v116
	s_nop 0
	v_rcp_f32_e32 v119, v120
	s_nop 0
	v_mul_f32_e32 v118, v118, v119
	v_cvt_f32_f16_sdwa v125, v117 dst_sel:DWORD dst_unused:UNUSED_PAD src0_sel:WORD_1
	v_cvt_f32_f16_e32 v124, v117
	v_cvt_pk_f16_f32 v116, v118, v116
	v_pk_fma_f32 v[118:119], v[2:3], v[200:201], v[140:141]
	s_nop 0
	v_pk_fma_f32 v[118:119], v[6:7], v[192:193], v[118:119]
	s_nop 0
	v_pk_fma_f32 v[118:119], v[10:11], v[184:185], v[118:119]
	s_nop 0
	v_pk_fma_f32 v[118:119], v[20:21], v[124:125], v[118:119]
	s_nop 0
	v_mul_f32_e32 v117, 0xbfb8aa3b, v118
	v_exp_f32_e32 v120, v117
	v_mul_f32_e32 v117, 0xbfb8aa3b, v119
	v_exp_f32_e32 v121, v117
	s_nop 0
	v_pk_add_f32 v[120:121], v[120:121], 1.0 op_sel_hi:[1,0]
	s_nop 0
	s_nop 0
	v_rcp_f32_e32 v117, v121
	s_nop 0
	v_mul_f32_e32 v117, v119, v117
	s_nop 0
	v_rcp_f32_e32 v119, v120
	s_nop 0
	v_mul_f32_e32 v118, v118, v119
	v_cvt_pk_f16_f32 v117, v118, v117
	global_store_dwordx4 v[180:181], v[114:117], off
	v_cvt_f32_f16_sdwa v181, v110 dst_sel:DWORD dst_unused:UNUSED_PAD src0_sel:WORD_1
	v_cvt_f32_f16_e32 v180, v110
	v_pk_fma_f32 v[114:115], v[22:23], v[186:187], v[146:147]
	s_nop 0
	v_pk_fma_f32 v[114:115], v[26:27], v[178:179], v[114:115]
	s_nop 0
	v_pk_fma_f32 v[114:115], v[30:31], v[130:131], v[114:115]
	s_nop 0
	v_pk_fma_f32 v[114:115], v[34:35], v[180:181], v[114:115]
	s_nop 0
	v_mul_f32_e32 v110, 0xbfb8aa3b, v114
	v_exp_f32_e32 v116, v110
	v_mul_f32_e32 v110, 0xbfb8aa3b, v115
	v_exp_f32_e32 v117, v110
	s_nop 0
	v_pk_add_f32 v[116:117], v[116:117], 1.0 op_sel_hi:[1,0]
	s_nop 0
	s_nop 0
	v_rcp_f32_e32 v110, v117
	s_nop 0
	v_mul_f32_e32 v110, v115, v110
	v_cvt_f32_f16_sdwa v121, v111 dst_sel:DWORD dst_unused:UNUSED_PAD src0_sel:WORD_1
	v_rcp_f32_e32 v115, v116
	s_nop 0
	v_mul_f32_e32 v114, v114, v115
	v_cvt_f32_f16_e32 v120, v111
	v_cvt_pk_f16_f32 v110, v114, v110
	v_pk_fma_f32 v[114:115], v[24:25], v[188:189], v[144:145]
	s_nop 0
	v_pk_fma_f32 v[114:115], v[28:29], v[122:123], v[114:115]
	s_nop 0
	v_pk_fma_f32 v[114:115], v[32:33], v[128:129], v[114:115]
	s_nop 0
	v_pk_fma_f32 v[114:115], v[36:37], v[120:121], v[114:115]
	s_nop 0
	v_mul_f32_e32 v111, 0xbfb8aa3b, v114
	v_exp_f32_e32 v116, v111
	v_mul_f32_e32 v111, 0xbfb8aa3b, v115
	v_exp_f32_e32 v117, v111
	s_nop 0
	v_pk_add_f32 v[116:117], v[116:117], 1.0 op_sel_hi:[1,0]
	s_nop 0
	s_nop 0
	v_rcp_f32_e32 v111, v117
	s_nop 0
	v_mul_f32_e32 v111, v115, v111
	s_nop 0
	v_rcp_f32_e32 v115, v116
	s_nop 0
	v_mul_f32_e32 v114, v114, v115
	v_cvt_f32_f16_sdwa v119, v112 dst_sel:DWORD dst_unused:UNUSED_PAD src0_sel:WORD_1
	v_cvt_f32_f16_e32 v118, v112
	v_cvt_pk_f16_f32 v111, v114, v111
	v_pk_fma_f32 v[114:115], v[0:1], v[190:191], v[142:143]
	s_nop 0
	v_pk_fma_f32 v[114:115], v[4:5], v[126:127], v[114:115]
	s_nop 0
	v_pk_fma_f32 v[114:115], v[8:9], v[182:183], v[114:115]
	s_nop 0
	v_pk_fma_f32 v[114:115], v[18:19], v[118:119], v[114:115]
	s_nop 0
	v_mul_f32_e32 v112, 0xbfb8aa3b, v114
	v_exp_f32_e32 v116, v112
	v_mul_f32_e32 v112, 0xbfb8aa3b, v115
	v_exp_f32_e32 v117, v112
	s_nop 0
	v_pk_add_f32 v[116:117], v[116:117], 1.0 op_sel_hi:[1,0]
	s_nop 0
	s_nop 0
	v_rcp_f32_e32 v112, v117
	s_nop 0
	v_mul_f32_e32 v112, v115, v112
	s_nop 0
	v_rcp_f32_e32 v115, v116
	s_nop 0
	v_mul_f32_e32 v114, v114, v115
	v_cvt_f32_f16_sdwa v117, v113 dst_sel:DWORD dst_unused:UNUSED_PAD src0_sel:WORD_1
	v_cvt_f32_f16_e32 v116, v113
	v_cvt_pk_f16_f32 v112, v114, v112
	v_pk_fma_f32 v[114:115], v[2:3], v[192:193], v[140:141]
; __device__ __forceinline__ void u4f(const u32x4& u, float (&f)[8]) { h2f(u.x, f[0], f[1]); h2f(u.y, f[2], f[3]); h2f(u.z, f[4], f[5]); h2f(u.w, f[6], f[7]); }
; __device__ __forceinline__ float siluf_(float x) { return x / (1.0f + __expf(-x)); }
; __device__ __forceinline__ void phase_conv(const Params& p, int l, const XcdBarrier& xbar) {
;     ...
;             for (int i = 0; i < 16; ++i) { float w3[8], o[8]; u4f(cur[i], w3);
; #pragma unroll
;                 for (int e = 0; e < 8; ++e) { const float a = bias[e] + w[0][e] * w0[e] + w[1][e] * w1[e] + w[2][e] * w2[e] + w[3][e] * w3[e]; o[e] = siluf_(a); w0[e] = w1[e]; w1[e] = w2[e]; w2[e] = w3[e]; }
;                 *(u32x4*)(proj + (size_t)(r + i) * PN + col) = (u32x4){pkh(o[0], o[1]), pkh(o[2], o[3]), pkh(o[4], o[5]), pkh(o[6], o[7])}; }
	s_nop 0
	v_pk_fma_f32 v[114:115], v[6:7], v[184:185], v[114:115]
	s_nop 0
	v_pk_fma_f32 v[114:115], v[10:11], v[124:125], v[114:115]
	s_nop 0
	v_pk_fma_f32 v[114:115], v[20:21], v[116:117], v[114:115]
	s_nop 0
	v_mul_f32_e32 v113, 0xbfb8aa3b, v114
	v_exp_f32_e32 v132, v113
	v_mul_f32_e32 v113, 0xbfb8aa3b, v115
	v_exp_f32_e32 v133, v113
	s_nop 0
	v_pk_add_f32 v[132:133], v[132:133], 1.0 op_sel_hi:[1,0]
	s_nop 0
	s_nop 0
	v_rcp_f32_e32 v113, v133
	s_nop 0
	v_mul_f32_e32 v113, v115, v113
	s_nop 0
	v_rcp_f32_e32 v115, v132
	s_nop 0
	v_mul_f32_e32 v114, v114, v115
	v_cvt_pk_f16_f32 v113, v114, v113
	v_cvt_f32_f16_sdwa v115, v106 dst_sel:DWORD dst_unused:UNUSED_PAD src0_sel:WORD_1
	v_cvt_f32_f16_e32 v114, v106
	global_store_dwordx4 v[176:177], v[110:113], off
	s_nop 1
	v_pk_fma_f32 v[110:111], v[22:23], v[178:179], v[146:147]
	s_nop 0
	v_pk_fma_f32 v[110:111], v[26:27], v[130:131], v[110:111]
	s_nop 0
	v_pk_fma_f32 v[110:111], v[30:31], v[180:181], v[110:111]
	s_nop 0
	v_pk_fma_f32 v[110:111], v[34:35], v[114:115], v[110:111]
	s_nop 0
	v_mul_f32_e32 v106, 0xbfb8aa3b, v110
	v_exp_f32_e32 v112, v106
	v_mul_f32_e32 v106, 0xbfb8aa3b, v111
	v_exp_f32_e32 v113, v106
	s_nop 0
	v_pk_add_f32 v[112:113], v[112:113], 1.0 op_sel_hi:[1,0]
	s_nop 0
	s_nop 0
	v_rcp_f32_e32 v106, v113
	s_nop 0
	v_mul_f32_e32 v106, v111, v106
	s_nop 0
	v_rcp_f32_e32 v111, v112
	s_nop 0
	v_mul_f32_e32 v110, v110, v111
	v_cvt_f32_f16_sdwa v113, v107 dst_sel:DWORD dst_unused:UNUSED_PAD src0_sel:WORD_1
	v_cvt_f32_f16_e32 v112, v107
	v_cvt_pk_f16_f32 v106, v110, v106
	v_pk_fma_f32 v[110:111], v[24:25], v[122:123], v[144:145]
	s_nop 0
	v_pk_fma_f32 v[110:111], v[28:29], v[128:129], v[110:111]
	s_nop 0
	v_pk_fma_f32 v[110:111], v[32:33], v[120:121], v[110:111]
	s_nop 0
	v_pk_fma_f32 v[110:111], v[36:37], v[112:113], v[110:111]
	s_nop 0
	v_mul_f32_e32 v107, 0xbfb8aa3b, v110
	v_exp_f32_e32 v122, v107
	v_mul_f32_e32 v107, 0xbfb8aa3b, v111
	v_exp_f32_e32 v123, v107
	s_nop 0
	v_pk_add_f32 v[122:123], v[122:123], 1.0 op_sel_hi:[1,0]
	s_nop 0
	s_nop 0
	v_rcp_f32_e32 v107, v123
	s_nop 0
	v_mul_f32_e32 v107, v111, v107
	s_nop 0
	v_rcp_f32_e32 v111, v122
	s_nop 0
	v_mul_f32_e32 v110, v110, v111
	v_cvt_pk_f16_f32 v107, v110, v107
	v_cvt_f32_f16_sdwa v111, v108 dst_sel:DWORD dst_unused:UNUSED_PAD src0_sel:WORD_1
	v_cvt_f32_f16_e32 v110, v108
	v_pk_fma_f32 v[122:123], v[0:1], v[126:127], v[142:143]
	s_nop 0
	v_pk_fma_f32 v[122:123], v[4:5], v[182:183], v[122:123]
	s_nop 0
	v_pk_fma_f32 v[122:123], v[8:9], v[118:119], v[122:123]
	s_nop 0
	v_pk_fma_f32 v[122:123], v[18:19], v[110:111], v[122:123]
	s_nop 0
	v_mul_f32_e32 v108, 0xbfb8aa3b, v122
	v_exp_f32_e32 v126, v108
	v_mul_f32_e32 v108, 0xbfb8aa3b, v123
	v_exp_f32_e32 v127, v108
	s_nop 0
	v_pk_add_f32 v[126:127], v[126:127], 1.0 op_sel_hi:[1,0]
	s_nop 0
	s_nop 0
	v_rcp_f32_e32 v108, v127
	s_nop 0
	v_mul_f32_e32 v108, v123, v108
	s_nop 0
	v_rcp_f32_e32 v123, v126
	s_nop 0
	v_mul_f32_e32 v122, v122, v123
	v_cvt_f32_f16_sdwa v133, v109 dst_sel:DWORD dst_unused:UNUSED_PAD src0_sel:WORD_1
	v_cvt_f32_f16_e32 v132, v109
	v_cvt_pk_f16_f32 v108, v122, v108
	v_pk_fma_f32 v[122:123], v[2:3], v[184:185], v[140:141]
	s_nop 0
	v_pk_fma_f32 v[122:123], v[6:7], v[124:125], v[122:123]
	s_nop 0
	v_pk_fma_f32 v[122:123], v[10:11], v[116:117], v[122:123]
	s_nop 0
	v_pk_fma_f32 v[122:123], v[20:21], v[132:133], v[122:123]
	s_nop 0
	v_mul_f32_e32 v109, 0xbfb8aa3b, v122
	v_exp_f32_e32 v126, v109
	v_mul_f32_e32 v109, 0xbfb8aa3b, v123
	v_exp_f32_e32 v127, v109
	s_nop 0
	v_pk_add_f32 v[126:127], v[126:127], 1.0 op_sel_hi:[1,0]
	s_nop 0
	s_nop 0
	v_rcp_f32_e32 v109, v127
	s_nop 0
	v_mul_f32_e32 v109, v123, v109
	s_nop 0
	v_rcp_f32_e32 v123, v126
	s_nop 0
	v_mul_f32_e32 v122, v122, v123
	v_cvt_pk_f16_f32 v109, v122, v109
	global_store_dwordx4 v[174:175], v[106:109], off
	s_nop 1
	v_cvt_f32_f16_sdwa v107, v102 dst_sel:DWORD dst_unused:UNUSED_PAD src0_sel:WORD_1
	v_cvt_f32_f16_e32 v106, v102
	v_pk_fma_f32 v[108:109], v[22:23], v[130:131], v[146:147]
	s_nop 0
	v_pk_fma_f32 v[108:109], v[26:27], v[180:181], v[108:109]
	s_nop 0
	v_pk_fma_f32 v[108:109], v[30:31], v[114:115], v[108:109]
	s_nop 0
	v_pk_fma_f32 v[108:109], v[34:35], v[106:107], v[108:109]
	s_nop 0
	v_mul_f32_e32 v102, 0xbfb8aa3b, v108
	v_exp_f32_e32 v122, v102
	v_mul_f32_e32 v102, 0xbfb8aa3b, v109
	v_exp_f32_e32 v123, v102
	s_nop 0
	v_pk_add_f32 v[122:123], v[122:123], 1.0 op_sel_hi:[1,0]
	s_nop 0
	s_nop 0
	v_rcp_f32_e32 v102, v123
	s_nop 0
	v_mul_f32_e32 v102, v109, v102
	v_cvt_f32_f16_sdwa v131, v103 dst_sel:DWORD dst_unused:UNUSED_PAD src0_sel:WORD_1
	v_rcp_f32_e32 v109, v122
	s_nop 0
	v_mul_f32_e32 v108, v108, v109
	v_cvt_f32_f16_e32 v130, v103
	v_cvt_pk_f16_f32 v102, v108, v102
	v_pk_fma_f32 v[108:109], v[24:25], v[128:129], v[144:145]
	s_nop 0
	v_pk_fma_f32 v[108:109], v[28:29], v[120:121], v[108:109]
	s_nop 0
	v_pk_fma_f32 v[108:109], v[32:33], v[112:113], v[108:109]
	s_nop 0
	v_pk_fma_f32 v[108:109], v[36:37], v[130:131], v[108:109]
	s_nop 0
	v_mul_f32_e32 v103, 0xbfb8aa3b, v108
	v_exp_f32_e32 v122, v103
	v_mul_f32_e32 v103, 0xbfb8aa3b, v109
	v_exp_f32_e32 v123, v103
	s_nop 0
	v_pk_add_f32 v[122:123], v[122:123], 1.0 op_sel_hi:[1,0]
	s_nop 0
	s_nop 0
	v_rcp_f32_e32 v103, v123
	s_nop 0
	v_mul_f32_e32 v103, v109, v103
	v_cvt_f32_f16_sdwa v129, v104 dst_sel:DWORD dst_unused:UNUSED_PAD src0_sel:WORD_1
	v_rcp_f32_e32 v109, v122
	s_nop 0
	v_mul_f32_e32 v108, v108, v109
	v_cvt_f32_f16_e32 v128, v104
	v_cvt_pk_f16_f32 v103, v108, v103
	v_pk_fma_f32 v[108:109], v[0:1], v[182:183], v[142:143]
	s_nop 0
	v_pk_fma_f32 v[108:109], v[4:5], v[118:119], v[108:109]
	s_nop 0
	v_pk_fma_f32 v[108:109], v[8:9], v[110:111], v[108:109]
; __device__ __forceinline__ void u4f(const u32x4& u, float (&f)[8]) { h2f(u.x, f[0], f[1]); h2f(u.y, f[2], f[3]); h2f(u.z, f[4], f[5]); h2f(u.w, f[6], f[7]); }
; __device__ __forceinline__ float siluf_(float x) { return x / (1.0f + __expf(-x)); }
; __device__ __forceinline__ void phase_conv(const Params& p, int l, const XcdBarrier& xbar) {
;     ...
;             for (int i = 0; i < 16; ++i) { float w3[8], o[8]; u4f(cur[i], w3);
; #pragma unroll
;                 for (int e = 0; e < 8; ++e) { const float a = bias[e] + w[0][e] * w0[e] + w[1][e] * w1[e] + w[2][e] * w2[e] + w[3][e] * w3[e]; o[e] = siluf_(a); w0[e] = w1[e]; w1[e] = w2[e]; w2[e] = w3[e]; }
;                 *(u32x4*)(proj + (size_t)(r + i) * PN + col) = (u32x4){pkh(o[0], o[1]), pkh(o[2], o[3]), pkh(o[4], o[5]), pkh(o[6], o[7])}; }
	s_nop 0
	v_pk_fma_f32 v[108:109], v[18:19], v[128:129], v[108:109]
	s_nop 0
	v_mul_f32_e32 v104, 0xbfb8aa3b, v108
	v_exp_f32_e32 v122, v104
	v_mul_f32_e32 v104, 0xbfb8aa3b, v109
	v_exp_f32_e32 v123, v104
	s_nop 0
	v_pk_add_f32 v[122:123], v[122:123], 1.0 op_sel_hi:[1,0]
	s_nop 0
	s_nop 0
	v_rcp_f32_e32 v104, v123
	s_nop 0
	v_mul_f32_e32 v104, v109, v104
	s_nop 0
	v_rcp_f32_e32 v109, v122
	s_nop 0
	v_mul_f32_e32 v108, v108, v109
	v_cvt_f32_f16_sdwa v127, v105 dst_sel:DWORD dst_unused:UNUSED_PAD src0_sel:WORD_1
	v_cvt_f32_f16_e32 v126, v105
	v_cvt_pk_f16_f32 v104, v108, v104
	v_pk_fma_f32 v[108:109], v[2:3], v[124:125], v[140:141]
	s_nop 0
	v_pk_fma_f32 v[108:109], v[6:7], v[116:117], v[108:109]
	s_nop 0
	v_pk_fma_f32 v[108:109], v[10:11], v[132:133], v[108:109]
	s_nop 0
	v_pk_fma_f32 v[108:109], v[20:21], v[126:127], v[108:109]
	s_nop 0
	v_mul_f32_e32 v105, 0xbfb8aa3b, v108
	v_exp_f32_e32 v122, v105
	v_mul_f32_e32 v105, 0xbfb8aa3b, v109
	v_exp_f32_e32 v123, v105
	s_nop 0
	v_pk_add_f32 v[122:123], v[122:123], 1.0 op_sel_hi:[1,0]
	s_nop 0
	s_nop 0
	v_rcp_f32_e32 v105, v123
	s_nop 0
	v_mul_f32_e32 v105, v109, v105
	s_nop 0
	v_rcp_f32_e32 v109, v122
	s_nop 0
	v_mul_f32_e32 v108, v108, v109
	v_cvt_pk_f16_f32 v105, v108, v105
	v_cvt_f32_f16_sdwa v125, v98 dst_sel:DWORD dst_unused:UNUSED_PAD src0_sel:WORD_1
	v_cvt_f32_f16_e32 v124, v98
	global_store_dwordx4 v[172:173], v[102:105], off
	s_nop 1
	v_pk_fma_f32 v[102:103], v[22:23], v[180:181], v[146:147]
	s_nop 0
	v_pk_fma_f32 v[102:103], v[26:27], v[114:115], v[102:103]
	s_nop 0
	v_pk_fma_f32 v[102:103], v[30:31], v[106:107], v[102:103]
	s_nop 0
	v_pk_fma_f32 v[102:103], v[34:35], v[124:125], v[102:103]
	s_nop 0
	v_mul_f32_e32 v98, 0xbfb8aa3b, v102
	v_exp_f32_e32 v104, v98
	v_mul_f32_e32 v98, 0xbfb8aa3b, v103
	v_exp_f32_e32 v105, v98
	s_nop 0
	v_pk_add_f32 v[104:105], v[104:105], 1.0 op_sel_hi:[1,0]
	s_nop 0
	s_nop 0
	v_rcp_f32_e32 v98, v105
	s_nop 0
	v_mul_f32_e32 v98, v103, v98
	v_cvt_f32_f16_sdwa v123, v99 dst_sel:DWORD dst_unused:UNUSED_PAD src0_sel:WORD_1
	v_rcp_f32_e32 v103, v104
	s_nop 0
	v_mul_f32_e32 v102, v102, v103
	v_cvt_f32_f16_e32 v122, v99
	v_cvt_pk_f16_f32 v98, v102, v98
	v_pk_fma_f32 v[102:103], v[24:25], v[120:121], v[144:145]
	s_nop 0
	v_pk_fma_f32 v[102:103], v[28:29], v[112:113], v[102:103]
	s_nop 0
	v_pk_fma_f32 v[102:103], v[32:33], v[130:131], v[102:103]
	s_nop 0
	v_pk_fma_f32 v[102:103], v[36:37], v[122:123], v[102:103]
	s_nop 0
	v_mul_f32_e32 v99, 0xbfb8aa3b, v102
	v_exp_f32_e32 v104, v99
	v_mul_f32_e32 v99, 0xbfb8aa3b, v103
	v_exp_f32_e32 v105, v99
	s_nop 0
	v_pk_add_f32 v[104:105], v[104:105], 1.0 op_sel_hi:[1,0]
	s_nop 0
	s_nop 0
	v_rcp_f32_e32 v99, v105
	s_nop 0
	v_mul_f32_e32 v99, v103, v99
	v_cvt_f32_f16_sdwa v121, v100 dst_sel:DWORD dst_unused:UNUSED_PAD src0_sel:WORD_1
	v_rcp_f32_e32 v103, v104
	s_nop 0
	v_mul_f32_e32 v102, v102, v103
	v_cvt_f32_f16_e32 v120, v100
	v_cvt_pk_f16_f32 v99, v102, v99
	v_pk_fma_f32 v[102:103], v[0:1], v[118:119], v[142:143]
	s_nop 0
	v_pk_fma_f32 v[102:103], v[4:5], v[110:111], v[102:103]
	s_nop 0
	v_pk_fma_f32 v[102:103], v[8:9], v[128:129], v[102:103]
	s_nop 0
	v_pk_fma_f32 v[102:103], v[18:19], v[120:121], v[102:103]
	s_nop 0
	v_mul_f32_e32 v100, 0xbfb8aa3b, v102
	v_exp_f32_e32 v104, v100
	v_mul_f32_e32 v100, 0xbfb8aa3b, v103
	v_exp_f32_e32 v105, v100
	s_nop 0
	v_pk_add_f32 v[104:105], v[104:105], 1.0 op_sel_hi:[1,0]
	s_nop 0
	s_nop 0
	v_rcp_f32_e32 v100, v105
	s_nop 0
	v_mul_f32_e32 v100, v103, v100
	v_cvt_f32_f16_sdwa v119, v101 dst_sel:DWORD dst_unused:UNUSED_PAD src0_sel:WORD_1
	v_rcp_f32_e32 v103, v104
	s_nop 0
	v_mul_f32_e32 v102, v102, v103
	v_cvt_f32_f16_e32 v118, v101
	v_cvt_pk_f16_f32 v100, v102, v100
	v_pk_fma_f32 v[102:103], v[2:3], v[116:117], v[140:141]
	s_nop 0
	v_pk_fma_f32 v[102:103], v[6:7], v[132:133], v[102:103]
	s_nop 0
	v_pk_fma_f32 v[102:103], v[10:11], v[126:127], v[102:103]
	s_nop 0
	v_pk_fma_f32 v[102:103], v[20:21], v[118:119], v[102:103]
	s_nop 0
	v_mul_f32_e32 v101, 0xbfb8aa3b, v102
	v_exp_f32_e32 v104, v101
	v_mul_f32_e32 v101, 0xbfb8aa3b, v103
	v_exp_f32_e32 v105, v101
	s_nop 0
	v_pk_add_f32 v[104:105], v[104:105], 1.0 op_sel_hi:[1,0]
	s_nop 0
	s_nop 0
	v_rcp_f32_e32 v101, v105
	s_nop 0
	v_mul_f32_e32 v101, v103, v101
	v_cvt_f32_f16_sdwa v117, v94 dst_sel:DWORD dst_unused:UNUSED_PAD src0_sel:WORD_1
	v_rcp_f32_e32 v103, v104
	s_nop 0
	v_mul_f32_e32 v102, v102, v103
	v_cvt_pk_f16_f32 v101, v102, v101
	v_cvt_f32_f16_e32 v116, v94
	global_store_dwordx4 v[170:171], v[98:101], off
	v_cvt_f32_f16_sdwa v109, v90 dst_sel:DWORD dst_unused:UNUSED_PAD src0_sel:WORD_1
	v_cvt_f32_f16_e32 v108, v90
	v_pk_fma_f32 v[98:99], v[22:23], v[114:115], v[146:147]
	v_cvt_f32_f16_sdwa v115, v95 dst_sel:DWORD dst_unused:UNUSED_PAD src0_sel:WORD_1
	v_pk_fma_f32 v[98:99], v[26:27], v[106:107], v[98:99]
	v_cvt_f32_f16_e32 v114, v95
	v_pk_fma_f32 v[98:99], v[30:31], v[124:125], v[98:99]
	s_nop 0
	v_pk_fma_f32 v[98:99], v[34:35], v[116:117], v[98:99]
	s_nop 0
	v_mul_f32_e32 v94, 0xbfb8aa3b, v98
	v_exp_f32_e32 v100, v94
	v_mul_f32_e32 v94, 0xbfb8aa3b, v99
	v_exp_f32_e32 v101, v94
	s_nop 0
	v_pk_add_f32 v[100:101], v[100:101], 1.0 op_sel_hi:[1,0]
	s_nop 0
	s_nop 0
	v_rcp_f32_e32 v94, v101
	s_nop 0
	v_mul_f32_e32 v94, v99, v94
	s_nop 0
	v_rcp_f32_e32 v99, v100
	s_nop 0
	v_mul_f32_e32 v98, v98, v99
	v_cvt_pk_f16_f32 v94, v98, v94
	v_pk_fma_f32 v[98:99], v[24:25], v[112:113], v[144:145]
	v_cvt_f32_f16_sdwa v113, v96 dst_sel:DWORD dst_unused:UNUSED_PAD src0_sel:WORD_1
	v_pk_fma_f32 v[98:99], v[28:29], v[130:131], v[98:99]
	v_cvt_f32_f16_e32 v112, v96
	v_pk_fma_f32 v[98:99], v[32:33], v[122:123], v[98:99]
	s_nop 0
; __device__ __forceinline__ void u4f(const u32x4& u, float (&f)[8]) { h2f(u.x, f[0], f[1]); h2f(u.y, f[2], f[3]); h2f(u.z, f[4], f[5]); h2f(u.w, f[6], f[7]); }
; __device__ __forceinline__ float siluf_(float x) { return x / (1.0f + __expf(-x)); }
; __device__ __forceinline__ void phase_conv(const Params& p, int l, const XcdBarrier& xbar) {
;     ...
;             for (int i = 0; i < 16; ++i) { float w3[8], o[8]; u4f(cur[i], w3);
; #pragma unroll
;                 for (int e = 0; e < 8; ++e) { const float a = bias[e] + w[0][e] * w0[e] + w[1][e] * w1[e] + w[2][e] * w2[e] + w[3][e] * w3[e]; o[e] = siluf_(a); w0[e] = w1[e]; w1[e] = w2[e]; w2[e] = w3[e]; }
;                 *(u32x4*)(proj + (size_t)(r + i) * PN + col) = (u32x4){pkh(o[0], o[1]), pkh(o[2], o[3]), pkh(o[4], o[5]), pkh(o[6], o[7])}; }
	v_pk_fma_f32 v[98:99], v[36:37], v[114:115], v[98:99]
	s_nop 0
	v_mul_f32_e32 v95, 0xbfb8aa3b, v98
	v_exp_f32_e32 v100, v95
	v_mul_f32_e32 v95, 0xbfb8aa3b, v99
	v_exp_f32_e32 v101, v95
	s_nop 0
	v_pk_add_f32 v[100:101], v[100:101], 1.0 op_sel_hi:[1,0]
	s_nop 0
	s_nop 0
	v_rcp_f32_e32 v95, v101
	s_nop 0
	v_mul_f32_e32 v95, v99, v95
	s_nop 0
	v_rcp_f32_e32 v99, v100
	s_nop 0
	v_mul_f32_e32 v98, v98, v99
	v_cvt_pk_f16_f32 v95, v98, v95
	v_pk_fma_f32 v[98:99], v[0:1], v[110:111], v[142:143]
	v_cvt_f32_f16_sdwa v111, v97 dst_sel:DWORD dst_unused:UNUSED_PAD src0_sel:WORD_1
	v_pk_fma_f32 v[98:99], v[4:5], v[128:129], v[98:99]
	v_cvt_f32_f16_e32 v110, v97
	v_pk_fma_f32 v[98:99], v[8:9], v[120:121], v[98:99]
	s_nop 0
	v_pk_fma_f32 v[98:99], v[18:19], v[112:113], v[98:99]
	s_nop 0
	v_mul_f32_e32 v96, 0xbfb8aa3b, v98
	v_exp_f32_e32 v100, v96
	v_mul_f32_e32 v96, 0xbfb8aa3b, v99
	v_exp_f32_e32 v101, v96
	s_nop 0
	v_pk_add_f32 v[100:101], v[100:101], 1.0 op_sel_hi:[1,0]
	s_nop 0
	s_nop 0
	v_rcp_f32_e32 v96, v101
	s_nop 0
	v_mul_f32_e32 v96, v99, v96
	s_nop 0
	v_rcp_f32_e32 v99, v100
	s_nop 0
	v_mul_f32_e32 v98, v98, v99
	v_cvt_pk_f16_f32 v96, v98, v96
	v_pk_fma_f32 v[98:99], v[2:3], v[132:133], v[140:141]
	s_nop 0
	v_pk_fma_f32 v[98:99], v[6:7], v[126:127], v[98:99]
	s_nop 0
	v_pk_fma_f32 v[98:99], v[10:11], v[118:119], v[98:99]
	s_nop 0
	v_pk_fma_f32 v[98:99], v[20:21], v[110:111], v[98:99]
	s_nop 0
	v_mul_f32_e32 v97, 0xbfb8aa3b, v98
	v_exp_f32_e32 v100, v97
	v_mul_f32_e32 v97, 0xbfb8aa3b, v99
	v_exp_f32_e32 v101, v97
	s_nop 0
	v_pk_add_f32 v[100:101], v[100:101], 1.0 op_sel_hi:[1,0]
	s_nop 0
	s_nop 0
	v_rcp_f32_e32 v97, v101
	s_nop 0
	v_mul_f32_e32 v97, v99, v97
	v_cvt_f32_f16_sdwa v105, v92 dst_sel:DWORD dst_unused:UNUSED_PAD src0_sel:WORD_1
	v_rcp_f32_e32 v99, v100
	s_nop 0
	v_mul_f32_e32 v98, v98, v99
	v_cvt_pk_f16_f32 v97, v98, v97
	global_store_dwordx4 v[168:169], v[94:97], off
	v_cvt_f32_f16_e32 v104, v92
	v_cvt_f32_f16_sdwa v103, v93 dst_sel:DWORD dst_unused:UNUSED_PAD src0_sel:WORD_1
	v_pk_fma_f32 v[94:95], v[22:23], v[106:107], v[146:147]
	v_cvt_f32_f16_sdwa v107, v91 dst_sel:DWORD dst_unused:UNUSED_PAD src0_sel:WORD_1
	v_pk_fma_f32 v[94:95], v[26:27], v[124:125], v[94:95]
	v_cvt_f32_f16_e32 v106, v91
	v_pk_fma_f32 v[94:95], v[30:31], v[116:117], v[94:95]
	v_cvt_f32_f16_e32 v102, v93
	v_pk_fma_f32 v[94:95], v[34:35], v[108:109], v[94:95]
	s_nop 0
	v_mul_f32_e32 v90, 0xbfb8aa3b, v94
	v_exp_f32_e32 v96, v90
	v_mul_f32_e32 v90, 0xbfb8aa3b, v95
	v_exp_f32_e32 v97, v90
	s_nop 0
	v_pk_add_f32 v[96:97], v[96:97], 1.0 op_sel_hi:[1,0]
	s_nop 0
	s_nop 0
	v_rcp_f32_e32 v90, v97
	s_nop 0
	v_mul_f32_e32 v90, v95, v90
	s_nop 0
	v_rcp_f32_e32 v95, v96
	s_nop 0
	v_mul_f32_e32 v94, v94, v95
	v_cvt_pk_f16_f32 v90, v94, v90
	v_pk_fma_f32 v[94:95], v[24:25], v[130:131], v[144:145]
	s_nop 0
	v_pk_fma_f32 v[94:95], v[28:29], v[122:123], v[94:95]
	s_nop 0
	v_pk_fma_f32 v[94:95], v[32:33], v[114:115], v[94:95]
	s_nop 0
	v_pk_fma_f32 v[94:95], v[36:37], v[106:107], v[94:95]
	s_nop 0
	v_mul_f32_e32 v91, 0xbfb8aa3b, v94
	v_exp_f32_e32 v96, v91
	v_mul_f32_e32 v91, 0xbfb8aa3b, v95
	v_exp_f32_e32 v97, v91
	s_nop 0
	v_pk_add_f32 v[96:97], v[96:97], 1.0 op_sel_hi:[1,0]
	s_nop 0
	s_nop 0
	v_rcp_f32_e32 v91, v97
	s_nop 0
	v_mul_f32_e32 v91, v95, v91
	s_nop 0
	v_rcp_f32_e32 v95, v96
	s_nop 0
	v_mul_f32_e32 v94, v94, v95
	v_cvt_pk_f16_f32 v91, v94, v91
	v_pk_fma_f32 v[94:95], v[0:1], v[128:129], v[142:143]
	s_nop 0
	v_pk_fma_f32 v[94:95], v[4:5], v[120:121], v[94:95]
	s_nop 0
	v_pk_fma_f32 v[94:95], v[8:9], v[112:113], v[94:95]
	s_nop 0
	v_pk_fma_f32 v[94:95], v[18:19], v[104:105], v[94:95]
	s_nop 0
	v_mul_f32_e32 v92, 0xbfb8aa3b, v94
	v_exp_f32_e32 v96, v92
	v_mul_f32_e32 v92, 0xbfb8aa3b, v95
	v_exp_f32_e32 v97, v92
	s_nop 0
	v_pk_add_f32 v[96:97], v[96:97], 1.0 op_sel_hi:[1,0]
	s_nop 0
	s_nop 0
	v_rcp_f32_e32 v92, v97
	s_nop 0
	v_mul_f32_e32 v92, v95, v92
	s_nop 0
	v_rcp_f32_e32 v95, v96
	s_nop 0
	v_mul_f32_e32 v94, v94, v95
	v_cvt_pk_f16_f32 v92, v94, v92
	v_pk_fma_f32 v[94:95], v[2:3], v[126:127], v[140:141]
	s_nop 0
	v_pk_fma_f32 v[94:95], v[6:7], v[118:119], v[94:95]
	s_nop 0
	v_pk_fma_f32 v[94:95], v[10:11], v[110:111], v[94:95]
	s_nop 0
	v_pk_fma_f32 v[94:95], v[20:21], v[102:103], v[94:95]
	s_nop 0
	v_mul_f32_e32 v93, 0xbfb8aa3b, v94
	v_exp_f32_e32 v96, v93
	v_mul_f32_e32 v93, 0xbfb8aa3b, v95
	v_exp_f32_e32 v97, v93
	s_nop 0
	v_pk_add_f32 v[96:97], v[96:97], 1.0 op_sel_hi:[1,0]
	s_nop 0
	s_nop 0
	v_rcp_f32_e32 v93, v97
	s_nop 0
	v_mul_f32_e32 v93, v95, v93
	v_cvt_f32_f16_sdwa v101, v86 dst_sel:DWORD dst_unused:UNUSED_PAD src0_sel:WORD_1
	v_rcp_f32_e32 v95, v96
	s_nop 0
	v_mul_f32_e32 v94, v94, v95
	v_cvt_pk_f16_f32 v93, v94, v93
	v_cvt_f32_f16_e32 v100, v86
	global_store_dwordx4 v[166:167], v[90:93], off
	v_cvt_f32_f16_sdwa v99, v87 dst_sel:DWORD dst_unused:UNUSED_PAD src0_sel:WORD_1
	v_cvt_f32_f16_e32 v98, v87
	v_pk_fma_f32 v[90:91], v[22:23], v[124:125], v[146:147]
	s_nop 0
	v_pk_fma_f32 v[90:91], v[26:27], v[116:117], v[90:91]
	s_nop 0
	v_pk_fma_f32 v[90:91], v[30:31], v[108:109], v[90:91]
	s_nop 0
	v_pk_fma_f32 v[90:91], v[34:35], v[100:101], v[90:91]
	s_nop 0
	v_mul_f32_e32 v86, 0xbfb8aa3b, v90
	v_exp_f32_e32 v92, v86
	v_mul_f32_e32 v86, 0xbfb8aa3b, v91
	v_exp_f32_e32 v93, v86
	s_nop 0
	v_pk_add_f32 v[92:93], v[92:93], 1.0 op_sel_hi:[1,0]
	s_nop 0
	s_nop 0
	v_rcp_f32_e32 v86, v93
	s_nop 0
	v_mul_f32_e32 v86, v91, v86
	s_nop 0
	v_rcp_f32_e32 v91, v92
	s_nop 0
	v_mul_f32_e32 v90, v90, v91
	v_cvt_pk_f16_f32 v86, v90, v86
	v_pk_fma_f32 v[90:91], v[24:25], v[122:123], v[144:145]
	s_nop 0
	v_pk_fma_f32 v[90:91], v[28:29], v[114:115], v[90:91]
	s_nop 0
; __device__ __forceinline__ void u4f(const u32x4& u, float (&f)[8]) { h2f(u.x, f[0], f[1]); h2f(u.y, f[2], f[3]); h2f(u.z, f[4], f[5]); h2f(u.w, f[6], f[7]); }
; __device__ __forceinline__ float siluf_(float x) { return x / (1.0f + __expf(-x)); }
; __device__ __forceinline__ void phase_conv(const Params& p, int l, const XcdBarrier& xbar) {
;     ...
;             for (int i = 0; i < 16; ++i) { float w3[8], o[8]; u4f(cur[i], w3);
; #pragma unroll
;                 for (int e = 0; e < 8; ++e) { const float a = bias[e] + w[0][e] * w0[e] + w[1][e] * w1[e] + w[2][e] * w2[e] + w[3][e] * w3[e]; o[e] = siluf_(a); w0[e] = w1[e]; w1[e] = w2[e]; w2[e] = w3[e]; }
;                 *(u32x4*)(proj + (size_t)(r + i) * PN + col) = (u32x4){pkh(o[0], o[1]), pkh(o[2], o[3]), pkh(o[4], o[5]), pkh(o[6], o[7])}; }
	v_pk_fma_f32 v[90:91], v[32:33], v[106:107], v[90:91]
	s_nop 0
	v_pk_fma_f32 v[90:91], v[36:37], v[98:99], v[90:91]
	s_nop 0
	v_mul_f32_e32 v87, 0xbfb8aa3b, v90
	v_exp_f32_e32 v92, v87
	v_mul_f32_e32 v87, 0xbfb8aa3b, v91
	v_exp_f32_e32 v93, v87
	s_nop 0
	v_pk_add_f32 v[92:93], v[92:93], 1.0 op_sel_hi:[1,0]
	s_nop 0
	s_nop 0
	v_rcp_f32_e32 v87, v93
	s_nop 0
	v_mul_f32_e32 v87, v91, v87
	v_cvt_f32_f16_sdwa v97, v88 dst_sel:DWORD dst_unused:UNUSED_PAD src0_sel:WORD_1
	v_rcp_f32_e32 v91, v92
	s_nop 0
	v_mul_f32_e32 v90, v90, v91
	v_cvt_f32_f16_e32 v96, v88
	v_cvt_pk_f16_f32 v87, v90, v87
	v_pk_fma_f32 v[90:91], v[0:1], v[120:121], v[142:143]
	s_nop 0
	v_pk_fma_f32 v[90:91], v[4:5], v[112:113], v[90:91]
	s_nop 0
	v_pk_fma_f32 v[90:91], v[8:9], v[104:105], v[90:91]
	s_nop 0
	v_pk_fma_f32 v[90:91], v[18:19], v[96:97], v[90:91]
	s_nop 0
	v_mul_f32_e32 v88, 0xbfb8aa3b, v90
	v_exp_f32_e32 v92, v88
	v_mul_f32_e32 v88, 0xbfb8aa3b, v91
	v_exp_f32_e32 v93, v88
	s_nop 0
	v_pk_add_f32 v[92:93], v[92:93], 1.0 op_sel_hi:[1,0]
	s_nop 0
	s_nop 0
	v_rcp_f32_e32 v88, v93
	s_nop 0
	v_mul_f32_e32 v88, v91, v88
	s_nop 0
	v_rcp_f32_e32 v91, v92
	s_nop 0
	v_mul_f32_e32 v90, v90, v91
	v_cvt_f32_f16_sdwa v95, v89 dst_sel:DWORD dst_unused:UNUSED_PAD src0_sel:WORD_1
	v_cvt_f32_f16_e32 v94, v89
	v_cvt_pk_f16_f32 v88, v90, v88
	v_pk_fma_f32 v[90:91], v[2:3], v[118:119], v[140:141]
	s_nop 0
	v_pk_fma_f32 v[90:91], v[6:7], v[110:111], v[90:91]
	v_pk_fma_f32 v[110:111], v[2:3], v[110:111], v[140:141]
	v_pk_fma_f32 v[90:91], v[10:11], v[102:103], v[90:91]
	v_pk_fma_f32 v[110:111], v[6:7], v[102:103], v[110:111]
	v_pk_fma_f32 v[90:91], v[20:21], v[94:95], v[90:91]
	v_pk_fma_f32 v[110:111], v[10:11], v[94:95], v[110:111]
	v_mul_f32_e32 v89, 0xbfb8aa3b, v90
	v_exp_f32_e32 v92, v89
	v_mul_f32_e32 v89, 0xbfb8aa3b, v91
	v_exp_f32_e32 v93, v89
	v_pk_fma_f32 v[102:103], v[2:3], v[102:103], v[140:141]
	v_pk_add_f32 v[92:93], v[92:93], 1.0 op_sel_hi:[1,0]
	s_nop 0
	v_pk_fma_f32 v[102:103], v[6:7], v[94:95], v[102:103]
	v_pk_fma_f32 v[94:95], v[2:3], v[94:95], v[140:141]
	v_rcp_f32_e32 v89, v93
	s_nop 0
	v_mul_f32_e32 v89, v91, v89
	s_nop 0
	v_rcp_f32_e32 v91, v92
	s_nop 0
	v_mul_f32_e32 v90, v90, v91
	v_cvt_pk_f16_f32 v89, v90, v89
	v_cvt_f32_f16_sdwa v93, v82 dst_sel:DWORD dst_unused:UNUSED_PAD src0_sel:WORD_1
	v_cvt_f32_f16_e32 v92, v82
	global_store_dwordx4 v[164:165], v[86:89], off
	s_nop 1
	v_pk_fma_f32 v[86:87], v[22:23], v[116:117], v[146:147]
	s_nop 0
	v_pk_fma_f32 v[86:87], v[26:27], v[108:109], v[86:87]
	s_nop 0
	v_pk_fma_f32 v[86:87], v[30:31], v[100:101], v[86:87]
	s_nop 0
	v_pk_fma_f32 v[86:87], v[34:35], v[92:93], v[86:87]
	s_nop 0
	v_mul_f32_e32 v82, 0xbfb8aa3b, v86
	v_exp_f32_e32 v88, v82
	v_mul_f32_e32 v82, 0xbfb8aa3b, v87
	v_exp_f32_e32 v89, v82
	s_nop 0
	v_pk_add_f32 v[88:89], v[88:89], 1.0 op_sel_hi:[1,0]
	s_nop 0
	s_nop 0
	v_rcp_f32_e32 v82, v89
	s_nop 0
	v_mul_f32_e32 v82, v87, v82
	s_nop 0
	v_rcp_f32_e32 v87, v88
	s_nop 0
	v_mul_f32_e32 v86, v86, v87
	v_cvt_f32_f16_sdwa v91, v83 dst_sel:DWORD dst_unused:UNUSED_PAD src0_sel:WORD_1
	v_cvt_f32_f16_e32 v90, v83
	v_cvt_pk_f16_f32 v82, v86, v82
	v_pk_fma_f32 v[86:87], v[24:25], v[114:115], v[144:145]
	s_nop 0
	v_pk_fma_f32 v[86:87], v[28:29], v[106:107], v[86:87]
	v_pk_fma_f32 v[106:107], v[24:25], v[106:107], v[144:145]
	v_pk_fma_f32 v[86:87], v[32:33], v[98:99], v[86:87]
	v_pk_fma_f32 v[106:107], v[28:29], v[98:99], v[106:107]
	v_pk_fma_f32 v[86:87], v[36:37], v[90:91], v[86:87]
	v_pk_fma_f32 v[106:107], v[32:33], v[90:91], v[106:107]
	v_mul_f32_e32 v83, 0xbfb8aa3b, v86
	v_exp_f32_e32 v88, v83
	v_mul_f32_e32 v83, 0xbfb8aa3b, v87
	v_exp_f32_e32 v89, v83
	v_pk_fma_f32 v[98:99], v[24:25], v[98:99], v[144:145]
	v_pk_add_f32 v[88:89], v[88:89], 1.0 op_sel_hi:[1,0]
	s_nop 0
	v_pk_fma_f32 v[98:99], v[28:29], v[90:91], v[98:99]
	v_pk_fma_f32 v[90:91], v[24:25], v[90:91], v[144:145]
	v_rcp_f32_e32 v83, v89
	s_nop 0
	v_mul_f32_e32 v83, v87, v83
	s_nop 0
	v_rcp_f32_e32 v87, v88
	s_nop 0
	v_mul_f32_e32 v86, v86, v87
	v_cvt_f32_f16_sdwa v89, v84 dst_sel:DWORD dst_unused:UNUSED_PAD src0_sel:WORD_1
	v_cvt_f32_f16_e32 v88, v84
	v_cvt_pk_f16_f32 v83, v86, v83
	v_pk_fma_f32 v[86:87], v[0:1], v[112:113], v[142:143]
	s_nop 0
	v_pk_fma_f32 v[86:87], v[4:5], v[104:105], v[86:87]
	v_pk_fma_f32 v[104:105], v[0:1], v[104:105], v[142:143]
	v_pk_fma_f32 v[86:87], v[8:9], v[96:97], v[86:87]
	v_pk_fma_f32 v[104:105], v[4:5], v[96:97], v[104:105]
	v_pk_fma_f32 v[86:87], v[18:19], v[88:89], v[86:87]
	v_pk_fma_f32 v[104:105], v[8:9], v[88:89], v[104:105]
	v_mul_f32_e32 v84, 0xbfb8aa3b, v86
	v_exp_f32_e32 v112, v84
	v_mul_f32_e32 v84, 0xbfb8aa3b, v87
	v_exp_f32_e32 v113, v84
	v_pk_fma_f32 v[96:97], v[0:1], v[96:97], v[142:143]
	v_pk_add_f32 v[112:113], v[112:113], 1.0 op_sel_hi:[1,0]
	s_nop 0
	v_pk_fma_f32 v[96:97], v[4:5], v[88:89], v[96:97]
	v_pk_fma_f32 v[88:89], v[0:1], v[88:89], v[142:143]
	v_rcp_f32_e32 v84, v113
	s_nop 0
	v_mul_f32_e32 v84, v87, v84
	s_nop 0
	v_rcp_f32_e32 v87, v112
	s_nop 0
	v_mul_f32_e32 v86, v86, v87
	v_cvt_pk_f16_f32 v84, v86, v84
	v_cvt_f32_f16_sdwa v87, v85 dst_sel:DWORD dst_unused:UNUSED_PAD src0_sel:WORD_1
	v_cvt_f32_f16_e32 v86, v85
	v_pk_fma_f32 v[110:111], v[20:21], v[86:87], v[110:111]
	s_nop 0
	v_mul_f32_e32 v85, 0xbfb8aa3b, v110
	v_exp_f32_e32 v112, v85
	v_mul_f32_e32 v85, 0xbfb8aa3b, v111
	v_exp_f32_e32 v113, v85
	v_pk_fma_f32 v[102:103], v[10:11], v[86:87], v[102:103]
	v_pk_fma_f32 v[94:95], v[6:7], v[86:87], v[94:95]
	v_pk_fma_f32 v[86:87], v[2:3], v[86:87], v[140:141]
	v_pk_add_f32 v[112:113], v[112:113], 1.0 op_sel_hi:[1,0]
	s_nop 0
	s_nop 0
	v_rcp_f32_e32 v85, v113
	s_nop 0
	v_mul_f32_e32 v85, v111, v85
; __device__ __forceinline__ void u4f(const u32x4& u, float (&f)[8]) { h2f(u.x, f[0], f[1]); h2f(u.y, f[2], f[3]); h2f(u.z, f[4], f[5]); h2f(u.w, f[6], f[7]); }
; __device__ __forceinline__ float siluf_(float x) { return x / (1.0f + __expf(-x)); }
; __device__ __forceinline__ void phase_conv(const Params& p, int l, const XcdBarrier& xbar) {
;     ...
;             for (int i = 0; i < 16; ++i) { float w3[8], o[8]; u4f(cur[i], w3);
; #pragma unroll
;                 for (int e = 0; e < 8; ++e) { const float a = bias[e] + w[0][e] * w0[e] + w[1][e] * w1[e] + w[2][e] * w2[e] + w[3][e] * w3[e]; o[e] = siluf_(a); w0[e] = w1[e]; w1[e] = w2[e]; w2[e] = w3[e]; }
;                 *(u32x4*)(proj + (size_t)(r + i) * PN + col) = (u32x4){pkh(o[0], o[1]), pkh(o[2], o[3]), pkh(o[4], o[5]), pkh(o[6], o[7])}; }
	s_nop 0
	v_rcp_f32_e32 v111, v112
	s_nop 0
	v_mul_f32_e32 v110, v110, v111
	v_cvt_pk_f16_f32 v85, v110, v85
	global_store_dwordx4 v[162:163], v[82:85], off
	s_nop 1
	v_cvt_f32_f16_sdwa v83, v78 dst_sel:DWORD dst_unused:UNUSED_PAD src0_sel:WORD_1
	v_cvt_f32_f16_e32 v82, v78
	v_pk_fma_f32 v[84:85], v[22:23], v[108:109], v[146:147]
	s_nop 0
	v_pk_fma_f32 v[84:85], v[26:27], v[100:101], v[84:85]
	s_nop 0
	v_pk_fma_f32 v[84:85], v[30:31], v[92:93], v[84:85]
	s_nop 0
	v_pk_fma_f32 v[84:85], v[34:35], v[82:83], v[84:85]
	s_nop 0
	v_mul_f32_e32 v78, 0xbfb8aa3b, v84
	v_exp_f32_e32 v108, v78
	v_mul_f32_e32 v78, 0xbfb8aa3b, v85
	v_exp_f32_e32 v109, v78
	s_nop 0
	v_pk_add_f32 v[108:109], v[108:109], 1.0 op_sel_hi:[1,0]
	s_nop 0
	s_nop 0
	v_rcp_f32_e32 v78, v109
	s_nop 0
	v_mul_f32_e32 v78, v85, v78
	s_nop 0
	v_rcp_f32_e32 v85, v108
	s_nop 0
	v_mul_f32_e32 v84, v84, v85
	v_cvt_pk_f16_f32 v78, v84, v78
	v_cvt_f32_f16_sdwa v85, v79 dst_sel:DWORD dst_unused:UNUSED_PAD src0_sel:WORD_1
	v_cvt_f32_f16_e32 v84, v79
	v_pk_fma_f32 v[106:107], v[36:37], v[84:85], v[106:107]
	s_nop 0
	v_mul_f32_e32 v79, 0xbfb8aa3b, v106
	v_exp_f32_e32 v108, v79
	v_mul_f32_e32 v79, 0xbfb8aa3b, v107
	v_exp_f32_e32 v109, v79
	v_pk_fma_f32 v[98:99], v[32:33], v[84:85], v[98:99]
	v_pk_fma_f32 v[90:91], v[28:29], v[84:85], v[90:91]
	v_pk_add_f32 v[108:109], v[108:109], 1.0 op_sel_hi:[1,0]
	s_nop 0
	s_nop 0
	v_rcp_f32_e32 v79, v109
	s_nop 0
	v_mul_f32_e32 v79, v107, v79
	s_nop 0
	v_rcp_f32_e32 v107, v108
	s_nop 0
	v_mul_f32_e32 v106, v106, v107
	v_cvt_pk_f16_f32 v79, v106, v79
	v_cvt_f32_f16_sdwa v107, v80 dst_sel:DWORD dst_unused:UNUSED_PAD src0_sel:WORD_1
	v_cvt_f32_f16_e32 v106, v80
	v_pk_fma_f32 v[104:105], v[18:19], v[106:107], v[104:105]
	s_nop 0
	v_mul_f32_e32 v80, 0xbfb8aa3b, v104
	v_exp_f32_e32 v108, v80
	v_mul_f32_e32 v80, 0xbfb8aa3b, v105
	v_exp_f32_e32 v109, v80
	v_pk_fma_f32 v[96:97], v[8:9], v[106:107], v[96:97]
	v_pk_fma_f32 v[88:89], v[4:5], v[106:107], v[88:89]
	v_pk_add_f32 v[108:109], v[108:109], 1.0 op_sel_hi:[1,0]
	s_nop 0
	s_nop 0
	v_rcp_f32_e32 v80, v109
	s_nop 0
	v_mul_f32_e32 v80, v105, v80
	s_nop 0
	v_rcp_f32_e32 v105, v108
	s_nop 0
	v_mul_f32_e32 v104, v104, v105
	v_cvt_pk_f16_f32 v80, v104, v80
	v_cvt_f32_f16_sdwa v105, v81 dst_sel:DWORD dst_unused:UNUSED_PAD src0_sel:WORD_1
	v_cvt_f32_f16_e32 v104, v81
	v_pk_fma_f32 v[102:103], v[20:21], v[104:105], v[102:103]
	s_nop 0
	v_mul_f32_e32 v81, 0xbfb8aa3b, v102
	v_exp_f32_e32 v108, v81
	v_mul_f32_e32 v81, 0xbfb8aa3b, v103
	v_exp_f32_e32 v109, v81
	v_pk_fma_f32 v[94:95], v[10:11], v[104:105], v[94:95]
	v_pk_fma_f32 v[86:87], v[6:7], v[104:105], v[86:87]
	v_pk_add_f32 v[108:109], v[108:109], 1.0 op_sel_hi:[1,0]
	s_nop 0
	s_nop 0
	v_rcp_f32_e32 v81, v109
	s_nop 0
	v_mul_f32_e32 v81, v103, v81
	s_nop 0
	v_rcp_f32_e32 v103, v108
	s_nop 0
	v_mul_f32_e32 v102, v102, v103
	v_cvt_pk_f16_f32 v81, v102, v81
	global_store_dwordx4 v[160:161], v[78:81], off
	s_nop 1
	v_cvt_f32_f16_sdwa v79, v74 dst_sel:DWORD dst_unused:UNUSED_PAD src0_sel:WORD_1
	v_cvt_f32_f16_e32 v78, v74
	v_pk_fma_f32 v[80:81], v[22:23], v[100:101], v[146:147]
	s_nop 0
	v_pk_fma_f32 v[80:81], v[26:27], v[92:93], v[80:81]
	s_nop 0
	v_pk_fma_f32 v[80:81], v[30:31], v[82:83], v[80:81]
	s_nop 0
	v_pk_fma_f32 v[80:81], v[34:35], v[78:79], v[80:81]
	s_nop 0
	v_mul_f32_e32 v74, 0xbfb8aa3b, v80
	v_exp_f32_e32 v100, v74
	v_mul_f32_e32 v74, 0xbfb8aa3b, v81
	v_exp_f32_e32 v101, v74
	s_nop 0
	v_pk_add_f32 v[100:101], v[100:101], 1.0 op_sel_hi:[1,0]
	s_nop 0
	s_nop 0
	v_rcp_f32_e32 v74, v101
	s_nop 0
	v_mul_f32_e32 v74, v81, v74
	s_nop 0
	v_rcp_f32_e32 v81, v100
	s_nop 0
	v_mul_f32_e32 v80, v80, v81
	v_cvt_pk_f16_f32 v74, v80, v74
	v_cvt_f32_f16_sdwa v81, v75 dst_sel:DWORD dst_unused:UNUSED_PAD src0_sel:WORD_1
	v_cvt_f32_f16_e32 v80, v75
	v_pk_fma_f32 v[98:99], v[36:37], v[80:81], v[98:99]
	s_nop 0
	v_mul_f32_e32 v75, 0xbfb8aa3b, v98
	v_exp_f32_e32 v100, v75
	v_mul_f32_e32 v75, 0xbfb8aa3b, v99
	v_exp_f32_e32 v101, v75
	v_pk_fma_f32 v[90:91], v[32:33], v[80:81], v[90:91]
	v_pk_add_f32 v[100:101], v[100:101], 1.0 op_sel_hi:[1,0]
	s_nop 0
	s_nop 0
	v_rcp_f32_e32 v75, v101
	s_nop 0
	v_mul_f32_e32 v75, v99, v75
	s_nop 0
	v_rcp_f32_e32 v99, v100
	s_nop 0
	v_mul_f32_e32 v98, v98, v99
	v_cvt_pk_f16_f32 v75, v98, v75
	v_cvt_f32_f16_sdwa v99, v76 dst_sel:DWORD dst_unused:UNUSED_PAD src0_sel:WORD_1
	v_cvt_f32_f16_e32 v98, v76
	v_pk_fma_f32 v[96:97], v[18:19], v[98:99], v[96:97]
	s_nop 0
	v_mul_f32_e32 v76, 0xbfb8aa3b, v96
	v_exp_f32_e32 v100, v76
	v_mul_f32_e32 v76, 0xbfb8aa3b, v97
	v_exp_f32_e32 v101, v76
	v_pk_fma_f32 v[88:89], v[8:9], v[98:99], v[88:89]
	v_pk_add_f32 v[100:101], v[100:101], 1.0 op_sel_hi:[1,0]
	s_nop 0
	s_nop 0
	v_rcp_f32_e32 v76, v101
	s_nop 0
	v_mul_f32_e32 v76, v97, v76
	s_nop 0
	v_rcp_f32_e32 v97, v100
	s_nop 0
	v_mul_f32_e32 v96, v96, v97
	v_cvt_pk_f16_f32 v76, v96, v76
	v_cvt_f32_f16_sdwa v97, v77 dst_sel:DWORD dst_unused:UNUSED_PAD src0_sel:WORD_1
	v_cvt_f32_f16_e32 v96, v77
	v_pk_fma_f32 v[94:95], v[20:21], v[96:97], v[94:95]
	s_nop 0
	v_mul_f32_e32 v77, 0xbfb8aa3b, v94
	v_exp_f32_e32 v100, v77
	v_mul_f32_e32 v77, 0xbfb8aa3b, v95
	v_exp_f32_e32 v101, v77
	v_pk_fma_f32 v[86:87], v[10:11], v[96:97], v[86:87]
	v_pk_add_f32 v[100:101], v[100:101], 1.0 op_sel_hi:[1,0]
	s_nop 0
	s_nop 0
	v_rcp_f32_e32 v77, v101
	s_nop 0
	v_mul_f32_e32 v77, v95, v77
	s_nop 0
	v_rcp_f32_e32 v95, v100
	s_nop 0
	v_mul_f32_e32 v94, v94, v95
	v_cvt_pk_f16_f32 v77, v94, v77
	global_store_dwordx4 v[158:159], v[74:77], off
	s_nop 1
	v_cvt_f32_f16_sdwa v75, v70 dst_sel:DWORD dst_unused:UNUSED_PAD src0_sel:WORD_1
	v_cvt_f32_f16_e32 v74, v70
	v_pk_fma_f32 v[76:77], v[22:23], v[92:93], v[146:147]
; __device__ __forceinline__ void u4f(const u32x4& u, float (&f)[8]) { h2f(u.x, f[0], f[1]); h2f(u.y, f[2], f[3]); h2f(u.z, f[4], f[5]); h2f(u.w, f[6], f[7]); }
; __device__ __forceinline__ float siluf_(float x) { return x / (1.0f + __expf(-x)); }
; __device__ __forceinline__ void phase_conv(const Params& p, int l, const XcdBarrier& xbar) {
;     ...
;             float w0[8], w1[8], w2[8];
;             u4f(pre[0], w0); u4f(pre[1], w1); u4f(pre[2], w2);
; #pragma unroll
;             for (int i = 0; i < 16; ++i) { float w3[8], o[8]; u4f(cur[i], w3);
; #pragma unroll
;                 for (int e = 0; e < 8; ++e) { const float a = bias[e] + w[0][e] * w0[e] + w[1][e] * w1[e] + w[2][e] * w2[e] + w[3][e] * w3[e]; o[e] = siluf_(a); w0[e] = w1[e]; w1[e] = w2[e]; w2[e] = w3[e]; }
;                 *(u32x4*)(proj + (size_t)(r + i) * PN + col) = (u32x4){pkh(o[0], o[1]), pkh(o[2], o[3]), pkh(o[4], o[5]), pkh(o[6], o[7])}; }
	s_nop 0
	v_pk_fma_f32 v[76:77], v[26:27], v[82:83], v[76:77]
	s_nop 0
	v_pk_fma_f32 v[76:77], v[30:31], v[78:79], v[76:77]
	s_nop 0
	v_pk_fma_f32 v[76:77], v[34:35], v[74:75], v[76:77]
	s_nop 0
	v_mul_f32_e32 v70, 0xbfb8aa3b, v76
	v_exp_f32_e32 v92, v70
	v_mul_f32_e32 v70, 0xbfb8aa3b, v77
	v_exp_f32_e32 v93, v70
	s_nop 0
	v_pk_add_f32 v[92:93], v[92:93], 1.0 op_sel_hi:[1,0]
	s_nop 0
	s_nop 0
	v_rcp_f32_e32 v70, v93
	s_nop 0
	v_mul_f32_e32 v70, v77, v70
	s_nop 0
	v_rcp_f32_e32 v77, v92
	s_nop 0
	v_mul_f32_e32 v76, v76, v77
	v_cvt_pk_f16_f32 v70, v76, v70
	v_cvt_f32_f16_sdwa v77, v71 dst_sel:DWORD dst_unused:UNUSED_PAD src0_sel:WORD_1
	v_cvt_f32_f16_e32 v76, v71
	v_pk_fma_f32 v[90:91], v[36:37], v[76:77], v[90:91]
	s_nop 0
	v_mul_f32_e32 v71, 0xbfb8aa3b, v90
	v_exp_f32_e32 v92, v71
	v_mul_f32_e32 v71, 0xbfb8aa3b, v91
	v_exp_f32_e32 v93, v71
	s_nop 0
	v_pk_add_f32 v[92:93], v[92:93], 1.0 op_sel_hi:[1,0]
	s_nop 0
	s_nop 0
	v_rcp_f32_e32 v71, v93
	s_nop 0
	v_mul_f32_e32 v71, v91, v71
	s_nop 0
	v_rcp_f32_e32 v91, v92
	s_nop 0
	v_mul_f32_e32 v90, v90, v91
	v_cvt_pk_f16_f32 v71, v90, v71
	v_cvt_f32_f16_sdwa v91, v72 dst_sel:DWORD dst_unused:UNUSED_PAD src0_sel:WORD_1
	v_cvt_f32_f16_e32 v90, v72
	v_pk_fma_f32 v[88:89], v[18:19], v[90:91], v[88:89]
	s_nop 0
	v_mul_f32_e32 v72, 0xbfb8aa3b, v88
	v_exp_f32_e32 v92, v72
	v_mul_f32_e32 v72, 0xbfb8aa3b, v89
	v_exp_f32_e32 v93, v72
	s_nop 0
	v_pk_add_f32 v[92:93], v[92:93], 1.0 op_sel_hi:[1,0]
	s_nop 0
	s_nop 0
	v_rcp_f32_e32 v72, v93
	s_nop 0
	v_mul_f32_e32 v72, v89, v72
	s_nop 0
	v_rcp_f32_e32 v89, v92
	s_nop 0
	v_mul_f32_e32 v88, v88, v89
	v_cvt_pk_f16_f32 v72, v88, v72
	v_cvt_f32_f16_sdwa v89, v73 dst_sel:DWORD dst_unused:UNUSED_PAD src0_sel:WORD_1
	v_cvt_f32_f16_e32 v88, v73
	v_pk_fma_f32 v[86:87], v[20:21], v[88:89], v[86:87]
	s_nop 0
	v_mul_f32_e32 v73, 0xbfb8aa3b, v86
	v_exp_f32_e32 v92, v73
	v_mul_f32_e32 v73, 0xbfb8aa3b, v87
	v_exp_f32_e32 v93, v73
	s_nop 0
	v_pk_add_f32 v[92:93], v[92:93], 1.0 op_sel_hi:[1,0]
	s_nop 0
	s_nop 0
	v_rcp_f32_e32 v73, v93
	s_nop 0
	v_mul_f32_e32 v73, v87, v73
	s_nop 0
	v_rcp_f32_e32 v87, v92
	s_nop 0
	v_mul_f32_e32 v86, v86, v87
	v_cvt_pk_f16_f32 v73, v86, v73
	global_store_dwordx4 v[156:157], v[70:73], off
	s_nop 1
	v_pk_fma_f32 v[70:71], v[22:23], v[82:83], v[146:147]
	s_nop 0
	v_pk_fma_f32 v[70:71], v[26:27], v[78:79], v[70:71]
	s_nop 0
	v_pk_fma_f32 v[70:71], v[30:31], v[74:75], v[70:71]
	s_nop 0
	v_pk_fma_f32 v[70:71], v[34:35], v[58:59], v[70:71]
	s_nop 0
	v_mul_f32_e32 v72, 0xbfb8aa3b, v70
	v_mul_f32_e32 v73, 0xbfb8aa3b, v71
	v_exp_f32_e32 v72, v72
	v_exp_f32_e32 v73, v73
	s_nop 0
	v_pk_add_f32 v[72:73], v[72:73], 1.0 op_sel_hi:[1,0]
	s_nop 0
	s_nop 0
	v_rcp_f32_e32 v82, v73
	s_nop 0
	v_mul_f32_e32 v71, v71, v82
	s_nop 0
	v_rcp_f32_e32 v73, v72
	s_nop 0
	v_mul_f32_e32 v70, v70, v73
	v_pk_fma_f32 v[72:73], v[24:25], v[84:85], v[144:145]
	v_cvt_pk_f16_f32 v70, v70, v71
	v_pk_fma_f32 v[72:73], v[28:29], v[80:81], v[72:73]
	s_nop 0
	v_pk_fma_f32 v[72:73], v[32:33], v[76:77], v[72:73]
	s_nop 0
	v_pk_fma_f32 v[72:73], v[36:37], v[60:61], v[72:73]
	s_nop 0
	v_mul_f32_e32 v71, 0xbfb8aa3b, v72
	v_exp_f32_e32 v82, v71
	v_mul_f32_e32 v71, 0xbfb8aa3b, v73
	v_exp_f32_e32 v83, v71
	s_nop 0
	v_pk_add_f32 v[82:83], v[82:83], 1.0 op_sel_hi:[1,0]
	s_nop 0
	s_nop 0
	v_rcp_f32_e32 v71, v83
	s_nop 0
	v_mul_f32_e32 v71, v73, v71
	s_nop 0
	v_rcp_f32_e32 v73, v82
	s_nop 0
	v_mul_f32_e32 v72, v72, v73
	v_cvt_pk_f16_f32 v71, v72, v71
	v_pk_fma_f32 v[72:73], v[0:1], v[106:107], v[142:143]
	s_nop 0
	v_pk_fma_f32 v[72:73], v[4:5], v[98:99], v[72:73]
	s_nop 0
	v_pk_fma_f32 v[72:73], v[8:9], v[90:91], v[72:73]
	s_nop 0
	v_pk_fma_f32 v[72:73], v[18:19], v[46:47], v[72:73]
	s_nop 0
	v_mul_f32_e32 v82, 0xbfb8aa3b, v72
	v_mul_f32_e32 v83, 0xbfb8aa3b, v73
	v_exp_f32_e32 v82, v82
	v_exp_f32_e32 v83, v83
	s_nop 0
	v_pk_add_f32 v[82:83], v[82:83], 1.0 op_sel_hi:[1,0]
	s_nop 0
	s_nop 0
	v_rcp_f32_e32 v84, v83
	s_nop 0
	v_mul_f32_e32 v73, v73, v84
	s_nop 0
	v_rcp_f32_e32 v83, v82
	s_nop 0
	v_mul_f32_e32 v72, v72, v83
	v_pk_fma_f32 v[82:83], v[2:3], v[104:105], v[140:141]
	v_cvt_pk_f16_f32 v72, v72, v73
	v_pk_fma_f32 v[82:83], v[6:7], v[96:97], v[82:83]
	s_nop 0
	v_pk_fma_f32 v[82:83], v[10:11], v[88:89], v[82:83]
	s_nop 0
	v_pk_fma_f32 v[82:83], v[20:21], v[48:49], v[82:83]
	s_nop 0
	v_mul_f32_e32 v73, 0xbfb8aa3b, v82
	v_exp_f32_e32 v84, v73
	v_mul_f32_e32 v73, 0xbfb8aa3b, v83
	v_exp_f32_e32 v85, v73
	s_nop 0
	v_pk_add_f32 v[84:85], v[84:85], 1.0 op_sel_hi:[1,0]
	s_nop 0
	s_nop 0
	v_rcp_f32_e32 v73, v85
	s_nop 0
	v_mul_f32_e32 v73, v83, v73
	s_nop 0
	v_rcp_f32_e32 v83, v84
	s_nop 0
	v_mul_f32_e32 v82, v82, v83
	v_cvt_pk_f16_f32 v73, v82, v73
	global_store_dwordx4 v[154:155], v[70:73], off
	s_nop 1
	v_pk_fma_f32 v[70:71], v[22:23], v[78:79], v[146:147]
	s_nop 0
	v_pk_fma_f32 v[70:71], v[26:27], v[74:75], v[70:71]
	s_nop 0
	v_pk_fma_f32 v[70:71], v[30:31], v[58:59], v[70:71]
	s_nop 0
; __device__ __forceinline__ void u4f(const u32x4& u, float (&f)[8]) { h2f(u.x, f[0], f[1]); h2f(u.y, f[2], f[3]); h2f(u.z, f[4], f[5]); h2f(u.w, f[6], f[7]); }
; __device__ __forceinline__ float siluf_(float x) { return x / (1.0f + __expf(-x)); }
; __device__ __forceinline__ void phase_conv(const Params& p, int l, const XcdBarrier& xbar) {
;     ...
;             float w0[8], w1[8], w2[8];
;             u4f(pre[0], w0); u4f(pre[1], w1); u4f(pre[2], w2);
; #pragma unroll
;             for (int i = 0; i < 16; ++i) { float w3[8], o[8]; u4f(cur[i], w3);
; #pragma unroll
;                 for (int e = 0; e < 8; ++e) { const float a = bias[e] + w[0][e] * w0[e] + w[1][e] * w1[e] + w[2][e] * w2[e] + w[3][e] * w3[e]; o[e] = siluf_(a); w0[e] = w1[e]; w1[e] = w2[e]; w2[e] = w3[e]; }
;                 *(u32x4*)(proj + (size_t)(r + i) * PN + col) = (u32x4){pkh(o[0], o[1]), pkh(o[2], o[3]), pkh(o[4], o[5]), pkh(o[6], o[7])}; }
	v_pk_fma_f32 v[70:71], v[34:35], v[62:63], v[70:71]
	s_nop 0
	v_mul_f32_e32 v72, 0xbfb8aa3b, v70
	v_mul_f32_e32 v73, 0xbfb8aa3b, v71
	v_exp_f32_e32 v72, v72
	v_exp_f32_e32 v73, v73
	s_nop 0
	v_pk_add_f32 v[72:73], v[72:73], 1.0 op_sel_hi:[1,0]
	s_nop 0
	s_nop 0
	v_rcp_f32_e32 v78, v73
	s_nop 0
	v_mul_f32_e32 v71, v71, v78
	s_nop 0
	v_rcp_f32_e32 v73, v72
	s_nop 0
	v_mul_f32_e32 v70, v70, v73
	v_pk_fma_f32 v[72:73], v[24:25], v[80:81], v[144:145]
	v_cvt_pk_f16_f32 v70, v70, v71
	v_pk_fma_f32 v[72:73], v[28:29], v[76:77], v[72:73]
	s_nop 0
	v_pk_fma_f32 v[72:73], v[32:33], v[60:61], v[72:73]
	s_nop 0
	v_pk_fma_f32 v[72:73], v[36:37], v[64:65], v[72:73]
	s_nop 0
	v_mul_f32_e32 v71, 0xbfb8aa3b, v72
	v_exp_f32_e32 v78, v71
	v_mul_f32_e32 v71, 0xbfb8aa3b, v73
	v_exp_f32_e32 v79, v71
	s_nop 0
	v_pk_add_f32 v[78:79], v[78:79], 1.0 op_sel_hi:[1,0]
	s_nop 0
	s_nop 0
	v_rcp_f32_e32 v71, v79
	s_nop 0
	v_mul_f32_e32 v71, v73, v71
	s_nop 0
	v_rcp_f32_e32 v73, v78
	s_nop 0
	v_mul_f32_e32 v72, v72, v73
	v_cvt_pk_f16_f32 v71, v72, v71
	v_pk_fma_f32 v[72:73], v[0:1], v[98:99], v[142:143]
	s_nop 0
	v_pk_fma_f32 v[72:73], v[4:5], v[90:91], v[72:73]
	s_nop 0
	v_pk_fma_f32 v[72:73], v[8:9], v[46:47], v[72:73]
	s_nop 0
	v_pk_fma_f32 v[72:73], v[18:19], v[50:51], v[72:73]
	s_nop 0
	v_mul_f32_e32 v78, 0xbfb8aa3b, v72
	v_mul_f32_e32 v79, 0xbfb8aa3b, v73
	v_exp_f32_e32 v78, v78
	v_exp_f32_e32 v79, v79
	s_nop 0
	v_pk_add_f32 v[78:79], v[78:79], 1.0 op_sel_hi:[1,0]
	s_nop 0
	s_nop 0
	v_rcp_f32_e32 v80, v79
	s_nop 0
	v_mul_f32_e32 v73, v73, v80
	s_nop 0
	v_rcp_f32_e32 v79, v78
	s_nop 0
	v_mul_f32_e32 v72, v72, v79
	v_pk_fma_f32 v[78:79], v[2:3], v[96:97], v[140:141]
	v_cvt_pk_f16_f32 v72, v72, v73
	v_pk_fma_f32 v[78:79], v[6:7], v[88:89], v[78:79]
	s_nop 0
	v_pk_fma_f32 v[78:79], v[10:11], v[48:49], v[78:79]
	s_nop 0
	v_pk_fma_f32 v[78:79], v[20:21], v[52:53], v[78:79]
	s_nop 0
	v_mul_f32_e32 v73, 0xbfb8aa3b, v78
	v_exp_f32_e32 v80, v73
	v_mul_f32_e32 v73, 0xbfb8aa3b, v79
	v_exp_f32_e32 v81, v73
	s_nop 0
	v_pk_add_f32 v[80:81], v[80:81], 1.0 op_sel_hi:[1,0]
	s_nop 0
	s_nop 0
	v_rcp_f32_e32 v73, v81
	s_nop 0
	v_mul_f32_e32 v73, v79, v73
	s_nop 0
	v_rcp_f32_e32 v79, v80
	s_nop 0
	v_mul_f32_e32 v78, v78, v79
	v_cvt_pk_f16_f32 v73, v78, v73
	global_store_dwordx4 v[136:137], v[70:73], off
	s_nop 1
	v_pk_fma_f32 v[70:71], v[22:23], v[74:75], v[146:147]
	s_nop 0
	v_pk_fma_f32 v[58:59], v[26:27], v[58:59], v[70:71]
	s_nop 0
	v_pk_fma_f32 v[58:59], v[30:31], v[62:63], v[58:59]
	s_nop 0
	v_pk_fma_f32 v[58:59], v[34:35], v[66:67], v[58:59]
	s_nop 0
	v_mul_f32_e32 v62, 0xbfb8aa3b, v58
	v_mul_f32_e32 v63, 0xbfb8aa3b, v59
	v_exp_f32_e32 v62, v62
	v_exp_f32_e32 v63, v63
	s_nop 0
	v_pk_add_f32 v[62:63], v[62:63], 1.0 op_sel_hi:[1,0]
	s_nop 0
	s_nop 0
	v_rcp_f32_e32 v66, v63
	s_nop 0
	v_mul_f32_e32 v59, v59, v66
	s_nop 0
	v_rcp_f32_e32 v63, v62
	s_nop 0
	v_mul_f32_e32 v58, v58, v63
	v_pk_fma_f32 v[62:63], v[24:25], v[76:77], v[144:145]
	v_cvt_pk_f16_f32 v58, v58, v59
	v_pk_fma_f32 v[60:61], v[28:29], v[60:61], v[62:63]
	s_nop 0
	v_pk_fma_f32 v[60:61], v[32:33], v[64:65], v[60:61]
	s_nop 0
	v_pk_fma_f32 v[60:61], v[36:37], v[68:69], v[60:61]
	s_nop 0
	v_mul_f32_e32 v59, 0xbfb8aa3b, v60
	v_exp_f32_e32 v62, v59
	v_mul_f32_e32 v59, 0xbfb8aa3b, v61
	v_exp_f32_e32 v63, v59
	s_nop 0
	v_pk_add_f32 v[62:63], v[62:63], 1.0 op_sel_hi:[1,0]
	s_nop 0
	s_nop 0
	v_rcp_f32_e32 v59, v63
	s_nop 0
	v_mul_f32_e32 v59, v61, v59
	s_nop 0
	v_rcp_f32_e32 v61, v62
	s_nop 0
	v_mul_f32_e32 v60, v60, v61
	v_cvt_pk_f16_f32 v59, v60, v59
	v_pk_fma_f32 v[60:61], v[0:1], v[90:91], v[142:143]
	s_nop 0
	v_pk_fma_f32 v[46:47], v[4:5], v[46:47], v[60:61]
	s_nop 0
	v_pk_fma_f32 v[46:47], v[8:9], v[50:51], v[46:47]
	s_nop 0
	v_pk_fma_f32 v[46:47], v[18:19], v[54:55], v[46:47]
	s_nop 0
	v_mul_f32_e32 v50, 0xbfb8aa3b, v46
	v_mul_f32_e32 v51, 0xbfb8aa3b, v47
	v_exp_f32_e32 v50, v50
	v_exp_f32_e32 v51, v51
	s_nop 0
	v_pk_add_f32 v[50:51], v[50:51], 1.0 op_sel_hi:[1,0]
	s_nop 0
	s_nop 0
	v_rcp_f32_e32 v54, v51
	s_nop 0
	v_mul_f32_e32 v47, v47, v54
	s_nop 0
	v_rcp_f32_e32 v51, v50
	s_nop 0
	v_mul_f32_e32 v46, v46, v51
	v_cvt_pk_f16_f32 v60, v46, v47
	v_pk_fma_f32 v[46:47], v[2:3], v[88:89], v[140:141]
	s_nop 0
	v_pk_fma_f32 v[46:47], v[6:7], v[48:49], v[46:47]
	s_nop 0
	v_pk_fma_f32 v[46:47], v[10:11], v[52:53], v[46:47]
	s_nop 0
	v_pk_fma_f32 v[46:47], v[20:21], v[56:57], v[46:47]
	s_nop 0
	v_mul_f32_e32 v48, 0xbfb8aa3b, v46
	v_mul_f32_e32 v49, 0xbfb8aa3b, v47
	v_exp_f32_e32 v48, v48
	v_exp_f32_e32 v49, v49
	s_nop 0
	v_pk_add_f32 v[48:49], v[48:49], 1.0 op_sel_hi:[1,0]
	s_nop 0
	s_nop 0
	v_rcp_f32_e32 v50, v49
	s_nop 0
	v_mul_f32_e32 v47, v47, v50
	s_mov_b32 s2, 0xfffde000
	s_mov_b32 s3, -1
	v_lshl_add_u64 v[152:153], v[152:153], 0, s[2:3]
	v_rcp_f32_e32 v49, v48
	s_nop 0
	v_mul_f32_e32 v46, v46, v49
	v_cvt_pk_f16_f32 v61, v46, v47
	global_store_dwordx4 v[134:135], v[58:61], off
	s_cbranch_scc1 .LBB0_686

; __device__ __forceinline__ float siluf_(float x) { return x / (1.0f + __expf(-x)); }
; __device__ __forceinline__ void u4f(const u32x4& u, float (&f)[8]) { h2f(u.x, f[0], f[1]); h2f(u.y, f[2], f[3]); h2f(u.z, f[4], f[5]); h2f(u.w, f[6], f[7]); }
; __device__ __forceinline__ float* pout() { return kargs()->out; }
; __device__ __forceinline__ void phase_conv(const Params& p, int l, const XcdBarrier& xbar) {
;     ...
;     } else if (kind == 1) {
;         u32x4 cur[4];
; #pragma unroll
;         for (int i = 0; i < 4; ++i) cur[i] = *(const u32x4*)(proj + (size_t)(row0 + i) * PN + col);
;         float win[7][8];
; #pragma unroll
;         for (int i = 0; i < 3; ++i) u4f(h[i], win[i]);
; #pragma unroll
;         for (int i = 0; i < 4; ++i) u4f(cur[i], win[3 + i]);
;         float* so = pout() + (ssd ? O_SSDC_S : O_GDNC_S) + (size_t)((l * NSB + unit) * 3) * 768 + ch;
; #pragma unroll
;         for (int i = 0; i < 3; ++i) { *(f32x4*)(so + i * 768) = (f32x4){win[4 + i][0], win[4 + i][1], win[4 + i][2], win[4 + i][3]};
;             *(f32x4*)(so + i * 768 + 4) = (f32x4){win[4 + i][4], win[4 + i][5], win[4 + i][6], win[4 + i][7]}; }
; #pragma unroll
;         for (int i = 0; i < 4; ++i) { float o[8];
; #pragma unroll
;             for (int e = 0; e < 8; ++e) { float a = bias[e];
; #pragma unroll
;                 for (int j = 0; j < 4; ++j) a += w[j][e] * win[i + j][e];
;                 o[e] = siluf_(a); }
;             *(u32x4*)(proj + (size_t)(row0 + i) * PN + col) = (u32x4){pkh(o[0], o[1]), pkh(o[2], o[3]), pkh(o[4], o[5]), pkh(o[6], o[7])}; }
.LBB0_686:
	s_andn2_saveexec_b64 s[4:5], s[50:51]
	s_cbranch_execz .LBB0_690
	s_and_saveexec_b64 s[6:7], s[44:45]
	s_cbranch_execz .LBB0_689
	v_ashrrev_i32_e32 v47, 31, v46
	v_lshl_add_u64 v[46:47], v[46:47], 1, s[52:53]
	v_mul_lo_u32 v16, v48, s18
	v_lshl_add_u64 v[86:87], v[46:47], 0, v[16:17]
	v_or_b32_e32 v16, 1, v48
	v_mad_i64_i32 v[80:81], s[2:3], v16, s18, v[46:47]
	v_or_b32_e32 v16, 2, v48
	v_mad_i64_i32 v[76:77], s[2:3], v16, s18, v[46:47]
	v_or_b32_e32 v16, 3, v48
	v_mad_i64_i32 v[74:75], s[2:3], v16, s18, v[46:47]
	global_load_dwordx4 v[54:57], v[76:77], off
	global_load_dwordx4 v[82:85], v[74:75], off
	global_load_dwordx4 v[70:73], v[86:87], off
	global_load_dwordx4 v[50:53], v[80:81], off
	s_mov_b64 s[2:3], s[0:1]
	s_load_dwordx2 s[2:3], s[2:3], 0xd8
	v_cndmask_b32_e64 v16, v228, v229, s[42:43]
	s_waitcnt vmcnt(5)
	v_cvt_f32_f16_sdwa v91, v38 dst_sel:DWORD dst_unused:UNUSED_PAD src0_sel:WORD_1
	v_cvt_f32_f16_e32 v90, v38
	v_cvt_f32_f16_sdwa v93, v39 dst_sel:DWORD dst_unused:UNUSED_PAD src0_sel:WORD_1
	v_cvt_f32_f16_e32 v92, v39
	v_cvt_f32_f16_sdwa v95, v40 dst_sel:DWORD dst_unused:UNUSED_PAD src0_sel:WORD_1
	v_cvt_f32_f16_sdwa v99, v15 dst_sel:DWORD dst_unused:UNUSED_PAD src0_sel:WORD_1
	v_cvt_f32_f16_e32 v98, v15
	s_waitcnt vmcnt(3)
	v_cvt_f32_f16_e32 v62, v54
	s_waitcnt vmcnt(2)
	v_cvt_f32_f16_e32 v66, v82
	v_cvt_f32_f16_sdwa v67, v82 dst_sel:DWORD dst_unused:UNUSED_PAD src0_sel:WORD_1
	v_cvt_f32_f16_e32 v68, v83
	v_cvt_f32_f16_sdwa v69, v83 dst_sel:DWORD dst_unused:UNUSED_PAD src0_sel:WORD_1
	s_waitcnt lgkmcnt(0)
	v_lshl_add_u64 v[82:83], s[2:3], 0, v[16:17]
	s_and_b64 s[2:3], s[58:59], exec
	s_cselect_b32 s2, 0x80, 0
	s_waitcnt vmcnt(0)
	v_cvt_f32_f16_e32 v58, v50
	v_cvt_f32_f16_sdwa v59, v50 dst_sel:DWORD dst_unused:UNUSED_PAD src0_sel:WORD_1
	v_cvt_f32_f16_e32 v60, v51
	v_cvt_f32_f16_sdwa v61, v51 dst_sel:DWORD dst_unused:UNUSED_PAD src0_sel:WORD_1
	v_add_u32_e32 v16, s2, v78
	s_movk_i32 s2, 0x2400
	v_cvt_f32_f16_e32 v46, v52
	v_cvt_f32_f16_sdwa v47, v52 dst_sel:DWORD dst_unused:UNUSED_PAD src0_sel:WORD_1
	v_cvt_f32_f16_e32 v48, v53
	v_cvt_f32_f16_sdwa v49, v53 dst_sel:DWORD dst_unused:UNUSED_PAD src0_sel:WORD_1
	v_mul_lo_u32 v16, v16, s2
	v_cvt_f32_f16_sdwa v63, v54 dst_sel:DWORD dst_unused:UNUSED_PAD src0_sel:WORD_1
	v_cvt_f32_f16_e32 v64, v55
	v_cvt_f32_f16_sdwa v65, v55 dst_sel:DWORD dst_unused:UNUSED_PAD src0_sel:WORD_1
	v_lshl_add_u64 v[78:79], v[82:83], 0, v[16:17]
	v_cvt_f32_f16_e32 v50, v56
	v_cvt_f32_f16_sdwa v51, v56 dst_sel:DWORD dst_unused:UNUSED_PAD src0_sel:WORD_1
	v_cvt_f32_f16_e32 v52, v57
	v_cvt_f32_f16_sdwa v53, v57 dst_sel:DWORD dst_unused:UNUSED_PAD src0_sel:WORD_1
	v_cvt_f32_f16_e32 v54, v84
	v_cvt_f32_f16_sdwa v55, v84 dst_sel:DWORD dst_unused:UNUSED_PAD src0_sel:WORD_1
	v_cvt_f32_f16_e32 v56, v85
	v_cvt_f32_f16_sdwa v57, v85 dst_sel:DWORD dst_unused:UNUSED_PAD src0_sel:WORD_1
	v_lshl_add_u64 v[78:79], v[148:149], 2, v[78:79]
	s_movk_i32 s2, 0x1000
	v_cvt_f32_f16_sdwa v85, v12 dst_sel:DWORD dst_unused:UNUSED_PAD src0_sel:WORD_1
	v_cvt_f32_f16_e32 v84, v12
	global_store_dwordx4 v[78:79], v[58:61], off
	global_store_dwordx4 v[78:79], v[46:49], off offset:16
	global_store_dwordx4 v[78:79], v[62:65], off offset:3072
	global_store_dwordx4 v[78:79], v[50:53], off offset:3088
	v_add_co_u32_e32 v78, vcc, s2, v78
	v_cvt_f32_f16_sdwa v83, v42 dst_sel:DWORD dst_unused:UNUSED_PAD src0_sel:WORD_1
	s_nop 0
	v_addc_co_u32_e32 v79, vcc, 0, v79, vcc
	v_cvt_f32_f16_e32 v82, v42
	global_store_dwordx4 v[78:79], v[66:69], off offset:2048
	global_store_dwordx4 v[78:79], v[54:57], off offset:2064
	v_cvt_f32_f16_e32 v78, v70
	v_cvt_f32_f16_sdwa v79, v70 dst_sel:DWORD dst_unused:UNUSED_PAD src0_sel:WORD_1
	v_pk_fma_f32 v[84:85], v[22:23], v[84:85], v[146:147]
	v_cvt_f32_f16_sdwa v39, v71 dst_sel:DWORD dst_unused:UNUSED_PAD src0_sel:WORD_1
	v_pk_fma_f32 v[84:85], v[26:27], v[90:91], v[84:85]
	s_nop 0
	v_pk_fma_f32 v[84:85], v[30:31], v[82:83], v[84:85]
	s_nop 0
	v_pk_fma_f32 v[84:85], v[34:35], v[78:79], v[84:85]
	s_nop 0
	v_mul_f32_e32 v12, 0xbfb8aa3b, v84
	v_exp_f32_e32 v88, v12
	v_mul_f32_e32 v12, 0xbfb8aa3b, v85
	v_exp_f32_e32 v89, v12
	s_nop 0
	v_pk_add_f32 v[88:89], v[88:89], 1.0 op_sel_hi:[1,0]
	s_nop 0
	s_nop 0
	v_rcp_f32_e32 v12, v89
	s_nop 0
	v_mul_f32_e32 v12, v85, v12
	v_cvt_f32_f16_sdwa v89, v13 dst_sel:DWORD dst_unused:UNUSED_PAD src0_sel:WORD_1
	v_rcp_f32_e32 v16, v88
	s_nop 0
	v_mul_f32_e32 v16, v84, v16
	v_cvt_f32_f16_e32 v88, v13
	v_cvt_f32_f16_sdwa v85, v43 dst_sel:DWORD dst_unused:UNUSED_PAD src0_sel:WORD_1
	v_cvt_f32_f16_e32 v84, v43
	v_cvt_f32_f16_e32 v38, v71
	v_pk_fma_f32 v[42:43], v[24:25], v[88:89], v[144:145]
	v_cvt_pk_f16_f32 v12, v16, v12
	v_pk_fma_f32 v[42:43], v[28:29], v[92:93], v[42:43]
	s_nop 0
	v_pk_fma_f32 v[42:43], v[32:33], v[84:85], v[42:43]
	s_nop 0
	v_pk_fma_f32 v[42:43], v[36:37], v[38:39], v[42:43]
	s_nop 0
	v_mul_f32_e32 v13, 0xbfb8aa3b, v42
	v_exp_f32_e32 v70, v13
	v_mul_f32_e32 v13, 0xbfb8aa3b, v43
	v_exp_f32_e32 v71, v13
	s_nop 0
	v_pk_add_f32 v[70:71], v[70:71], 1.0 op_sel_hi:[1,0]
	s_nop 0
	s_nop 0
	v_rcp_f32_e32 v13, v71
	s_nop 0
	v_mul_f32_e32 v13, v43, v13
	v_cvt_f32_f16_e32 v94, v40
	v_cvt_f32_f16_sdwa v89, v14 dst_sel:DWORD dst_unused:UNUSED_PAD src0_sel:WORD_1
	v_cvt_f32_f16_e32 v88, v14
	v_rcp_f32_e32 v16, v70
	s_nop 0
	v_mul_f32_e32 v16, v42, v16
	v_cvt_f32_f16_sdwa v71, v44 dst_sel:DWORD dst_unused:UNUSED_PAD src0_sel:WORD_1
	v_cvt_f32_f16_e32 v70, v44
	v_cvt_f32_f16_e32 v42, v72
	v_cvt_f32_f16_sdwa v43, v72 dst_sel:DWORD dst_unused:UNUSED_PAD src0_sel:WORD_1
	v_pk_fma_f32 v[88:89], v[0:1], v[88:89], v[142:143]
	v_cvt_pk_f16_f32 v13, v16, v13
; __device__ __forceinline__ float siluf_(float x) { return x / (1.0f + __expf(-x)); }
; __device__ __forceinline__ void phase_conv(const Params& p, int l, const XcdBarrier& xbar) {
;     ...
; #pragma unroll
;         for (int i = 0; i < 4; ++i) { float o[8];
; #pragma unroll
;             for (int e = 0; e < 8; ++e) { float a = bias[e];
; #pragma unroll
;                 for (int j = 0; j < 4; ++j) a += w[j][e] * win[i + j][e];
;                 o[e] = siluf_(a); }
;             *(u32x4*)(proj + (size_t)(row0 + i) * PN + col) = (u32x4){pkh(o[0], o[1]), pkh(o[2], o[3]), pkh(o[4], o[5]), pkh(o[6], o[7])}; }
	v_pk_fma_f32 v[88:89], v[4:5], v[94:95], v[88:89]
	s_nop 0
	v_pk_fma_f32 v[88:89], v[8:9], v[70:71], v[88:89]
	s_nop 0
	v_pk_fma_f32 v[88:89], v[18:19], v[42:43], v[88:89]
	s_nop 0
	v_mul_f32_e32 v14, 0xbfb8aa3b, v88
	v_exp_f32_e32 v96, v14
	v_mul_f32_e32 v14, 0xbfb8aa3b, v89
	v_exp_f32_e32 v97, v14
	s_nop 0
	v_pk_add_f32 v[96:97], v[96:97], 1.0 op_sel_hi:[1,0]
	s_nop 0
	s_nop 0
	v_rcp_f32_e32 v14, v97
	s_nop 0
	v_mul_f32_e32 v14, v89, v14
	v_cvt_f32_f16_sdwa v97, v41 dst_sel:DWORD dst_unused:UNUSED_PAD src0_sel:WORD_1
	v_rcp_f32_e32 v16, v96
	s_nop 0
	v_mul_f32_e32 v16, v88, v16
	v_cvt_f32_f16_e32 v96, v41
	v_cvt_f32_f16_sdwa v89, v45 dst_sel:DWORD dst_unused:UNUSED_PAD src0_sel:WORD_1
	v_cvt_f32_f16_e32 v88, v45
	v_cvt_f32_f16_e32 v40, v73
	v_cvt_f32_f16_sdwa v41, v73 dst_sel:DWORD dst_unused:UNUSED_PAD src0_sel:WORD_1
	v_pk_fma_f32 v[44:45], v[2:3], v[98:99], v[140:141]
	v_cvt_pk_f16_f32 v14, v16, v14
	v_pk_fma_f32 v[44:45], v[6:7], v[96:97], v[44:45]
	s_nop 0
	v_pk_fma_f32 v[44:45], v[10:11], v[88:89], v[44:45]
	s_nop 0
	v_pk_fma_f32 v[44:45], v[20:21], v[40:41], v[44:45]
	s_nop 0
	v_mul_f32_e32 v15, 0xbfb8aa3b, v44
	v_exp_f32_e32 v72, v15
	v_mul_f32_e32 v15, 0xbfb8aa3b, v45
	v_exp_f32_e32 v73, v15
	s_nop 0
	v_pk_add_f32 v[72:73], v[72:73], 1.0 op_sel_hi:[1,0]
	s_nop 0
	s_nop 0
	v_rcp_f32_e32 v15, v73
	s_nop 0
	v_mul_f32_e32 v15, v45, v15
	s_nop 0
	v_rcp_f32_e32 v16, v72
	s_nop 0
	v_mul_f32_e32 v16, v44, v16
	v_cvt_pk_f16_f32 v15, v16, v15
	global_store_dwordx4 v[86:87], v[12:15], off
	s_nop 1
	v_pk_fma_f32 v[12:13], v[22:23], v[90:91], v[146:147]
	s_nop 0
	v_pk_fma_f32 v[12:13], v[26:27], v[82:83], v[12:13]
	s_nop 0
	v_pk_fma_f32 v[12:13], v[30:31], v[78:79], v[12:13]
	s_nop 0
	v_pk_fma_f32 v[12:13], v[34:35], v[58:59], v[12:13]
	s_nop 0
	v_mul_f32_e32 v14, 0xbfb8aa3b, v12
	v_mul_f32_e32 v15, 0xbfb8aa3b, v13
	v_exp_f32_e32 v14, v14
	v_exp_f32_e32 v15, v15
	s_nop 0
	v_pk_add_f32 v[14:15], v[14:15], 1.0 op_sel_hi:[1,0]
	s_nop 0
	s_nop 0
	v_rcp_f32_e32 v16, v15
	s_nop 0
	v_mul_f32_e32 v13, v13, v16
	s_nop 0
	v_rcp_f32_e32 v15, v14
	s_nop 0
	v_mul_f32_e32 v12, v12, v15
	v_pk_fma_f32 v[14:15], v[24:25], v[92:93], v[144:145]
	v_cvt_pk_f16_f32 v12, v12, v13
	v_pk_fma_f32 v[14:15], v[28:29], v[84:85], v[14:15]
	s_nop 0
	v_pk_fma_f32 v[14:15], v[32:33], v[38:39], v[14:15]
	s_nop 0
	v_pk_fma_f32 v[14:15], v[36:37], v[60:61], v[14:15]
	s_nop 0
	v_mul_f32_e32 v13, 0xbfb8aa3b, v14
	v_exp_f32_e32 v44, v13
	v_mul_f32_e32 v13, 0xbfb8aa3b, v15
	v_exp_f32_e32 v45, v13
	s_nop 0
	v_pk_add_f32 v[44:45], v[44:45], 1.0 op_sel_hi:[1,0]
	s_nop 0
	s_nop 0
	v_rcp_f32_e32 v13, v45
	s_nop 0
	v_mul_f32_e32 v13, v15, v13
	s_nop 0
	v_rcp_f32_e32 v15, v44
	s_nop 0
	v_mul_f32_e32 v14, v14, v15
	v_cvt_pk_f16_f32 v13, v14, v13
	v_pk_fma_f32 v[14:15], v[0:1], v[94:95], v[142:143]
	s_nop 0
	v_pk_fma_f32 v[14:15], v[4:5], v[70:71], v[14:15]
	s_nop 0
	v_pk_fma_f32 v[14:15], v[8:9], v[42:43], v[14:15]
	s_nop 0
	v_pk_fma_f32 v[14:15], v[18:19], v[46:47], v[14:15]
	s_nop 0
	v_mul_f32_e32 v16, 0xbfb8aa3b, v14
	v_exp_f32_e32 v44, v16
	v_mul_f32_e32 v16, 0xbfb8aa3b, v15
	v_exp_f32_e32 v45, v16
	s_nop 0
	v_pk_add_f32 v[44:45], v[44:45], 1.0 op_sel_hi:[1,0]
	s_nop 0
	s_nop 0
	v_rcp_f32_e32 v16, v45
	s_nop 0
	v_mul_f32_e32 v15, v15, v16
	s_nop 0
	v_rcp_f32_e32 v16, v44
	s_nop 0
	v_mul_f32_e32 v14, v14, v16
	v_pk_fma_f32 v[44:45], v[2:3], v[96:97], v[140:141]
	v_cvt_pk_f16_f32 v14, v14, v15
	v_pk_fma_f32 v[44:45], v[6:7], v[88:89], v[44:45]
	s_nop 0
	v_pk_fma_f32 v[44:45], v[10:11], v[40:41], v[44:45]
	s_nop 0
	v_pk_fma_f32 v[44:45], v[20:21], v[48:49], v[44:45]
	s_nop 0
	v_mul_f32_e32 v15, 0xbfb8aa3b, v44
	v_exp_f32_e32 v72, v15
	v_mul_f32_e32 v15, 0xbfb8aa3b, v45
	v_exp_f32_e32 v73, v15
	s_nop 0
	v_pk_add_f32 v[72:73], v[72:73], 1.0 op_sel_hi:[1,0]
	s_nop 0
	s_nop 0
	v_rcp_f32_e32 v15, v73
	s_nop 0
	v_mul_f32_e32 v15, v45, v15
	s_nop 0
	v_rcp_f32_e32 v16, v72
	s_nop 0
	v_mul_f32_e32 v16, v44, v16
	v_cvt_pk_f16_f32 v15, v16, v15
	global_store_dwordx4 v[80:81], v[12:15], off
	s_nop 1
	v_pk_fma_f32 v[12:13], v[22:23], v[82:83], v[146:147]
	s_nop 0
	v_pk_fma_f32 v[12:13], v[26:27], v[78:79], v[12:13]
	s_nop 0
	v_pk_fma_f32 v[12:13], v[30:31], v[58:59], v[12:13]
	s_nop 0
	v_pk_fma_f32 v[12:13], v[34:35], v[62:63], v[12:13]
	s_nop 0
	v_mul_f32_e32 v14, 0xbfb8aa3b, v12
	v_mul_f32_e32 v15, 0xbfb8aa3b, v13
	v_exp_f32_e32 v14, v14
	v_exp_f32_e32 v15, v15
	s_nop 0
	v_pk_add_f32 v[14:15], v[14:15], 1.0 op_sel_hi:[1,0]
	s_nop 0
	s_nop 0
	v_rcp_f32_e32 v16, v15
	s_nop 0
	v_mul_f32_e32 v13, v13, v16
	s_nop 0
; __device__ __forceinline__ float siluf_(float x) { return x / (1.0f + __expf(-x)); }
; __device__ __forceinline__ void phase_conv(const Params& p, int l, const XcdBarrier& xbar) {
;     ...
; #pragma unroll
;         for (int i = 0; i < 4; ++i) { float o[8];
; #pragma unroll
;             for (int e = 0; e < 8; ++e) { float a = bias[e];
; #pragma unroll
;                 for (int j = 0; j < 4; ++j) a += w[j][e] * win[i + j][e];
;                 o[e] = siluf_(a); }
;             *(u32x4*)(proj + (size_t)(row0 + i) * PN + col) = (u32x4){pkh(o[0], o[1]), pkh(o[2], o[3]), pkh(o[4], o[5]), pkh(o[6], o[7])}; }
	v_rcp_f32_e32 v15, v14
	s_nop 0
	v_mul_f32_e32 v12, v12, v15
	v_pk_fma_f32 v[14:15], v[24:25], v[84:85], v[144:145]
	v_cvt_pk_f16_f32 v12, v12, v13
	v_pk_fma_f32 v[14:15], v[28:29], v[38:39], v[14:15]
	s_nop 0
	v_pk_fma_f32 v[14:15], v[32:33], v[60:61], v[14:15]
	s_nop 0
	v_pk_fma_f32 v[14:15], v[36:37], v[64:65], v[14:15]
	s_nop 0
	v_mul_f32_e32 v13, 0xbfb8aa3b, v14
	v_exp_f32_e32 v44, v13
	v_mul_f32_e32 v13, 0xbfb8aa3b, v15
	v_exp_f32_e32 v45, v13
	s_nop 0
	v_pk_add_f32 v[44:45], v[44:45], 1.0 op_sel_hi:[1,0]
	s_nop 0
	s_nop 0
	v_rcp_f32_e32 v13, v45
	s_nop 0
	v_mul_f32_e32 v13, v15, v13
	s_nop 0
	v_rcp_f32_e32 v15, v44
	s_nop 0
	v_mul_f32_e32 v14, v14, v15
	v_cvt_pk_f16_f32 v13, v14, v13
	v_pk_fma_f32 v[14:15], v[0:1], v[70:71], v[142:143]
	v_pk_fma_f32 v[0:1], v[0:1], v[42:43], v[142:143]
	v_pk_fma_f32 v[14:15], v[4:5], v[42:43], v[14:15]
	v_pk_fma_f32 v[0:1], v[4:5], v[46:47], v[0:1]
	v_pk_fma_f32 v[14:15], v[8:9], v[46:47], v[14:15]
	v_pk_fma_f32 v[0:1], v[8:9], v[50:51], v[0:1]
	v_pk_fma_f32 v[14:15], v[18:19], v[50:51], v[14:15]
	v_pk_fma_f32 v[0:1], v[18:19], v[54:55], v[0:1]
	v_mul_f32_e32 v16, 0xbfb8aa3b, v14
	v_exp_f32_e32 v44, v16
	v_mul_f32_e32 v16, 0xbfb8aa3b, v15
	v_exp_f32_e32 v45, v16
	v_mul_f32_e32 v4, 0xbfb8aa3b, v0
	v_mul_f32_e32 v5, 0xbfb8aa3b, v1
	v_exp_f32_e32 v4, v4
	v_pk_add_f32 v[44:45], v[44:45], 1.0 op_sel_hi:[1,0]
	v_exp_f32_e32 v5, v5
	s_nop 0
	v_pk_add_f32 v[4:5], v[4:5], 1.0 op_sel_hi:[1,0]
	v_rcp_f32_e32 v16, v45
	s_nop 0
	v_mul_f32_e32 v15, v15, v16
	v_div_scale_f32 v8, s[2:3], v5, v5, v1
	v_rcp_f32_e32 v9, v8
	v_rcp_f32_e32 v16, v44
	s_nop 0
	v_mul_f32_e32 v14, v14, v16
	v_pk_fma_f32 v[44:45], v[2:3], v[88:89], v[140:141]
	v_cvt_pk_f16_f32 v14, v14, v15
	v_pk_fma_f32 v[44:45], v[6:7], v[40:41], v[44:45]
	s_nop 0
	v_pk_fma_f32 v[44:45], v[10:11], v[48:49], v[44:45]
	s_nop 0
	v_pk_fma_f32 v[44:45], v[20:21], v[52:53], v[44:45]
	s_nop 0
	v_mul_f32_e32 v15, 0xbfb8aa3b, v44
	v_exp_f32_e32 v70, v15
	v_mul_f32_e32 v15, 0xbfb8aa3b, v45
	v_exp_f32_e32 v71, v15
	s_nop 0
	v_pk_add_f32 v[70:71], v[70:71], 1.0 op_sel_hi:[1,0]
	s_nop 0
	s_nop 0
	v_rcp_f32_e32 v15, v71
	s_nop 0
	v_mul_f32_e32 v15, v45, v15
	s_nop 0
	v_rcp_f32_e32 v16, v70
	s_nop 0
	v_mul_f32_e32 v16, v44, v16
	v_cvt_pk_f16_f32 v15, v16, v15
	global_store_dwordx4 v[76:77], v[12:15], off
	s_nop 1
	v_pk_fma_f32 v[12:13], v[22:23], v[78:79], v[146:147]
	s_nop 0
	v_pk_fma_f32 v[12:13], v[26:27], v[58:59], v[12:13]
	s_nop 0
	v_pk_fma_f32 v[12:13], v[30:31], v[62:63], v[12:13]
	s_nop 0
	v_pk_fma_f32 v[12:13], v[34:35], v[66:67], v[12:13]
	s_nop 0
	v_mul_f32_e32 v14, 0xbfb8aa3b, v12
	v_mul_f32_e32 v15, 0xbfb8aa3b, v13
	v_exp_f32_e32 v14, v14
	v_exp_f32_e32 v15, v15
	s_nop 0
	v_pk_add_f32 v[14:15], v[14:15], 1.0 op_sel_hi:[1,0]
	s_nop 0
	s_nop 0
	v_rcp_f32_e32 v16, v15
	s_nop 0
	v_mul_f32_e32 v13, v13, v16
	s_nop 0
	v_rcp_f32_e32 v15, v14
	s_nop 0
	v_mul_f32_e32 v12, v12, v15
	v_pk_fma_f32 v[14:15], v[24:25], v[38:39], v[144:145]
	v_cvt_pk_f16_f32 v12, v12, v13
	v_pk_fma_f32 v[14:15], v[28:29], v[60:61], v[14:15]
	s_nop 0
	v_pk_fma_f32 v[14:15], v[32:33], v[64:65], v[14:15]
	s_nop 0
	v_pk_fma_f32 v[14:15], v[36:37], v[68:69], v[14:15]
	s_nop 0
	v_mul_f32_e32 v13, 0xbfb8aa3b, v14
	v_exp_f32_e32 v22, v13
	v_mul_f32_e32 v13, 0xbfb8aa3b, v15
	v_exp_f32_e32 v23, v13
	s_nop 0
	v_pk_add_f32 v[22:23], v[22:23], 1.0 op_sel_hi:[1,0]
	s_nop 0
	s_nop 0
	v_rcp_f32_e32 v13, v23
	s_nop 0
	v_mul_f32_e32 v13, v15, v13
	s_nop 0
	v_rcp_f32_e32 v15, v22
	s_nop 0
	v_mul_f32_e32 v14, v14, v15
	v_cvt_pk_f16_f32 v13, v14, v13
	v_fma_f32 v14, -v8, v9, 1.0
	v_fmac_f32_e32 v9, v14, v9
	v_div_scale_f32 v14, vcc, v1, v5, v1
	v_mul_f32_e32 v15, v14, v9
	v_fma_f32 v16, -v8, v15, v14
	v_fmac_f32_e32 v15, v16, v9
	v_fma_f32 v8, -v8, v15, v14
	v_div_fmas_f32 v8, v8, v9, v15
	v_div_fixup_f32 v1, v8, v5, v1
	s_nop 0
	v_rcp_f32_e32 v5, v4
	s_nop 0
	v_mul_f32_e32 v0, v0, v5
	v_cvt_pk_f16_f32 v14, v0, v1
	v_pk_fma_f32 v[0:1], v[2:3], v[40:41], v[140:141]
	s_nop 0
	v_pk_fma_f32 v[0:1], v[6:7], v[48:49], v[0:1]
	s_nop 0
	v_pk_fma_f32 v[0:1], v[10:11], v[52:53], v[0:1]
	s_nop 0
	v_pk_fma_f32 v[0:1], v[20:21], v[56:57], v[0:1]
	s_nop 0
	v_mul_f32_e32 v2, 0xbfb8aa3b, v0
	v_mul_f32_e32 v3, 0xbfb8aa3b, v1
	v_exp_f32_e32 v2, v2
	v_exp_f32_e32 v3, v3
	s_nop 0
	v_pk_add_f32 v[2:3], v[2:3], 1.0 op_sel_hi:[1,0]
	s_nop 0
	s_nop 0
	v_rcp_f32_e32 v4, v3
	s_nop 0
	v_mul_f32_e32 v1, v1, v4
	s_nop 0
	v_rcp_f32_e32 v3, v2
	s_nop 0
	v_mul_f32_e32 v0, v0, v3
	v_cvt_pk_f16_f32 v15, v0, v1
	global_store_dwordx4 v[74:75], v[12:15], off

; __global__ void __launch_bounds__(512, 2) hymba_fwd(Params p) {
;     ...
;         if (ph == 3) grid.sync();
;         else if (ph < 18) xcd_barrier(xbar);
.LBB0_1065:
	s_cmp_lg_u32 s27, 0x63
	s_mov_b64 s[4:5], -1
	s_cselect_b64 s[6:7], -1, 0
	s_andn2_b64 vcc, exec, s[6:7]
	s_mov_b64 s[6:7], 0
	s_cbranch_vccnz .LBB0_1062
